# GEMM loops: per-phase s_setprio flips removed (on top of lambda caching, CMP batching, peeled zero-accumulator first half-iteration)
# speedup vs baseline: 1.0016x; 1.0010x over previous
; #define STAGE(P, BASE, br, kt) do { const bf16_t* _gb = (BASE) + (long)(br) * K + (long)(kt) * 64; asm volatile("" : "+s"(_gb)); \
;     __builtin_amdgcn_global_load_lds((const unsigned*)(_gb + go0), (lds_u32*)((char*)(P) + tid * 16), 16, 0, 0); \
;     __builtin_amdgcn_global_load_lds((const unsigned*)(_gb + go1), (lds_u32*)((char*)(P) + tid * 16 + 8192), 16, 0, 0); } while (0)
; #define LDA(dst, b, h) _Pragma("unroll") for (int m = 0; m < 4; ++m) _Pragma("unroll") for (int k = 0; k < 2; ++k) \
;     dst[m][k] = *(const __attribute__((address_space(3))) bf16x8*)(aB + (((b) * 2 + (h)) * 16384 + m * 2048 + k * 1024))
; #define LDB(dst, b, h) _Pragma("unroll") for (int n = 0; n < 2; ++n) _Pragma("unroll") for (int k = 0; k < 2; ++k) \
;     dst[n][k] = *(const __attribute__((address_space(3))) bf16x8*)(bB + (((b) * 2 + (h)) * 16384 + n * 2048 + k * 1024))
; #define MMA(ai, bj, At, Bq) do { __builtin_amdgcn_s_setprio(1); \
;     _Pragma("unroll") for (int m = 0; m < 4; ++m) _Pragma("unroll") for (int n = 0; n < 2; ++n) _Pragma("unroll") for (int k = 0; k < 2; ++k) \
;       acc[ai][bj][m][n] = __builtin_amdgcn_mfma_f32_16x16x32_bf16(At[m][k], Bq[n][k], acc[ai][bj][m][n], 0, 0, 0); \
;     __builtin_amdgcn_s_setprio(0); } while (0)
; #define WAIT_L(n) asm volatile("s_waitcnt lgkmcnt(" #n ")" ::: "memory")
; #define BAR __builtin_amdgcn_s_barrier()
; #define SCHED __builtin_amdgcn_sched_barrier(0)
; template <int MODE>
; DI void gemm_tile(const Params& p, const bf16_t* __restrict__ A, const bf16_t* __restrict__ Bt, int K, int brow, int bcol, int mp, int nt, bool vt, char* smem) {
;     ...
;   const int wid = tid >> 6, lane = tid & 63, wr = wid >> 2, wc = wid & 3, fr = lane & 15, fq = lane >> 4;
;   const int laneoff = (fr * 64 + fq * 16) ^ ((fr >> 3) << 5);
;   const __attribute__((address_space(3))) char* aB = (const __attribute__((address_space(3))) char*)smem + wr * 8192 + laneoff;
;   const __attribute__((address_space(3))) char* bB = (const __attribute__((address_space(3))) char*)smem + 65536 + wc * 4096 + laneoff;
;     ...
;     LDB(B0, 0, 0); SCHED; LDA(At, 0, 0); STAGE(SA(1, 1), A, brow + 128, t + 1);
;     WAIT_L(8); BAR; WAIT_L(0); MMA(0, 0, At, B0); BAR; SCHED;
;     LDB(B1, 0, 1); STAGE(SB(0, 0), Bt, bcol, t + 2);
;     BAR; WAIT_L(0); MMA(0, 1, At, B1); BAR;
;     LDA(At, 0, 1); STAGE(SA(0, 0), A, brow, t + 2);
.LBB0_36:
	s_or_b64 exec, exec, s[16:17]
	v_and_b32_e32 v142, 15, v0
	s_add_u32 s1, s12, 0x100
	v_bfe_u32 v131, v0, 6, 2
	v_and_b32_e32 v141, 48, v0
	v_and_b32_e32 v2, 32, v130
	v_lshlrev_b32_e32 v5, 6, v142
	s_addc_u32 s3, s13, 0
	s_waitcnt lgkmcnt(0)
	v_lshlrev_b32_e32 v3, 13, v6
	v_lshl_or_b32 v4, v131, 12, v205
	v_bitop3_b32 v5, v5, v2, v141 bitop3:0x36
	s_add_u32 s5, s20, s14
	s_addc_u32 s16, s21, s15
	s_mov_b32 s17, -2
	s_mov_b64 s[14:15], 0
	v_add_u32_e32 v147, v4, v5
	v_add_u32_e32 v145, v3, v5
	s_nop 0
	ds_read_b128 v[164:167], v147
	ds_read_b128 v[168:171], v147 offset:1024
	ds_read_b128 v[172:175], v147 offset:2048
	ds_read_b128 v[176:179], v147 offset:3072
	s_add_u32 s23, s5, s14
	s_addc_u32 s25, s16, s15
	s_add_u32 s24, s23, 0x80
	v_add_u32_e32 v162, 0xc000, v140
	s_addc_u32 s25, s25, 0
	v_readfirstlane_b32 s23, v162
	v_add_u32_e32 v163, 0xe000, v140
	ds_read_b128 v[180:183], v145
	ds_read_b128 v[184:187], v145 offset:1024
	ds_read_b128 v[188:191], v145 offset:2048
	ds_read_b128 v[192:195], v145 offset:3072
	ds_read_b128 v[196:199], v145 offset:4096
	ds_read_b128 v[214:217], v145 offset:5120
	ds_read_b128 v[218:221], v145 offset:6144
	ds_read_b128 v[222:225], v145 offset:7168
	s_mov_b32 m0, s23
	v_lshl_add_u64 v[226:227], s[24:25], 0, v[136:137]
	v_readfirstlane_b32 s23, v163
	global_load_lds_dwordx4 v[226:227], off
	v_lshl_add_u64 v[226:227], s[24:25], 0, v[138:139]
	s_mov_b32 m0, s23
	s_nop 0
	global_load_lds_dwordx4 v[226:227], off
	s_waitcnt lgkmcnt(8)
	s_barrier
	s_waitcnt lgkmcnt(0)
	s_nop 0
	s_waitcnt lgkmcnt(0)
	v_mfma_f32_16x16x32_bf16 v[126:129], v[180:183], v[164:167], 0
	v_mfma_f32_16x16x32_bf16 v[122:125], v[180:183], v[172:175], 0
	v_mfma_f32_16x16x32_bf16 v[118:121], v[188:191], v[164:167], 0
	v_mfma_f32_16x16x32_bf16 v[114:117], v[188:191], v[172:175], 0
	v_mfma_f32_16x16x32_bf16 v[110:113], v[196:199], v[164:167], 0
	v_mfma_f32_16x16x32_bf16 v[106:109], v[196:199], v[172:175], 0
	v_mfma_f32_16x16x32_bf16 v[102:105], v[218:221], v[164:167], 0
	v_mfma_f32_16x16x32_bf16 v[98:101], v[218:221], v[172:175], 0
	v_mfma_f32_16x16x32_bf16 v[126:129], v[184:187], v[168:171], v[126:129]
	v_mfma_f32_16x16x32_bf16 v[122:125], v[184:187], v[176:179], v[122:125]
	v_mfma_f32_16x16x32_bf16 v[118:121], v[192:195], v[168:171], v[118:121]
	v_mfma_f32_16x16x32_bf16 v[114:117], v[192:195], v[176:179], v[114:117]
	v_mfma_f32_16x16x32_bf16 v[110:113], v[214:217], v[168:171], v[110:113]
	v_mfma_f32_16x16x32_bf16 v[106:109], v[214:217], v[176:179], v[106:109]
	v_mfma_f32_16x16x32_bf16 v[102:105], v[222:225], v[168:171], v[102:105]
	v_mfma_f32_16x16x32_bf16 v[98:101], v[222:225], v[176:179], v[98:101]
	s_nop 0
	s_barrier
	s_add_u32 s23, s6, s14
	s_addc_u32 s26, s7, s15
	s_add_u32 s24, s23, 0x100
	s_addc_u32 s25, s26, 0
	v_readfirstlane_b32 s27, v144
	s_nop 0
	ds_read_b128 v[226:229], v147 offset:16384
	ds_read_b128 v[230:233], v147 offset:17408
	ds_read_b128 v[234:237], v147 offset:18432
	ds_read_b128 v[238:241], v147 offset:19456
	s_mov_b32 m0, s27
	v_lshl_add_u64 v[242:243], s[24:25], 0, v[136:137]
	global_load_lds_dwordx4 v[242:243], off
	v_lshl_add_u64 v[242:243], s[24:25], 0, v[138:139]
	v_readfirstlane_b32 s24, v146
	s_mov_b32 m0, s24
	s_nop 0
	global_load_lds_dwordx4 v[242:243], off
	s_barrier
	s_waitcnt lgkmcnt(0)
	s_nop 0
	s_waitcnt lgkmcnt(0)
	v_mfma_f32_16x16x32_bf16 v[94:97], v[180:183], v[226:229], 0
	v_mfma_f32_16x16x32_bf16 v[90:93], v[180:183], v[234:237], 0
	v_mfma_f32_16x16x32_bf16 v[86:89], v[188:191], v[226:229], 0
	v_mfma_f32_16x16x32_bf16 v[82:85], v[188:191], v[234:237], 0
	v_mfma_f32_16x16x32_bf16 v[78:81], v[196:199], v[226:229], 0
	v_mfma_f32_16x16x32_bf16 v[74:77], v[196:199], v[234:237], 0
	v_mfma_f32_16x16x32_bf16 v[70:73], v[218:221], v[226:229], 0
	v_mfma_f32_16x16x32_bf16 v[66:69], v[218:221], v[234:237], 0
	v_mfma_f32_16x16x32_bf16 v[94:97], v[184:187], v[230:233], v[94:97]
	v_mfma_f32_16x16x32_bf16 v[90:93], v[184:187], v[238:241], v[90:93]
	v_mfma_f32_16x16x32_bf16 v[86:89], v[192:195], v[230:233], v[86:89]
	v_mfma_f32_16x16x32_bf16 v[82:85], v[192:195], v[238:241], v[82:85]
	v_mfma_f32_16x16x32_bf16 v[78:81], v[214:217], v[230:233], v[78:81]
	v_mfma_f32_16x16x32_bf16 v[74:77], v[214:217], v[238:241], v[74:77]
	v_mfma_f32_16x16x32_bf16 v[70:73], v[222:225], v[230:233], v[70:73]
	v_mfma_f32_16x16x32_bf16 v[66:69], v[222:225], v[238:241], v[66:69]
	s_nop 0
	s_add_u32 s27, s8, s14
	s_addc_u32 s28, s9, s15
	s_add_u32 s24, s27, 0x100
	s_addc_u32 s25, s28, 0
	v_readfirstlane_b32 s29, v140
	s_barrier
	s_nop 0
	ds_read_b128 v[180:183], v145 offset:16384
	ds_read_b128 v[184:187], v145 offset:17408
	ds_read_b128 v[188:191], v145 offset:18432
	ds_read_b128 v[192:195], v145 offset:19456
	ds_read_b128 v[196:199], v145 offset:20480
	ds_read_b128 v[214:217], v145 offset:21504
	ds_read_b128 v[218:221], v145 offset:22528
	ds_read_b128 v[222:225], v145 offset:23552
	s_mov_b32 m0, s29
	v_lshl_add_u64 v[242:243], s[24:25], 0, v[136:137]
	global_load_lds_dwordx4 v[242:243], off
	v_lshl_add_u64 v[242:243], s[24:25], 0, v[138:139]
	v_readfirstlane_b32 s24, v143
	s_mov_b32 m0, s24
	s_nop 0
	global_load_lds_dwordx4 v[242:243], off
	s_barrier
; #define STAGE(P, BASE, br, kt) do { const bf16_t* _gb = (BASE) + (long)(br) * K + (long)(kt) * 64; asm volatile("" : "+s"(_gb)); \
;     __builtin_amdgcn_global_load_lds((const unsigned*)(_gb + go0), (lds_u32*)((char*)(P) + tid * 16), 16, 0, 0); \
;     __builtin_amdgcn_global_load_lds((const unsigned*)(_gb + go1), (lds_u32*)((char*)(P) + tid * 16 + 8192), 16, 0, 0); } while (0)
; #define LDA(dst, b, h) _Pragma("unroll") for (int m = 0; m < 4; ++m) _Pragma("unroll") for (int k = 0; k < 2; ++k) \
;     dst[m][k] = *(const __attribute__((address_space(3))) bf16x8*)(aB + (((b) * 2 + (h)) * 16384 + m * 2048 + k * 1024))
; #define LDB(dst, b, h) _Pragma("unroll") for (int n = 0; n < 2; ++n) _Pragma("unroll") for (int k = 0; k < 2; ++k) \
;     dst[n][k] = *(const __attribute__((address_space(3))) bf16x8*)(bB + (((b) * 2 + (h)) * 16384 + n * 2048 + k * 1024))
; #define MMA(ai, bj, At, Bq) do { __builtin_amdgcn_s_setprio(1); \
;     _Pragma("unroll") for (int m = 0; m < 4; ++m) _Pragma("unroll") for (int n = 0; n < 2; ++n) _Pragma("unroll") for (int k = 0; k < 2; ++k) \
;       acc[ai][bj][m][n] = __builtin_amdgcn_mfma_f32_16x16x32_bf16(At[m][k], Bq[n][k], acc[ai][bj][m][n], 0, 0, 0); \
;     __builtin_amdgcn_s_setprio(0); } while (0)
; #define WAIT_V(n) asm volatile("s_waitcnt vmcnt(" #n ")" ::: "memory")
; #define WAIT_L(n) asm volatile("s_waitcnt lgkmcnt(" #n ")" ::: "memory")
; #define BAR __builtin_amdgcn_s_barrier()
; #define SCHED __builtin_amdgcn_sched_barrier(0)
; template <int MODE>
; DI void gemm_tile(const Params& p, const bf16_t* __restrict__ A, const bf16_t* __restrict__ Bt, int K, int brow, int bcol, int mp, int nt, bool vt, char* smem) {
;     ...
;     LDB(B0, 0, 0); SCHED; LDA(At, 0, 0); STAGE(SA(1, 1), A, brow + 128, t + 1);
;     WAIT_L(8); BAR; WAIT_L(0); MMA(0, 0, At, B0); BAR; SCHED;
;     LDB(B1, 0, 1); STAGE(SB(0, 0), Bt, bcol, t + 2);
;     ...
;     BAR; WAIT_L(0); MMA(1, 0, At, B0); BAR; SCHED;
;     STAGE(SB(0, 1), Bt, bcol + 128, t + 2);
;     WAIT_V(6); BAR; MMA(1, 1, At, B1); BAR;
	s_waitcnt lgkmcnt(0)
	s_nop 0
	s_waitcnt lgkmcnt(0)
	v_mfma_f32_16x16x32_bf16 v[62:65], v[180:183], v[164:167], 0
	v_mfma_f32_16x16x32_bf16 v[58:61], v[180:183], v[172:175], 0
	v_mfma_f32_16x16x32_bf16 v[54:57], v[188:191], v[164:167], 0
	v_mfma_f32_16x16x32_bf16 v[50:53], v[188:191], v[172:175], 0
	v_mfma_f32_16x16x32_bf16 v[46:49], v[196:199], v[164:167], 0
	v_mfma_f32_16x16x32_bf16 v[42:45], v[196:199], v[172:175], 0
	v_mfma_f32_16x16x32_bf16 v[38:41], v[218:221], v[164:167], 0
	v_mfma_f32_16x16x32_bf16 v[34:37], v[218:221], v[172:175], 0
	v_mfma_f32_16x16x32_bf16 v[62:65], v[184:187], v[168:171], v[62:65]
	v_mfma_f32_16x16x32_bf16 v[58:61], v[184:187], v[176:179], v[58:61]
	v_mfma_f32_16x16x32_bf16 v[54:57], v[192:195], v[168:171], v[54:57]
	v_mfma_f32_16x16x32_bf16 v[50:53], v[192:195], v[176:179], v[50:53]
	v_mfma_f32_16x16x32_bf16 v[46:49], v[214:217], v[168:171], v[46:49]
	v_mfma_f32_16x16x32_bf16 v[42:45], v[214:217], v[176:179], v[42:45]
	v_mfma_f32_16x16x32_bf16 v[38:41], v[222:225], v[168:171], v[38:41]
	v_mfma_f32_16x16x32_bf16 v[34:37], v[222:225], v[176:179], v[34:37]
	s_nop 0
	s_barrier
	s_add_u32 s29, s10, s14
	s_addc_u32 s30, s11, s15
	s_add_u32 s24, s29, 0x100
	s_addc_u32 s25, s30, 0
	v_readfirstlane_b32 s31, v148
	s_mov_b32 m0, s31
	v_lshl_add_u64 v[164:165], s[24:25], 0, v[136:137]
	global_load_lds_dwordx4 v[164:165], off
	v_lshl_add_u64 v[164:165], s[24:25], 0, v[138:139]
	v_readfirstlane_b32 s24, v149
	s_mov_b32 m0, s24
	s_nop 0
	global_load_lds_dwordx4 v[164:165], off
	s_waitcnt vmcnt(6)
	s_barrier
	s_nop 0
	v_mfma_f32_16x16x32_bf16 v[30:33], v[180:183], v[226:229], 0
	v_mfma_f32_16x16x32_bf16 v[26:29], v[180:183], v[234:237], 0
	v_mfma_f32_16x16x32_bf16 v[22:25], v[188:191], v[226:229], 0
	v_mfma_f32_16x16x32_bf16 v[18:21], v[188:191], v[234:237], 0
	v_mfma_f32_16x16x32_bf16 v[14:17], v[196:199], v[226:229], 0
	v_mfma_f32_16x16x32_bf16 v[10:13], v[196:199], v[234:237], 0
	v_mfma_f32_16x16x32_bf16 v[6:9], v[218:221], v[226:229], 0
	v_mfma_f32_16x16x32_bf16 v[2:5], v[218:221], v[234:237], 0
	v_mfma_f32_16x16x32_bf16 v[30:33], v[184:187], v[230:233], v[30:33]
	v_mfma_f32_16x16x32_bf16 v[26:29], v[184:187], v[238:241], v[26:29]
	v_mfma_f32_16x16x32_bf16 v[22:25], v[192:195], v[230:233], v[22:25]
	v_mfma_f32_16x16x32_bf16 v[18:21], v[192:195], v[238:241], v[18:21]
	v_mfma_f32_16x16x32_bf16 v[14:17], v[214:217], v[230:233], v[14:17]
	v_mfma_f32_16x16x32_bf16 v[10:13], v[214:217], v[238:241], v[10:13]
	v_mfma_f32_16x16x32_bf16 v[6:9], v[222:225], v[230:233], v[6:9]
	v_mfma_f32_16x16x32_bf16 v[2:5], v[222:225], v[238:241], v[2:5]
	s_nop 0
	s_barrier
	s_branch .Lgemm0_p5
.LBB0_37:
	s_nop 0
	ds_read_b128 v[164:167], v147
	ds_read_b128 v[168:171], v147 offset:1024
	ds_read_b128 v[172:175], v147 offset:2048
	ds_read_b128 v[176:179], v147 offset:3072
	s_add_u32 s23, s5, s14
	s_addc_u32 s25, s16, s15
	s_add_u32 s24, s23, 0x80
	v_add_u32_e32 v162, 0xc000, v140
	s_addc_u32 s25, s25, 0
	v_readfirstlane_b32 s23, v162
	v_add_u32_e32 v163, 0xe000, v140
	ds_read_b128 v[180:183], v145
	ds_read_b128 v[184:187], v145 offset:1024
	ds_read_b128 v[188:191], v145 offset:2048
	ds_read_b128 v[192:195], v145 offset:3072
	ds_read_b128 v[196:199], v145 offset:4096
	ds_read_b128 v[214:217], v145 offset:5120
	ds_read_b128 v[218:221], v145 offset:6144
	ds_read_b128 v[222:225], v145 offset:7168
	s_mov_b32 m0, s23
	v_lshl_add_u64 v[226:227], s[24:25], 0, v[136:137]
	v_readfirstlane_b32 s23, v163
	global_load_lds_dwordx4 v[226:227], off
	v_lshl_add_u64 v[226:227], s[24:25], 0, v[138:139]
	s_mov_b32 m0, s23
	s_nop 0
	global_load_lds_dwordx4 v[226:227], off
	s_waitcnt lgkmcnt(8)
	s_barrier
	s_waitcnt lgkmcnt(0)
	s_nop 0
	s_waitcnt lgkmcnt(0)
	v_mfma_f32_16x16x32_bf16 v[126:129], v[180:183], v[164:167], v[126:129]
	v_mfma_f32_16x16x32_bf16 v[122:125], v[180:183], v[172:175], v[122:125]
	v_mfma_f32_16x16x32_bf16 v[118:121], v[188:191], v[164:167], v[118:121]
	v_mfma_f32_16x16x32_bf16 v[114:117], v[188:191], v[172:175], v[114:117]
	v_mfma_f32_16x16x32_bf16 v[110:113], v[196:199], v[164:167], v[110:113]
	v_mfma_f32_16x16x32_bf16 v[106:109], v[196:199], v[172:175], v[106:109]
	v_mfma_f32_16x16x32_bf16 v[102:105], v[218:221], v[164:167], v[102:105]
	v_mfma_f32_16x16x32_bf16 v[98:101], v[218:221], v[172:175], v[98:101]
	v_mfma_f32_16x16x32_bf16 v[126:129], v[184:187], v[168:171], v[126:129]
	v_mfma_f32_16x16x32_bf16 v[122:125], v[184:187], v[176:179], v[122:125]
	v_mfma_f32_16x16x32_bf16 v[118:121], v[192:195], v[168:171], v[118:121]
	v_mfma_f32_16x16x32_bf16 v[114:117], v[192:195], v[176:179], v[114:117]
	v_mfma_f32_16x16x32_bf16 v[110:113], v[214:217], v[168:171], v[110:113]
	v_mfma_f32_16x16x32_bf16 v[106:109], v[214:217], v[176:179], v[106:109]
	v_mfma_f32_16x16x32_bf16 v[102:105], v[222:225], v[168:171], v[102:105]
	v_mfma_f32_16x16x32_bf16 v[98:101], v[222:225], v[176:179], v[98:101]
	s_nop 0
	s_barrier
	s_add_u32 s23, s6, s14
	s_addc_u32 s26, s7, s15
	s_add_u32 s24, s23, 0x100
	s_addc_u32 s25, s26, 0
	v_readfirstlane_b32 s27, v144
	s_nop 0
	ds_read_b128 v[226:229], v147 offset:16384
	ds_read_b128 v[230:233], v147 offset:17408
	ds_read_b128 v[234:237], v147 offset:18432
	ds_read_b128 v[238:241], v147 offset:19456
	s_mov_b32 m0, s27
	v_lshl_add_u64 v[242:243], s[24:25], 0, v[136:137]
	global_load_lds_dwordx4 v[242:243], off
	v_lshl_add_u64 v[242:243], s[24:25], 0, v[138:139]
	v_readfirstlane_b32 s24, v146
	s_mov_b32 m0, s24
	s_nop 0
	global_load_lds_dwordx4 v[242:243], off
	s_barrier
; #define STAGE(P, BASE, br, kt) do { const bf16_t* _gb = (BASE) + (long)(br) * K + (long)(kt) * 64; asm volatile("" : "+s"(_gb)); \
;     __builtin_amdgcn_global_load_lds((const unsigned*)(_gb + go0), (lds_u32*)((char*)(P) + tid * 16), 16, 0, 0); \
;     __builtin_amdgcn_global_load_lds((const unsigned*)(_gb + go1), (lds_u32*)((char*)(P) + tid * 16 + 8192), 16, 0, 0); } while (0)
; #define LDA(dst, b, h) _Pragma("unroll") for (int m = 0; m < 4; ++m) _Pragma("unroll") for (int k = 0; k < 2; ++k) \
;     dst[m][k] = *(const __attribute__((address_space(3))) bf16x8*)(aB + (((b) * 2 + (h)) * 16384 + m * 2048 + k * 1024))
; #define MMA(ai, bj, At, Bq) do { __builtin_amdgcn_s_setprio(1); \
;     _Pragma("unroll") for (int m = 0; m < 4; ++m) _Pragma("unroll") for (int n = 0; n < 2; ++n) _Pragma("unroll") for (int k = 0; k < 2; ++k) \
;       acc[ai][bj][m][n] = __builtin_amdgcn_mfma_f32_16x16x32_bf16(At[m][k], Bq[n][k], acc[ai][bj][m][n], 0, 0, 0); \
;     __builtin_amdgcn_s_setprio(0); } while (0)
; #define WAIT_V(n) asm volatile("s_waitcnt vmcnt(" #n ")" ::: "memory")
; #define WAIT_L(n) asm volatile("s_waitcnt lgkmcnt(" #n ")" ::: "memory")
; #define BAR __builtin_amdgcn_s_barrier()
; #define SCHED __builtin_amdgcn_sched_barrier(0)
; template <int MODE>
; DI void gemm_tile(const Params& p, const bf16_t* __restrict__ A, const bf16_t* __restrict__ Bt, int K, int brow, int bcol, int mp, int nt, bool vt, char* smem) {
;     ...
;     BAR; WAIT_L(0); MMA(0, 1, At, B1); BAR;
;     LDA(At, 0, 1); STAGE(SA(0, 0), A, brow, t + 2);
;     BAR; WAIT_L(0); MMA(1, 0, At, B0); BAR; SCHED;
;     STAGE(SB(0, 1), Bt, bcol + 128, t + 2);
;     WAIT_V(6); BAR; MMA(1, 1, At, B1); BAR;
	s_waitcnt lgkmcnt(0)
	s_nop 0
	s_waitcnt lgkmcnt(0)
	v_mfma_f32_16x16x32_bf16 v[94:97], v[180:183], v[226:229], v[94:97]
	v_mfma_f32_16x16x32_bf16 v[90:93], v[180:183], v[234:237], v[90:93]
	v_mfma_f32_16x16x32_bf16 v[86:89], v[188:191], v[226:229], v[86:89]
	v_mfma_f32_16x16x32_bf16 v[82:85], v[188:191], v[234:237], v[82:85]
	v_mfma_f32_16x16x32_bf16 v[78:81], v[196:199], v[226:229], v[78:81]
	v_mfma_f32_16x16x32_bf16 v[74:77], v[196:199], v[234:237], v[74:77]
	v_mfma_f32_16x16x32_bf16 v[70:73], v[218:221], v[226:229], v[70:73]
	v_mfma_f32_16x16x32_bf16 v[66:69], v[218:221], v[234:237], v[66:69]
	v_mfma_f32_16x16x32_bf16 v[94:97], v[184:187], v[230:233], v[94:97]
	v_mfma_f32_16x16x32_bf16 v[90:93], v[184:187], v[238:241], v[90:93]
	v_mfma_f32_16x16x32_bf16 v[86:89], v[192:195], v[230:233], v[86:89]
	v_mfma_f32_16x16x32_bf16 v[82:85], v[192:195], v[238:241], v[82:85]
	v_mfma_f32_16x16x32_bf16 v[78:81], v[214:217], v[230:233], v[78:81]
	v_mfma_f32_16x16x32_bf16 v[74:77], v[214:217], v[238:241], v[74:77]
	v_mfma_f32_16x16x32_bf16 v[70:73], v[222:225], v[230:233], v[70:73]
	v_mfma_f32_16x16x32_bf16 v[66:69], v[222:225], v[238:241], v[66:69]
	s_nop 0
	s_add_u32 s27, s8, s14
	s_addc_u32 s28, s9, s15
	s_add_u32 s24, s27, 0x100
	s_addc_u32 s25, s28, 0
	v_readfirstlane_b32 s29, v140
	s_barrier
	s_nop 0
	ds_read_b128 v[180:183], v145 offset:16384
	ds_read_b128 v[184:187], v145 offset:17408
	ds_read_b128 v[188:191], v145 offset:18432
	ds_read_b128 v[192:195], v145 offset:19456
	ds_read_b128 v[196:199], v145 offset:20480
	ds_read_b128 v[214:217], v145 offset:21504
	ds_read_b128 v[218:221], v145 offset:22528
	ds_read_b128 v[222:225], v145 offset:23552
	s_mov_b32 m0, s29
	v_lshl_add_u64 v[242:243], s[24:25], 0, v[136:137]
	global_load_lds_dwordx4 v[242:243], off
	v_lshl_add_u64 v[242:243], s[24:25], 0, v[138:139]
	v_readfirstlane_b32 s24, v143
	s_mov_b32 m0, s24
	s_nop 0
	global_load_lds_dwordx4 v[242:243], off
	s_barrier
	s_waitcnt lgkmcnt(0)
	s_nop 0
	s_waitcnt lgkmcnt(0)
	v_mfma_f32_16x16x32_bf16 v[62:65], v[180:183], v[164:167], v[62:65]
	v_mfma_f32_16x16x32_bf16 v[58:61], v[180:183], v[172:175], v[58:61]
	v_mfma_f32_16x16x32_bf16 v[54:57], v[188:191], v[164:167], v[54:57]
	v_mfma_f32_16x16x32_bf16 v[50:53], v[188:191], v[172:175], v[50:53]
	v_mfma_f32_16x16x32_bf16 v[46:49], v[196:199], v[164:167], v[46:49]
	v_mfma_f32_16x16x32_bf16 v[42:45], v[196:199], v[172:175], v[42:45]
	v_mfma_f32_16x16x32_bf16 v[38:41], v[218:221], v[164:167], v[38:41]
	v_mfma_f32_16x16x32_bf16 v[34:37], v[218:221], v[172:175], v[34:37]
	v_mfma_f32_16x16x32_bf16 v[62:65], v[184:187], v[168:171], v[62:65]
	v_mfma_f32_16x16x32_bf16 v[58:61], v[184:187], v[176:179], v[58:61]
	v_mfma_f32_16x16x32_bf16 v[54:57], v[192:195], v[168:171], v[54:57]
	v_mfma_f32_16x16x32_bf16 v[50:53], v[192:195], v[176:179], v[50:53]
	v_mfma_f32_16x16x32_bf16 v[46:49], v[214:217], v[168:171], v[46:49]
	v_mfma_f32_16x16x32_bf16 v[42:45], v[214:217], v[176:179], v[42:45]
	v_mfma_f32_16x16x32_bf16 v[38:41], v[222:225], v[168:171], v[38:41]
	v_mfma_f32_16x16x32_bf16 v[34:37], v[222:225], v[176:179], v[34:37]
	s_nop 0
	s_barrier
	s_add_u32 s29, s10, s14
	s_addc_u32 s30, s11, s15
	s_add_u32 s24, s29, 0x100
	s_addc_u32 s25, s30, 0
	v_readfirstlane_b32 s31, v148
	s_mov_b32 m0, s31
	v_lshl_add_u64 v[164:165], s[24:25], 0, v[136:137]
	global_load_lds_dwordx4 v[164:165], off
	v_lshl_add_u64 v[164:165], s[24:25], 0, v[138:139]
	v_readfirstlane_b32 s24, v149
	s_mov_b32 m0, s24
	s_nop 0
	global_load_lds_dwordx4 v[164:165], off
	s_waitcnt vmcnt(6)
	s_barrier
	s_nop 0
	v_mfma_f32_16x16x32_bf16 v[30:33], v[180:183], v[226:229], v[30:33]
	v_mfma_f32_16x16x32_bf16 v[26:29], v[180:183], v[234:237], v[26:29]
	v_mfma_f32_16x16x32_bf16 v[22:25], v[188:191], v[226:229], v[22:25]
	v_mfma_f32_16x16x32_bf16 v[18:21], v[188:191], v[234:237], v[18:21]
	v_mfma_f32_16x16x32_bf16 v[14:17], v[196:199], v[226:229], v[14:17]
	v_mfma_f32_16x16x32_bf16 v[10:13], v[196:199], v[234:237], v[10:13]
	v_mfma_f32_16x16x32_bf16 v[6:9], v[218:221], v[226:229], v[6:9]
	v_mfma_f32_16x16x32_bf16 v[2:5], v[218:221], v[234:237], v[2:5]
	v_mfma_f32_16x16x32_bf16 v[30:33], v[184:187], v[230:233], v[30:33]
	v_mfma_f32_16x16x32_bf16 v[26:29], v[184:187], v[238:241], v[26:29]
	v_mfma_f32_16x16x32_bf16 v[22:25], v[192:195], v[230:233], v[22:25]
	v_mfma_f32_16x16x32_bf16 v[18:21], v[192:195], v[238:241], v[18:21]
	v_mfma_f32_16x16x32_bf16 v[14:17], v[214:217], v[230:233], v[14:17]
	v_mfma_f32_16x16x32_bf16 v[10:13], v[214:217], v[238:241], v[10:13]
	v_mfma_f32_16x16x32_bf16 v[6:9], v[222:225], v[230:233], v[6:9]
	v_mfma_f32_16x16x32_bf16 v[2:5], v[222:225], v[238:241], v[2:5]
	s_nop 0
	s_barrier
; #define STAGE(P, BASE, br, kt) do { const bf16_t* _gb = (BASE) + (long)(br) * K + (long)(kt) * 64; asm volatile("" : "+s"(_gb)); \
;     __builtin_amdgcn_global_load_lds((const unsigned*)(_gb + go0), (lds_u32*)((char*)(P) + tid * 16), 16, 0, 0); \
;     __builtin_amdgcn_global_load_lds((const unsigned*)(_gb + go1), (lds_u32*)((char*)(P) + tid * 16 + 8192), 16, 0, 0); } while (0)
; #define LDA(dst, b, h) _Pragma("unroll") for (int m = 0; m < 4; ++m) _Pragma("unroll") for (int k = 0; k < 2; ++k) \
;     dst[m][k] = *(const __attribute__((address_space(3))) bf16x8*)(aB + (((b) * 2 + (h)) * 16384 + m * 2048 + k * 1024))
; #define LDB(dst, b, h) _Pragma("unroll") for (int n = 0; n < 2; ++n) _Pragma("unroll") for (int k = 0; k < 2; ++k) \
;     dst[n][k] = *(const __attribute__((address_space(3))) bf16x8*)(bB + (((b) * 2 + (h)) * 16384 + n * 2048 + k * 1024))
; #define MMA(ai, bj, At, Bq) do { __builtin_amdgcn_s_setprio(1); \
;     _Pragma("unroll") for (int m = 0; m < 4; ++m) _Pragma("unroll") for (int n = 0; n < 2; ++n) _Pragma("unroll") for (int k = 0; k < 2; ++k) \
;       acc[ai][bj][m][n] = __builtin_amdgcn_mfma_f32_16x16x32_bf16(At[m][k], Bq[n][k], acc[ai][bj][m][n], 0, 0, 0); \
;     __builtin_amdgcn_s_setprio(0); } while (0)
; #define WAIT_L(n) asm volatile("s_waitcnt lgkmcnt(" #n ")" ::: "memory")
; #define BAR __builtin_amdgcn_s_barrier()
; #define SCHED __builtin_amdgcn_sched_barrier(0)
; template <int MODE>
; DI void gemm_tile(const Params& p, const bf16_t* __restrict__ A, const bf16_t* __restrict__ Bt, int K, int brow, int bcol, int mp, int nt, bool vt, char* smem) {
;     ...
;     LDB(B0, 1, 0); SCHED; LDA(At, 1, 0); STAGE(SA(0, 1), A, brow + 128, t + 2);
;     WAIT_L(8); BAR; WAIT_L(0); MMA(0, 0, At, B0); BAR; SCHED;
;     LDB(B1, 1, 1); STAGE(SB(1, 0), Bt, bcol, t + 3);
;     BAR; WAIT_L(0); MMA(0, 1, At, B1); BAR;
;     LDA(At, 1, 1); STAGE(SA(1, 0), A, brow, t + 3);
;     BAR; WAIT_L(0); MMA(1, 0, At, B0); BAR; SCHED;
.Lgemm0_p5:
	s_nop 0
	ds_read_b128 v[164:167], v147 offset:32768
	ds_read_b128 v[168:171], v147 offset:33792
	ds_read_b128 v[172:175], v147 offset:34816
	ds_read_b128 v[176:179], v147 offset:35840
	s_add_u32 s24, s1, s14
	s_addc_u32 s25, s3, s15
	v_readfirstlane_b32 s31, v150
	ds_read_b128 v[180:183], v145 offset:32768
	ds_read_b128 v[184:187], v145 offset:33792
	ds_read_b128 v[188:191], v145 offset:34816
	ds_read_b128 v[192:195], v145 offset:35840
	ds_read_b128 v[196:199], v145 offset:36864
	ds_read_b128 v[214:217], v145 offset:37888
	ds_read_b128 v[218:221], v145 offset:38912
	ds_read_b128 v[222:225], v145 offset:39936
	s_mov_b32 m0, s31
	v_lshl_add_u64 v[226:227], s[24:25], 0, v[136:137]
	global_load_lds_dwordx4 v[226:227], off
	v_lshl_add_u64 v[226:227], s[24:25], 0, v[138:139]
	v_readfirstlane_b32 s24, v151
	s_mov_b32 m0, s24
	s_nop 0
	global_load_lds_dwordx4 v[226:227], off
	s_waitcnt lgkmcnt(8)
	s_barrier
	s_waitcnt lgkmcnt(0)
	s_nop 0
	s_waitcnt lgkmcnt(0)
	v_mfma_f32_16x16x32_bf16 v[126:129], v[180:183], v[164:167], v[126:129]
	v_mfma_f32_16x16x32_bf16 v[122:125], v[180:183], v[172:175], v[122:125]
	v_mfma_f32_16x16x32_bf16 v[118:121], v[188:191], v[164:167], v[118:121]
	v_mfma_f32_16x16x32_bf16 v[114:117], v[188:191], v[172:175], v[114:117]
	v_mfma_f32_16x16x32_bf16 v[110:113], v[196:199], v[164:167], v[110:113]
	v_mfma_f32_16x16x32_bf16 v[106:109], v[196:199], v[172:175], v[106:109]
	v_mfma_f32_16x16x32_bf16 v[102:105], v[218:221], v[164:167], v[102:105]
	v_mfma_f32_16x16x32_bf16 v[98:101], v[218:221], v[172:175], v[98:101]
	v_mfma_f32_16x16x32_bf16 v[126:129], v[184:187], v[168:171], v[126:129]
	v_mfma_f32_16x16x32_bf16 v[122:125], v[184:187], v[176:179], v[122:125]
	v_mfma_f32_16x16x32_bf16 v[118:121], v[192:195], v[168:171], v[118:121]
	v_mfma_f32_16x16x32_bf16 v[114:117], v[192:195], v[176:179], v[114:117]
	v_mfma_f32_16x16x32_bf16 v[110:113], v[214:217], v[168:171], v[110:113]
	v_mfma_f32_16x16x32_bf16 v[106:109], v[214:217], v[176:179], v[106:109]
	v_mfma_f32_16x16x32_bf16 v[102:105], v[222:225], v[168:171], v[102:105]
	v_mfma_f32_16x16x32_bf16 v[98:101], v[222:225], v[176:179], v[98:101]
	s_nop 0
	s_barrier
	s_add_u32 s24, s23, 0x180
	s_addc_u32 s25, s26, 0
	v_readfirstlane_b32 s23, v156
	s_nop 0
	ds_read_b128 v[226:229], v147 offset:49152
	ds_read_b128 v[230:233], v147 offset:50176
	ds_read_b128 v[234:237], v147 offset:51200
	ds_read_b128 v[238:241], v147 offset:52224
	s_mov_b32 m0, s23
	v_lshl_add_u64 v[242:243], s[24:25], 0, v[136:137]
	v_readfirstlane_b32 s23, v157
	global_load_lds_dwordx4 v[242:243], off
	v_lshl_add_u64 v[242:243], s[24:25], 0, v[138:139]
	s_mov_b32 m0, s23
	s_nop 0
	global_load_lds_dwordx4 v[242:243], off
	s_barrier
	s_waitcnt lgkmcnt(0)
	s_nop 0
	s_waitcnt lgkmcnt(0)
	v_mfma_f32_16x16x32_bf16 v[94:97], v[180:183], v[226:229], v[94:97]
	v_mfma_f32_16x16x32_bf16 v[90:93], v[180:183], v[234:237], v[90:93]
	v_mfma_f32_16x16x32_bf16 v[86:89], v[188:191], v[226:229], v[86:89]
	v_mfma_f32_16x16x32_bf16 v[82:85], v[188:191], v[234:237], v[82:85]
	v_mfma_f32_16x16x32_bf16 v[78:81], v[196:199], v[226:229], v[78:81]
	v_mfma_f32_16x16x32_bf16 v[74:77], v[196:199], v[234:237], v[74:77]
	v_mfma_f32_16x16x32_bf16 v[70:73], v[218:221], v[226:229], v[70:73]
	v_mfma_f32_16x16x32_bf16 v[66:69], v[218:221], v[234:237], v[66:69]
	v_mfma_f32_16x16x32_bf16 v[94:97], v[184:187], v[230:233], v[94:97]
	v_mfma_f32_16x16x32_bf16 v[90:93], v[184:187], v[238:241], v[90:93]
	v_mfma_f32_16x16x32_bf16 v[86:89], v[192:195], v[230:233], v[86:89]
	v_mfma_f32_16x16x32_bf16 v[82:85], v[192:195], v[238:241], v[82:85]
	v_mfma_f32_16x16x32_bf16 v[78:81], v[214:217], v[230:233], v[78:81]
	v_mfma_f32_16x16x32_bf16 v[74:77], v[214:217], v[238:241], v[74:77]
	v_mfma_f32_16x16x32_bf16 v[70:73], v[222:225], v[230:233], v[70:73]
	v_mfma_f32_16x16x32_bf16 v[66:69], v[222:225], v[238:241], v[66:69]
	s_nop 0
	s_add_u32 s24, s27, 0x180
	s_addc_u32 s25, s28, 0
	v_readfirstlane_b32 s23, v158
	s_barrier
	s_nop 0
	ds_read_b128 v[180:183], v145 offset:49152
	ds_read_b128 v[184:187], v145 offset:50176
	ds_read_b128 v[188:191], v145 offset:51200
	ds_read_b128 v[192:195], v145 offset:52224
	ds_read_b128 v[196:199], v145 offset:53248
	ds_read_b128 v[214:217], v145 offset:54272
	ds_read_b128 v[218:221], v145 offset:55296
	ds_read_b128 v[222:225], v145 offset:56320
	s_mov_b32 m0, s23
	v_lshl_add_u64 v[242:243], s[24:25], 0, v[136:137]
	v_readfirstlane_b32 s23, v159
	global_load_lds_dwordx4 v[242:243], off
	v_lshl_add_u64 v[242:243], s[24:25], 0, v[138:139]
	s_mov_b32 m0, s23
	s_nop 0
	global_load_lds_dwordx4 v[242:243], off
	s_barrier
	s_waitcnt lgkmcnt(0)
	s_nop 0
	s_waitcnt lgkmcnt(0)
	v_mfma_f32_16x16x32_bf16 v[62:65], v[180:183], v[164:167], v[62:65]
	v_mfma_f32_16x16x32_bf16 v[58:61], v[180:183], v[172:175], v[58:61]
	v_mfma_f32_16x16x32_bf16 v[54:57], v[188:191], v[164:167], v[54:57]
	v_mfma_f32_16x16x32_bf16 v[50:53], v[188:191], v[172:175], v[50:53]
	v_mfma_f32_16x16x32_bf16 v[46:49], v[196:199], v[164:167], v[46:49]
	v_mfma_f32_16x16x32_bf16 v[42:45], v[196:199], v[172:175], v[42:45]
	v_mfma_f32_16x16x32_bf16 v[38:41], v[218:221], v[164:167], v[38:41]
	v_mfma_f32_16x16x32_bf16 v[34:37], v[218:221], v[172:175], v[34:37]
	v_mfma_f32_16x16x32_bf16 v[62:65], v[184:187], v[168:171], v[62:65]
	v_mfma_f32_16x16x32_bf16 v[58:61], v[184:187], v[176:179], v[58:61]
	v_mfma_f32_16x16x32_bf16 v[54:57], v[192:195], v[168:171], v[54:57]
	v_mfma_f32_16x16x32_bf16 v[50:53], v[192:195], v[176:179], v[50:53]
	v_mfma_f32_16x16x32_bf16 v[46:49], v[214:217], v[168:171], v[46:49]
	v_mfma_f32_16x16x32_bf16 v[42:45], v[214:217], v[176:179], v[42:45]
	v_mfma_f32_16x16x32_bf16 v[38:41], v[222:225], v[168:171], v[38:41]
	v_mfma_f32_16x16x32_bf16 v[34:37], v[222:225], v[176:179], v[34:37]
	s_nop 0
	s_barrier
; #define STAGE(P, BASE, br, kt) do { const bf16_t* _gb = (BASE) + (long)(br) * K + (long)(kt) * 64; asm volatile("" : "+s"(_gb)); \
;     __builtin_amdgcn_global_load_lds((const unsigned*)(_gb + go0), (lds_u32*)((char*)(P) + tid * 16), 16, 0, 0); \
;     __builtin_amdgcn_global_load_lds((const unsigned*)(_gb + go1), (lds_u32*)((char*)(P) + tid * 16 + 8192), 16, 0, 0); } while (0)
; #define LDA(dst, b, h) _Pragma("unroll") for (int m = 0; m < 4; ++m) _Pragma("unroll") for (int k = 0; k < 2; ++k) \
;     dst[m][k] = *(const __attribute__((address_space(3))) bf16x8*)(aB + (((b) * 2 + (h)) * 16384 + m * 2048 + k * 1024))
; #define LDB(dst, b, h) _Pragma("unroll") for (int n = 0; n < 2; ++n) _Pragma("unroll") for (int k = 0; k < 2; ++k) \
;     dst[n][k] = *(const __attribute__((address_space(3))) bf16x8*)(bB + (((b) * 2 + (h)) * 16384 + n * 2048 + k * 1024))
; #define MMA(ai, bj, At, Bq) do { __builtin_amdgcn_s_setprio(1); \
;     _Pragma("unroll") for (int m = 0; m < 4; ++m) _Pragma("unroll") for (int n = 0; n < 2; ++n) _Pragma("unroll") for (int k = 0; k < 2; ++k) \
;       acc[ai][bj][m][n] = __builtin_amdgcn_mfma_f32_16x16x32_bf16(At[m][k], Bq[n][k], acc[ai][bj][m][n], 0, 0, 0); \
;     __builtin_amdgcn_s_setprio(0); } while (0)
; #define WAIT_V(n) asm volatile("s_waitcnt vmcnt(" #n ")" ::: "memory")
; #define WAIT_L(n) asm volatile("s_waitcnt lgkmcnt(" #n ")" ::: "memory")
; #define BAR __builtin_amdgcn_s_barrier()
; template <int MODE>
; DI void gemm_tile(const Params& p, const bf16_t* __restrict__ A, const bf16_t* __restrict__ Bt, int K, int brow, int bcol, int mp, int nt, bool vt, char* smem) {
;     ...
;     STAGE(SB(1, 1), Bt, bcol + 128, t + 3);
;     WAIT_V(6); BAR; MMA(1, 1, At, B1); BAR;
;   }
;   { LDB(B0, 0, 0); LDA(At, 0, 0); STAGE(SA(1, 1), A, brow + 128, ntk - 1);
;     BAR; WAIT_L(0); MMA(0, 0, At, B0); BAR;
;     LDB(B1, 0, 1); BAR; WAIT_L(0); MMA(0, 1, At, B1); BAR;
;     LDA(At, 0, 1); WAIT_V(4); BAR; WAIT_L(0); MMA(1, 0, At, B0); MMA(1, 1, At, B1); BAR; }
	s_add_u32 s24, s29, 0x180
	s_addc_u32 s25, s30, 0
	v_readfirstlane_b32 s23, v160
	s_mov_b32 m0, s23
	v_lshl_add_u64 v[164:165], s[24:25], 0, v[136:137]
	v_readfirstlane_b32 s23, v161
	global_load_lds_dwordx4 v[164:165], off
	v_lshl_add_u64 v[164:165], s[24:25], 0, v[138:139]
	s_mov_b32 m0, s23
	s_nop 0
	global_load_lds_dwordx4 v[164:165], off
	s_waitcnt vmcnt(6)
	s_barrier
	s_nop 0
	v_mfma_f32_16x16x32_bf16 v[30:33], v[180:183], v[226:229], v[30:33]
	v_mfma_f32_16x16x32_bf16 v[26:29], v[180:183], v[234:237], v[26:29]
	v_mfma_f32_16x16x32_bf16 v[22:25], v[188:191], v[226:229], v[22:25]
	v_mfma_f32_16x16x32_bf16 v[18:21], v[188:191], v[234:237], v[18:21]
	v_mfma_f32_16x16x32_bf16 v[14:17], v[196:199], v[226:229], v[14:17]
	v_mfma_f32_16x16x32_bf16 v[10:13], v[196:199], v[234:237], v[10:13]
	v_mfma_f32_16x16x32_bf16 v[6:9], v[218:221], v[226:229], v[6:9]
	v_mfma_f32_16x16x32_bf16 v[2:5], v[218:221], v[234:237], v[2:5]
	v_mfma_f32_16x16x32_bf16 v[30:33], v[184:187], v[230:233], v[30:33]
	v_mfma_f32_16x16x32_bf16 v[26:29], v[184:187], v[238:241], v[26:29]
	v_mfma_f32_16x16x32_bf16 v[22:25], v[192:195], v[230:233], v[22:25]
	v_mfma_f32_16x16x32_bf16 v[18:21], v[192:195], v[238:241], v[18:21]
	v_mfma_f32_16x16x32_bf16 v[14:17], v[214:217], v[230:233], v[14:17]
	v_mfma_f32_16x16x32_bf16 v[10:13], v[214:217], v[238:241], v[10:13]
	v_mfma_f32_16x16x32_bf16 v[6:9], v[222:225], v[230:233], v[6:9]
	v_mfma_f32_16x16x32_bf16 v[2:5], v[222:225], v[238:241], v[2:5]
	s_nop 0
	s_add_i32 s17, s17, 2
	s_add_u32 s14, s14, 0x100
	s_addc_u32 s15, s15, 0
	s_cmp_lt_u32 s17, 12
	s_barrier
	s_cbranch_scc1 .LBB0_37
	s_add_u32 s6, s12, 0x780
	s_addc_u32 s7, s13, 0
	v_readfirstlane_b32 s1, v162
	s_nop 0
	ds_read_b128 v[136:139], v147
	ds_read_b128 v[148:151], v147 offset:1024
	ds_read_b128 v[156:159], v147 offset:2048
	ds_read_b128 v[164:167], v147 offset:3072
	ds_read_b128 v[168:171], v145
	ds_read_b128 v[172:175], v145 offset:1024
	ds_read_b128 v[176:179], v145 offset:2048
	ds_read_b128 v[180:183], v145 offset:3072
	ds_read_b128 v[184:187], v145 offset:4096
	ds_read_b128 v[188:191], v145 offset:5120
	ds_read_b128 v[192:195], v145 offset:6144
	ds_read_b128 v[196:199], v145 offset:7168
	s_mov_b32 m0, s1
	v_lshl_add_u64 v[134:135], v[134:135], 1, s[6:7]
	v_readfirstlane_b32 s1, v163
	global_load_lds_dwordx4 v[134:135], off
	v_lshl_add_u64 v[132:133], v[132:133], 1, s[6:7]
	s_mov_b32 m0, s1
	s_nop 0
	global_load_lds_dwordx4 v[132:133], off
	s_barrier
	s_waitcnt lgkmcnt(0)
	s_nop 0
	s_waitcnt lgkmcnt(0)
	v_mfma_f32_16x16x32_bf16 v[126:129], v[168:171], v[136:139], v[126:129]
	v_mfma_f32_16x16x32_bf16 v[122:125], v[168:171], v[156:159], v[122:125]
	v_mfma_f32_16x16x32_bf16 v[118:121], v[176:179], v[136:139], v[118:121]
	v_mfma_f32_16x16x32_bf16 v[114:117], v[176:179], v[156:159], v[114:117]
	v_mfma_f32_16x16x32_bf16 v[126:129], v[172:175], v[148:151], v[126:129]
	v_mfma_f32_16x16x32_bf16 v[122:125], v[172:175], v[164:167], v[122:125]
	v_mfma_f32_16x16x32_bf16 v[118:121], v[180:183], v[148:151], v[118:121]
	v_mfma_f32_16x16x32_bf16 v[114:117], v[180:183], v[164:167], v[114:117]
	v_mfma_f32_16x16x32_bf16 v[110:113], v[184:187], v[136:139], v[110:113]
	v_mfma_f32_16x16x32_bf16 v[106:109], v[184:187], v[156:159], v[106:109]
	v_mfma_f32_16x16x32_bf16 v[102:105], v[192:195], v[136:139], v[102:105]
	v_mfma_f32_16x16x32_bf16 v[98:101], v[192:195], v[156:159], v[98:101]
	v_mfma_f32_16x16x32_bf16 v[132:135], v[188:191], v[148:151], v[110:113]
	v_mfma_f32_16x16x32_bf16 v[160:163], v[188:191], v[164:167], v[106:109]
	v_mfma_f32_16x16x32_bf16 v[214:217], v[196:199], v[148:151], v[102:105]
	v_mfma_f32_16x16x32_bf16 v[218:221], v[196:199], v[164:167], v[98:101]
	s_nop 0
	s_barrier
	s_nop 0
	s_nop 0
	ds_read_b128 v[98:101], v147 offset:16384
	ds_read_b128 v[102:105], v147 offset:17408
	ds_read_b128 v[106:109], v147 offset:18432
	ds_read_b128 v[110:113], v147 offset:19456
	s_barrier
	s_waitcnt lgkmcnt(0)
	s_nop 0
	s_waitcnt lgkmcnt(3)
	v_mfma_f32_16x16x32_bf16 v[94:97], v[168:171], v[98:101], v[94:97]
	s_waitcnt lgkmcnt(1)
	v_mfma_f32_16x16x32_bf16 v[90:93], v[168:171], v[106:109], v[90:93]
	v_mfma_f32_16x16x32_bf16 v[86:89], v[176:179], v[98:101], v[86:89]
	v_mfma_f32_16x16x32_bf16 v[82:85], v[176:179], v[106:109], v[82:85]
	v_mfma_f32_16x16x32_bf16 v[94:97], v[172:175], v[102:105], v[94:97]
	s_waitcnt lgkmcnt(0)
	v_mfma_f32_16x16x32_bf16 v[90:93], v[172:175], v[110:113], v[90:93]
	v_mfma_f32_16x16x32_bf16 v[86:89], v[180:183], v[102:105], v[86:89]
	v_mfma_f32_16x16x32_bf16 v[82:85], v[180:183], v[110:113], v[82:85]
	v_mfma_f32_16x16x32_bf16 v[78:81], v[184:187], v[98:101], v[78:81]
	v_mfma_f32_16x16x32_bf16 v[74:77], v[184:187], v[106:109], v[74:77]
	v_mfma_f32_16x16x32_bf16 v[70:73], v[192:195], v[98:101], v[70:73]
	v_mfma_f32_16x16x32_bf16 v[66:69], v[192:195], v[106:109], v[66:69]
	v_mfma_f32_16x16x32_bf16 v[168:171], v[188:191], v[102:105], v[78:81]
	v_mfma_f32_16x16x32_bf16 v[172:175], v[188:191], v[110:113], v[74:77]
	v_mfma_f32_16x16x32_bf16 v[176:179], v[196:199], v[102:105], v[70:73]
	v_mfma_f32_16x16x32_bf16 v[180:183], v[196:199], v[110:113], v[66:69]
	s_nop 0
	s_barrier
	s_nop 1
	ds_read_b128 v[66:69], v145 offset:16384
	ds_read_b128 v[70:73], v145 offset:17408
	ds_read_b128 v[74:77], v145 offset:18432
	ds_read_b128 v[78:81], v145 offset:19456
	ds_read_b128 v[184:187], v145 offset:20480
	ds_read_b128 v[188:191], v145 offset:21504
	ds_read_b128 v[192:195], v145 offset:22528
	ds_read_b128 v[196:199], v145 offset:23552
	s_waitcnt vmcnt(4)
	s_barrier
; #define LDA(dst, b, h) _Pragma("unroll") for (int m = 0; m < 4; ++m) _Pragma("unroll") for (int k = 0; k < 2; ++k) \
;     dst[m][k] = *(const __attribute__((address_space(3))) bf16x8*)(aB + (((b) * 2 + (h)) * 16384 + m * 2048 + k * 1024))
; #define LDB(dst, b, h) _Pragma("unroll") for (int n = 0; n < 2; ++n) _Pragma("unroll") for (int k = 0; k < 2; ++k) \
;     dst[n][k] = *(const __attribute__((address_space(3))) bf16x8*)(bB + (((b) * 2 + (h)) * 16384 + n * 2048 + k * 1024))
; #define MMA(ai, bj, At, Bq) do { __builtin_amdgcn_s_setprio(1); \
;     _Pragma("unroll") for (int m = 0; m < 4; ++m) _Pragma("unroll") for (int n = 0; n < 2; ++n) _Pragma("unroll") for (int k = 0; k < 2; ++k) \
;       acc[ai][bj][m][n] = __builtin_amdgcn_mfma_f32_16x16x32_bf16(At[m][k], Bq[n][k], acc[ai][bj][m][n], 0, 0, 0); \
;     __builtin_amdgcn_s_setprio(0); } while (0)
; #define WAIT_V(n) asm volatile("s_waitcnt vmcnt(" #n ")" ::: "memory")
; #define WAIT_L(n) asm volatile("s_waitcnt lgkmcnt(" #n ")" ::: "memory")
; #define BAR __builtin_amdgcn_s_barrier()
; template <int MODE>
; DI void gemm_tile(const Params& p, const bf16_t* __restrict__ A, const bf16_t* __restrict__ Bt, int K, int brow, int bcol, int mp, int nt, bool vt, char* smem) {
;     ...
;     LDA(At, 0, 1); WAIT_V(4); BAR; WAIT_L(0); MMA(1, 0, At, B0); MMA(1, 1, At, B1); BAR; }
;   { LDB(B0, 1, 0); LDA(At, 1, 0); WAIT_V(2); BAR; WAIT_L(0); MMA(0, 0, At, B0); BAR;
	s_waitcnt lgkmcnt(0)
	s_nop 0
	s_waitcnt lgkmcnt(7)
	v_mfma_f32_16x16x32_bf16 v[62:65], v[66:69], v[136:139], v[62:65]
	v_mfma_f32_16x16x32_bf16 v[58:61], v[66:69], v[156:159], v[58:61]
	s_waitcnt lgkmcnt(5)
	v_mfma_f32_16x16x32_bf16 v[54:57], v[74:77], v[136:139], v[54:57]
	v_mfma_f32_16x16x32_bf16 v[50:53], v[74:77], v[156:159], v[50:53]
	v_mfma_f32_16x16x32_bf16 v[62:65], v[70:73], v[148:151], v[62:65]
	v_mfma_f32_16x16x32_bf16 v[58:61], v[70:73], v[164:167], v[58:61]
	s_waitcnt lgkmcnt(4)
	v_mfma_f32_16x16x32_bf16 v[54:57], v[78:81], v[148:151], v[54:57]
	v_mfma_f32_16x16x32_bf16 v[50:53], v[78:81], v[164:167], v[50:53]
	s_waitcnt lgkmcnt(3)
	v_mfma_f32_16x16x32_bf16 v[46:49], v[184:187], v[136:139], v[46:49]
	v_mfma_f32_16x16x32_bf16 v[42:45], v[184:187], v[156:159], v[42:45]
	s_waitcnt lgkmcnt(1)
	v_mfma_f32_16x16x32_bf16 v[38:41], v[192:195], v[136:139], v[38:41]
	v_mfma_f32_16x16x32_bf16 v[34:37], v[192:195], v[156:159], v[34:37]
	v_mfma_f32_16x16x32_bf16 v[222:225], v[188:191], v[148:151], v[46:49]
	v_mfma_f32_16x16x32_bf16 v[226:229], v[188:191], v[164:167], v[42:45]
	s_waitcnt lgkmcnt(0)
	v_mfma_f32_16x16x32_bf16 v[136:139], v[196:199], v[148:151], v[38:41]
	v_mfma_f32_16x16x32_bf16 v[148:151], v[196:199], v[164:167], v[34:37]
	s_nop 0
	s_nop 0
	v_mfma_f32_16x16x32_bf16 v[30:33], v[66:69], v[98:101], v[30:33]
	v_mfma_f32_16x16x32_bf16 v[26:29], v[66:69], v[106:109], v[26:29]
	v_mfma_f32_16x16x32_bf16 v[22:25], v[74:77], v[98:101], v[22:25]
	v_mfma_f32_16x16x32_bf16 v[18:21], v[74:77], v[106:109], v[18:21]
	v_mfma_f32_16x16x32_bf16 v[30:33], v[70:73], v[102:105], v[30:33]
	v_mfma_f32_16x16x32_bf16 v[26:29], v[70:73], v[110:113], v[26:29]
	v_mfma_f32_16x16x32_bf16 v[22:25], v[78:81], v[102:105], v[22:25]
	v_mfma_f32_16x16x32_bf16 v[18:21], v[78:81], v[110:113], v[18:21]
	v_mfma_f32_16x16x32_bf16 v[14:17], v[184:187], v[98:101], v[14:17]
	v_mfma_f32_16x16x32_bf16 v[10:13], v[184:187], v[106:109], v[10:13]
	v_mfma_f32_16x16x32_bf16 v[6:9], v[192:195], v[98:101], v[6:9]
	v_mfma_f32_16x16x32_bf16 v[2:5], v[192:195], v[106:109], v[2:5]
	v_mfma_f32_16x16x32_bf16 v[156:159], v[188:191], v[102:105], v[14:17]
	v_mfma_f32_16x16x32_bf16 v[164:167], v[188:191], v[110:113], v[10:13]
	v_mfma_f32_16x16x32_bf16 v[184:187], v[196:199], v[102:105], v[6:9]
	v_mfma_f32_16x16x32_bf16 v[188:191], v[196:199], v[110:113], v[2:5]
	s_nop 0
	s_barrier
	s_nop 1
	ds_read_b128 v[2:5], v147 offset:32768
	ds_read_b128 v[6:9], v147 offset:33792
	ds_read_b128 v[10:13], v147 offset:34816
	ds_read_b128 v[14:17], v147 offset:35840
	ds_read_b128 v[34:37], v145 offset:32768
	ds_read_b128 v[38:41], v145 offset:33792
	ds_read_b128 v[42:45], v145 offset:34816
	ds_read_b128 v[46:49], v145 offset:35840
	ds_read_b128 v[192:195], v145 offset:36864
	ds_read_b128 v[196:199], v145 offset:37888
	ds_read_b128 v[230:233], v145 offset:38912
	ds_read_b128 v[234:237], v145 offset:39936
	s_waitcnt vmcnt(2)
	s_barrier
	s_waitcnt lgkmcnt(0)
	s_nop 0
	s_waitcnt lgkmcnt(7)
	v_mfma_f32_16x16x32_bf16 v[66:69], v[34:37], v[2:5], v[126:129]
	s_waitcnt lgkmcnt(6)
	v_mfma_f32_16x16x32_bf16 v[98:101], v[38:41], v[6:9], v[66:69]
	v_mfma_f32_16x16x32_bf16 v[66:69], v[34:37], v[10:13], v[122:125]
	v_mfma_f32_16x16x32_bf16 v[102:105], v[38:41], v[14:17], v[66:69]
	s_waitcnt lgkmcnt(5)
	v_mfma_f32_16x16x32_bf16 v[66:69], v[42:45], v[2:5], v[118:121]
	s_waitcnt lgkmcnt(4)
	v_mfma_f32_16x16x32_bf16 v[106:109], v[46:49], v[6:9], v[66:69]
	v_mfma_f32_16x16x32_bf16 v[66:69], v[42:45], v[10:13], v[114:117]
	v_mfma_f32_16x16x32_bf16 v[110:113], v[46:49], v[14:17], v[66:69]
	s_waitcnt lgkmcnt(3)
	v_mfma_f32_16x16x32_bf16 v[66:69], v[192:195], v[2:5], v[132:135]
	s_waitcnt lgkmcnt(2)
	v_mfma_f32_16x16x32_bf16 v[114:117], v[196:199], v[6:9], v[66:69]
	v_mfma_f32_16x16x32_bf16 v[66:69], v[192:195], v[10:13], v[160:163]
	v_mfma_f32_16x16x32_bf16 v[118:121], v[196:199], v[14:17], v[66:69]
	s_waitcnt lgkmcnt(1)
	v_mfma_f32_16x16x32_bf16 v[66:69], v[230:233], v[2:5], v[214:217]
	s_waitcnt lgkmcnt(0)
	v_mfma_f32_16x16x32_bf16 v[122:125], v[234:237], v[6:9], v[66:69]
	v_mfma_f32_16x16x32_bf16 v[66:69], v[230:233], v[10:13], v[218:221]
	v_mfma_f32_16x16x32_bf16 v[126:129], v[234:237], v[14:17], v[66:69]
	s_nop 0
	s_barrier
; #define LDA(dst, b, h) _Pragma("unroll") for (int m = 0; m < 4; ++m) _Pragma("unroll") for (int k = 0; k < 2; ++k) \
;     dst[m][k] = *(const __attribute__((address_space(3))) bf16x8*)(aB + (((b) * 2 + (h)) * 16384 + m * 2048 + k * 1024))
; #define LDB(dst, b, h) _Pragma("unroll") for (int n = 0; n < 2; ++n) _Pragma("unroll") for (int k = 0; k < 2; ++k) \
;     dst[n][k] = *(const __attribute__((address_space(3))) bf16x8*)(bB + (((b) * 2 + (h)) * 16384 + n * 2048 + k * 1024))
; #define MMA(ai, bj, At, Bq) do { __builtin_amdgcn_s_setprio(1); \
;     _Pragma("unroll") for (int m = 0; m < 4; ++m) _Pragma("unroll") for (int n = 0; n < 2; ++n) _Pragma("unroll") for (int k = 0; k < 2; ++k) \
;       acc[ai][bj][m][n] = __builtin_amdgcn_mfma_f32_16x16x32_bf16(At[m][k], Bq[n][k], acc[ai][bj][m][n], 0, 0, 0); \
;     __builtin_amdgcn_s_setprio(0); } while (0)
; #define WAIT_V(n) asm volatile("s_waitcnt vmcnt(" #n ")" ::: "memory")
; #define WAIT_L(n) asm volatile("s_waitcnt lgkmcnt(" #n ")" ::: "memory")
; #define BAR __builtin_amdgcn_s_barrier()
; template <int MODE>
; DI void gemm_tile(const Params& p, const bf16_t* __restrict__ A, const bf16_t* __restrict__ Bt, int K, int brow, int bcol, int mp, int nt, bool vt, char* smem) {
;     ...
;   { LDB(B0, 1, 0); LDA(At, 1, 0); WAIT_V(2); BAR; WAIT_L(0); MMA(0, 0, At, B0); BAR;
;     LDB(B1, 1, 1); WAIT_V(0); BAR; WAIT_L(0); MMA(0, 1, At, B1); BAR;
;     LDA(At, 1, 1); BAR; WAIT_L(0); MMA(1, 0, At, B0); MMA(1, 1, At, B1); BAR; }
;   if (wr == 0) BAR;
	ds_read_b128 v[132:135], v147 offset:49152
	ds_read_b128 v[160:163], v147 offset:50176
	ds_read_b128 v[214:217], v147 offset:51200
	ds_read_b128 v[218:221], v147 offset:52224
	s_waitcnt vmcnt(0)
	s_barrier
	s_waitcnt lgkmcnt(0)
	s_nop 0
	s_waitcnt lgkmcnt(3)
	v_mfma_f32_16x16x32_bf16 v[66:69], v[34:37], v[132:135], v[94:97]
	s_waitcnt lgkmcnt(1)
	v_mfma_f32_16x16x32_bf16 v[34:37], v[34:37], v[214:217], v[90:93]
	s_waitcnt lgkmcnt(0)
	v_mfma_f32_16x16x32_bf16 v[70:73], v[38:41], v[218:221], v[34:37]
	v_mfma_f32_16x16x32_bf16 v[34:37], v[42:45], v[132:135], v[86:89]
	v_mfma_f32_16x16x32_bf16 v[74:77], v[46:49], v[160:163], v[34:37]
	v_mfma_f32_16x16x32_bf16 v[34:37], v[42:45], v[214:217], v[82:85]
	v_mfma_f32_16x16x32_bf16 v[78:81], v[46:49], v[218:221], v[34:37]
	v_mfma_f32_16x16x32_bf16 v[34:37], v[192:195], v[132:135], v[168:171]
	v_mfma_f32_16x16x32_bf16 v[82:85], v[196:199], v[160:163], v[34:37]
	v_mfma_f32_16x16x32_bf16 v[34:37], v[192:195], v[214:217], v[172:175]
	v_mfma_f32_16x16x32_bf16 v[86:89], v[196:199], v[218:221], v[34:37]
	v_mfma_f32_16x16x32_bf16 v[34:37], v[230:233], v[132:135], v[176:179]
	v_mfma_f32_16x16x32_bf16 v[90:93], v[234:237], v[160:163], v[34:37]
	v_mfma_f32_16x16x32_bf16 v[34:37], v[230:233], v[214:217], v[180:183]
	v_mfma_f32_16x16x32_bf16 v[66:69], v[38:41], v[160:163], v[66:69]
	v_mfma_f32_16x16x32_bf16 v[94:97], v[234:237], v[218:221], v[34:37]
	s_nop 0
	s_barrier
	ds_read_b128 v[168:171], v145 offset:49152
	ds_read_b128 v[172:175], v145 offset:50176
	ds_read_b128 v[176:179], v145 offset:51200
	ds_read_b128 v[180:183], v145 offset:52224
	ds_read_b128 v[192:195], v145 offset:53248
	ds_read_b128 v[196:199], v145 offset:54272
	ds_read_b128 v[230:233], v145 offset:55296
	ds_read_b128 v[144:147], v145 offset:56320
	s_barrier
	s_waitcnt lgkmcnt(0)
	s_nop 0
	s_waitcnt lgkmcnt(7)
	v_mfma_f32_16x16x32_bf16 v[34:37], v[168:171], v[2:5], v[62:65]
	s_waitcnt lgkmcnt(5)
	v_mfma_f32_16x16x32_bf16 v[42:45], v[176:179], v[2:5], v[54:57]
	v_mfma_f32_16x16x32_bf16 v[46:49], v[176:179], v[10:13], v[50:53]
	s_waitcnt lgkmcnt(3)
	v_mfma_f32_16x16x32_bf16 v[50:53], v[192:195], v[2:5], v[222:225]
	s_waitcnt lgkmcnt(1)
	v_mfma_f32_16x16x32_bf16 v[2:5], v[230:233], v[2:5], v[136:139]
	v_mfma_f32_16x16x32_bf16 v[38:41], v[168:171], v[10:13], v[58:61]
	v_mfma_f32_16x16x32_bf16 v[54:57], v[192:195], v[10:13], v[226:229]
	s_waitcnt lgkmcnt(0)
	v_mfma_f32_16x16x32_bf16 v[58:61], v[144:147], v[6:9], v[2:5]
	v_mfma_f32_16x16x32_bf16 v[2:5], v[230:233], v[10:13], v[148:151]
	v_mfma_f32_16x16x32_bf16 v[34:37], v[172:175], v[6:9], v[34:37]
	v_mfma_f32_16x16x32_bf16 v[38:41], v[172:175], v[14:17], v[38:41]
	v_mfma_f32_16x16x32_bf16 v[42:45], v[180:183], v[6:9], v[42:45]
	v_mfma_f32_16x16x32_bf16 v[46:49], v[180:183], v[14:17], v[46:49]
	v_mfma_f32_16x16x32_bf16 v[50:53], v[196:199], v[6:9], v[50:53]
	v_mfma_f32_16x16x32_bf16 v[54:57], v[196:199], v[14:17], v[54:57]
	v_mfma_f32_16x16x32_bf16 v[62:65], v[144:147], v[14:17], v[2:5]
	s_nop 0
	s_nop 0
	v_mfma_f32_16x16x32_bf16 v[2:5], v[168:171], v[132:135], v[30:33]
	v_mfma_f32_16x16x32_bf16 v[6:9], v[168:171], v[214:217], v[26:29]
	v_mfma_f32_16x16x32_bf16 v[10:13], v[176:179], v[132:135], v[22:25]
	v_mfma_f32_16x16x32_bf16 v[14:17], v[176:179], v[214:217], v[18:21]
	v_mfma_f32_16x16x32_bf16 v[18:21], v[192:195], v[132:135], v[156:159]
	v_mfma_f32_16x16x32_bf16 v[22:25], v[192:195], v[214:217], v[164:167]
	v_mfma_f32_16x16x32_bf16 v[26:29], v[230:233], v[132:135], v[184:187]
	v_mfma_f32_16x16x32_bf16 v[30:33], v[230:233], v[214:217], v[188:191]
	v_mfma_f32_16x16x32_bf16 v[2:5], v[172:175], v[160:163], v[2:5]
	v_mfma_f32_16x16x32_bf16 v[6:9], v[172:175], v[218:221], v[6:9]
	v_mfma_f32_16x16x32_bf16 v[10:13], v[180:183], v[160:163], v[10:13]
	v_mfma_f32_16x16x32_bf16 v[14:17], v[180:183], v[218:221], v[14:17]
	v_mfma_f32_16x16x32_bf16 v[18:21], v[196:199], v[160:163], v[18:21]
	v_mfma_f32_16x16x32_bf16 v[22:25], v[196:199], v[218:221], v[22:25]
	v_mfma_f32_16x16x32_bf16 v[26:29], v[144:147], v[160:163], v[26:29]
	v_mfma_f32_16x16x32_bf16 v[30:33], v[144:147], v[218:221], v[30:33]
	s_nop 0
	s_movk_i32 s1, 0x100
	v_cmp_gt_u32_e32 vcc, s1, v0
	s_barrier
	s_and_saveexec_b64 s[6:7], vcc
	s_cbranch_execz .LBB0_40
	s_barrier

; #define LDA(dst, b, h) _Pragma("unroll") for (int m = 0; m < 4; ++m) _Pragma("unroll") for (int k = 0; k < 2; ++k) \
;     dst[m][k] = *(const __attribute__((address_space(3))) bf16x8*)(aB + (((b) * 2 + (h)) * 16384 + m * 2048 + k * 1024))
; #define WAIT_V(n) asm volatile("s_waitcnt vmcnt(" #n ")" ::: "memory")
; template <int MODE>
; DI void gemm_tile(const Params& p, const bf16_t* __restrict__ A, const bf16_t* __restrict__ Bt, int K, int brow, int bcol, int mp, int nt, bool vt, char* smem) {
;     ...
;   const int wid = tid >> 6, lane = tid & 63, wr = wid >> 2, wc = wid & 3, fr = lane & 15, fq = lane >> 4;
;   const int laneoff = (fr * 64 + fq * 16) ^ ((fr >> 3) << 5);
;   const __attribute__((address_space(3))) char* aB = (const __attribute__((address_space(3))) char*)smem + wr * 8192 + laneoff;
;   const __attribute__((address_space(3))) char* bB = (const __attribute__((address_space(3))) char*)smem + 65536 + wc * 4096 + laneoff;
;   f32x4 acc[2][2][4][2];
; #pragma unroll
;   for (int a = 0; a < 2; ++a)
; #pragma unroll
;     for (int b = 0; b < 2; ++b)
; #pragma unroll
;       for (int m = 0; m < 4; ++m)
; #pragma unroll
;         for (int n = 0; n < 2; ++n) acc[a][b][m][n] = (f32x4){0.f, 0.f, 0.f, 0.f};
;   bf16x8 At[4][2], B0[2][2], B1[2][2];
;   const int ntk = K / 64;
;   const int m0 = mp * 256, n0 = nt * 256;
;   float* rsl = (float*)(smem + 131072);
;   float4 ssa = make_float4(0.f, 0.f, 0.f, 0.f);
;   if (MODE == MODE_PROJ || MODE == MODE_UP)
;     ssa = *(const float4*)((const float*)(p.ws + (MODE == MODE_UP ? OFF_SSB : OFF_SSA)) + (size_t)m0 * 8 + tid * 4);
;   STAGE(SB(0, 0), Bt, bcol, 0); STAGE(SA(0, 0), A, brow, 0);
;   STAGE(SB(0, 1), Bt, bcol + 128, 0); STAGE(SA(0, 1), A, brow + 128, 0);
;   if (wr == 1) BAR;
;   WAIT_V(4); BAR;
;   STAGE(SB(1, 0), Bt, bcol, 1); STAGE(SA(1, 0), A, brow, 1); STAGE(SB(1, 1), Bt, bcol + 128, 1);
;   WAIT_V(6); BAR;
;   if (MODE == MODE_PROJ || MODE == MODE_UP) {
;     float t = (ssa.x + ssa.y) + (ssa.z + ssa.w);
;     t += __shfl_xor(t, 1);
;     if ((tid & 1) == 0) rsl[tid >> 1] = rsqrtf(t * (1.f / 1024.f) + 1e-6f);
;   }
;   for (int t = 0; t < ntk - 2; t += 2) {
;     LDB(B0, 0, 0); SCHED; LDA(At, 0, 0); STAGE(SA(1, 1), A, brow + 128, t + 1);
;     WAIT_L(8); BAR; WAIT_L(0); MMA(0, 0, At, B0); BAR; SCHED;
;     LDB(B1, 0, 1); STAGE(SB(0, 0), Bt, bcol, t + 2);
;     BAR; WAIT_L(0); MMA(0, 1, At, B1); BAR;
.LBB0_58:
	s_or_b64 exec, exec, s[16:17]
	v_and_b32_e32 v147, 15, v144
	v_lshlrev_b32_e32 v0, 2, v144
	s_add_u32 s16, s6, 0x80
	v_add_u32_e32 v156, 0x18000, v138
	v_and_b32_e32 v146, 48, v144
	v_and_b32_e32 v3, 32, v0
	v_lshlrev_b32_e32 v4, 13, v2
	v_lshlrev_b32_e32 v2, 6, v147
	s_addc_u32 s17, s7, 0
	v_readfirstlane_b32 s1, v156
	v_bitop3_b32 v6, v2, v3, v146 bitop3:0x36
	s_waitcnt vmcnt(4)
	s_barrier
	s_mov_b32 m0, s1
	v_lshl_add_u64 v[2:3], s[16:17], 0, v[134:135]
	v_add_u32_e32 v157, 0x1a000, v138
	global_load_lds_dwordx4 v[2:3], off
	v_lshl_add_u64 v[2:3], s[16:17], 0, v[136:137]
	v_readfirstlane_b32 s1, v157
	s_add_u32 s16, s8, 0x80
	v_add_u32_e32 v158, 0x8000, v138
	s_mov_b32 m0, s1
	s_addc_u32 s17, s9, 0
	v_readfirstlane_b32 s1, v158
	global_load_lds_dwordx4 v[2:3], off
	s_mov_b32 m0, s1
	v_lshl_add_u64 v[2:3], s[16:17], 0, v[134:135]
	v_add_u32_e32 v159, 0xa000, v138
	global_load_lds_dwordx4 v[2:3], off
	v_lshl_add_u64 v[2:3], s[16:17], 0, v[136:137]
	v_readfirstlane_b32 s1, v159
	s_add_u32 s16, s10, 0x80
	v_add_u32_e32 v160, 0x1c000, v138
	s_mov_b32 m0, s1
	s_addc_u32 s17, s11, 0
	v_readfirstlane_b32 s1, v160
	v_add_u32_e32 v161, 0x1e000, v138
	global_load_lds_dwordx4 v[2:3], off
	s_mov_b32 m0, s1
	v_lshl_add_u64 v[2:3], s[16:17], 0, v[134:135]
	v_readfirstlane_b32 s1, v161
	global_load_lds_dwordx4 v[2:3], off
	v_lshl_add_u64 v[2:3], s[16:17], 0, v[136:137]
	s_mov_b32 m0, s1
	s_add_u32 s1, s12, 0x100
	global_load_lds_dwordx4 v[2:3], off
	v_bfe_u32 v145, v144, 6, 2
	s_waitcnt vmcnt(6)
	s_addc_u32 s5, s13, 0
	v_lshl_or_b32 v5, v145, 12, v205
	s_add_u32 s16, s20, s14
	s_addc_u32 s17, s21, s15
	s_mov_b32 s24, -2
	s_mov_b64 s[14:15], 0
	v_add_u32_e32 v142, v5, v6
	v_add_u32_e32 v140, v4, v6
	s_nop 0
	s_barrier
	s_nop 0
	ds_read_b128 v[164:167], v142
	ds_read_b128 v[168:171], v142 offset:1024
	ds_read_b128 v[172:175], v142 offset:2048
	ds_read_b128 v[176:179], v142 offset:3072
	s_add_u32 s25, s16, s14
	s_addc_u32 s27, s17, s15
	s_add_u32 s26, s25, 0x80
	v_add_u32_e32 v162, 0xc000, v138
	s_addc_u32 s27, s27, 0
	v_readfirstlane_b32 s25, v162
	v_add_u32_e32 v163, 0xe000, v138
	ds_read_b128 v[180:183], v140
	ds_read_b128 v[184:187], v140 offset:1024
	ds_read_b128 v[188:191], v140 offset:2048
	ds_read_b128 v[192:195], v140 offset:3072
	ds_read_b128 v[196:199], v140 offset:4096
	ds_read_b128 v[214:217], v140 offset:5120
	ds_read_b128 v[218:221], v140 offset:6144
	ds_read_b128 v[222:225], v140 offset:7168
	s_mov_b32 m0, s25
	v_lshl_add_u64 v[226:227], s[26:27], 0, v[134:135]
	v_readfirstlane_b32 s25, v163
	global_load_lds_dwordx4 v[226:227], off
	v_lshl_add_u64 v[226:227], s[26:27], 0, v[136:137]
	s_mov_b32 m0, s25
	s_nop 0
	global_load_lds_dwordx4 v[226:227], off
	s_waitcnt lgkmcnt(8)
	s_barrier
	s_waitcnt lgkmcnt(0)
	s_nop 0
	s_waitcnt lgkmcnt(0)
	v_mfma_f32_16x16x32_bf16 v[126:129], v[180:183], v[164:167], 0
	v_mfma_f32_16x16x32_bf16 v[122:125], v[180:183], v[172:175], 0
	v_mfma_f32_16x16x32_bf16 v[118:121], v[188:191], v[164:167], 0
	v_mfma_f32_16x16x32_bf16 v[114:117], v[188:191], v[172:175], 0
	v_mfma_f32_16x16x32_bf16 v[110:113], v[196:199], v[164:167], 0
	v_mfma_f32_16x16x32_bf16 v[106:109], v[196:199], v[172:175], 0
	v_mfma_f32_16x16x32_bf16 v[102:105], v[218:221], v[164:167], 0
	v_mfma_f32_16x16x32_bf16 v[98:101], v[218:221], v[172:175], 0
	v_mfma_f32_16x16x32_bf16 v[126:129], v[184:187], v[168:171], v[126:129]
	v_mfma_f32_16x16x32_bf16 v[122:125], v[184:187], v[176:179], v[122:125]
	v_mfma_f32_16x16x32_bf16 v[118:121], v[192:195], v[168:171], v[118:121]
	v_mfma_f32_16x16x32_bf16 v[114:117], v[192:195], v[176:179], v[114:117]
	v_mfma_f32_16x16x32_bf16 v[110:113], v[214:217], v[168:171], v[110:113]
	v_mfma_f32_16x16x32_bf16 v[106:109], v[214:217], v[176:179], v[106:109]
	v_mfma_f32_16x16x32_bf16 v[102:105], v[222:225], v[168:171], v[102:105]
	v_mfma_f32_16x16x32_bf16 v[98:101], v[222:225], v[176:179], v[98:101]
	s_nop 0
	s_barrier
	s_add_u32 s25, s6, s14
	s_addc_u32 s28, s7, s15
	s_add_u32 s26, s25, 0x100
	s_addc_u32 s27, s28, 0
	v_readfirstlane_b32 s29, v141
	s_nop 0
	ds_read_b128 v[226:229], v142 offset:16384
	ds_read_b128 v[230:233], v142 offset:17408
	ds_read_b128 v[234:237], v142 offset:18432
	ds_read_b128 v[238:241], v142 offset:19456
	s_mov_b32 m0, s29
	v_lshl_add_u64 v[242:243], s[26:27], 0, v[134:135]
	global_load_lds_dwordx4 v[242:243], off
	v_lshl_add_u64 v[242:243], s[26:27], 0, v[136:137]
	v_readfirstlane_b32 s26, v143
	s_mov_b32 m0, s26
	s_nop 0
	global_load_lds_dwordx4 v[242:243], off
	s_barrier
	s_waitcnt lgkmcnt(0)
	s_nop 0
	s_waitcnt lgkmcnt(0)
	v_mfma_f32_16x16x32_bf16 v[94:97], v[180:183], v[226:229], 0
	v_mfma_f32_16x16x32_bf16 v[90:93], v[180:183], v[234:237], 0
	v_mfma_f32_16x16x32_bf16 v[86:89], v[188:191], v[226:229], 0
	v_mfma_f32_16x16x32_bf16 v[82:85], v[188:191], v[234:237], 0
	v_mfma_f32_16x16x32_bf16 v[78:81], v[196:199], v[226:229], 0
	v_mfma_f32_16x16x32_bf16 v[74:77], v[196:199], v[234:237], 0
	v_mfma_f32_16x16x32_bf16 v[70:73], v[218:221], v[226:229], 0
	v_mfma_f32_16x16x32_bf16 v[66:69], v[218:221], v[234:237], 0
	v_mfma_f32_16x16x32_bf16 v[94:97], v[184:187], v[230:233], v[94:97]
	v_mfma_f32_16x16x32_bf16 v[90:93], v[184:187], v[238:241], v[90:93]
	v_mfma_f32_16x16x32_bf16 v[86:89], v[192:195], v[230:233], v[86:89]
	v_mfma_f32_16x16x32_bf16 v[82:85], v[192:195], v[238:241], v[82:85]
	v_mfma_f32_16x16x32_bf16 v[78:81], v[214:217], v[230:233], v[78:81]
	v_mfma_f32_16x16x32_bf16 v[74:77], v[214:217], v[238:241], v[74:77]
	v_mfma_f32_16x16x32_bf16 v[70:73], v[222:225], v[230:233], v[70:73]
	v_mfma_f32_16x16x32_bf16 v[66:69], v[222:225], v[238:241], v[66:69]
	s_nop 0
	s_add_u32 s29, s8, s14
	s_addc_u32 s30, s9, s15
	s_add_u32 s26, s29, 0x100
	s_addc_u32 s27, s30, 0
	v_readfirstlane_b32 s31, v138
	s_barrier
; #define STAGE(P, BASE, br, kt) do { const bf16_t* _gb = (BASE) + (long)(br) * K + (long)(kt) * 64; asm volatile("" : "+s"(_gb)); \
;     __builtin_amdgcn_global_load_lds((const unsigned*)(_gb + go0), (lds_u32*)((char*)(P) + tid * 16), 16, 0, 0); \
;     __builtin_amdgcn_global_load_lds((const unsigned*)(_gb + go1), (lds_u32*)((char*)(P) + tid * 16 + 8192), 16, 0, 0); } while (0)
; #define LDA(dst, b, h) _Pragma("unroll") for (int m = 0; m < 4; ++m) _Pragma("unroll") for (int k = 0; k < 2; ++k) \
;     dst[m][k] = *(const __attribute__((address_space(3))) bf16x8*)(aB + (((b) * 2 + (h)) * 16384 + m * 2048 + k * 1024))
; #define LDB(dst, b, h) _Pragma("unroll") for (int n = 0; n < 2; ++n) _Pragma("unroll") for (int k = 0; k < 2; ++k) \
;     dst[n][k] = *(const __attribute__((address_space(3))) bf16x8*)(bB + (((b) * 2 + (h)) * 16384 + n * 2048 + k * 1024))
; #define MMA(ai, bj, At, Bq) do { __builtin_amdgcn_s_setprio(1); \
;     _Pragma("unroll") for (int m = 0; m < 4; ++m) _Pragma("unroll") for (int n = 0; n < 2; ++n) _Pragma("unroll") for (int k = 0; k < 2; ++k) \
;       acc[ai][bj][m][n] = __builtin_amdgcn_mfma_f32_16x16x32_bf16(At[m][k], Bq[n][k], acc[ai][bj][m][n], 0, 0, 0); \
;     __builtin_amdgcn_s_setprio(0); } while (0)
; #define WAIT_V(n) asm volatile("s_waitcnt vmcnt(" #n ")" ::: "memory")
; #define WAIT_L(n) asm volatile("s_waitcnt lgkmcnt(" #n ")" ::: "memory")
; #define BAR __builtin_amdgcn_s_barrier()
; #define SCHED __builtin_amdgcn_sched_barrier(0)
; template <int MODE>
; DI void gemm_tile(const Params& p, const bf16_t* __restrict__ A, const bf16_t* __restrict__ Bt, int K, int brow, int bcol, int mp, int nt, bool vt, char* smem) {
;     ...
;     LDB(B0, 0, 0); SCHED; LDA(At, 0, 0); STAGE(SA(1, 1), A, brow + 128, t + 1);
;     WAIT_L(8); BAR; WAIT_L(0); MMA(0, 0, At, B0); BAR; SCHED;
;     LDB(B1, 0, 1); STAGE(SB(0, 0), Bt, bcol, t + 2);
;     BAR; WAIT_L(0); MMA(0, 1, At, B1); BAR;
;     LDA(At, 0, 1); STAGE(SA(0, 0), A, brow, t + 2);
;     BAR; WAIT_L(0); MMA(1, 0, At, B0); BAR; SCHED;
;     STAGE(SB(0, 1), Bt, bcol + 128, t + 2);
;     WAIT_V(6); BAR; MMA(1, 1, At, B1); BAR;
	s_nop 0
	ds_read_b128 v[180:183], v140 offset:16384
	ds_read_b128 v[184:187], v140 offset:17408
	ds_read_b128 v[188:191], v140 offset:18432
	ds_read_b128 v[192:195], v140 offset:19456
	ds_read_b128 v[196:199], v140 offset:20480
	ds_read_b128 v[214:217], v140 offset:21504
	ds_read_b128 v[218:221], v140 offset:22528
	ds_read_b128 v[222:225], v140 offset:23552
	s_mov_b32 m0, s31
	v_lshl_add_u64 v[242:243], s[26:27], 0, v[134:135]
	global_load_lds_dwordx4 v[242:243], off
	v_lshl_add_u64 v[242:243], s[26:27], 0, v[136:137]
	v_readfirstlane_b32 s26, v139
	s_mov_b32 m0, s26
	s_nop 0
	global_load_lds_dwordx4 v[242:243], off
	s_barrier
	s_waitcnt lgkmcnt(0)
	s_nop 0
	s_waitcnt lgkmcnt(0)
	v_mfma_f32_16x16x32_bf16 v[62:65], v[180:183], v[164:167], 0
	v_mfma_f32_16x16x32_bf16 v[58:61], v[180:183], v[172:175], 0
	v_mfma_f32_16x16x32_bf16 v[54:57], v[188:191], v[164:167], 0
	v_mfma_f32_16x16x32_bf16 v[50:53], v[188:191], v[172:175], 0
	v_mfma_f32_16x16x32_bf16 v[46:49], v[196:199], v[164:167], 0
	v_mfma_f32_16x16x32_bf16 v[42:45], v[196:199], v[172:175], 0
	v_mfma_f32_16x16x32_bf16 v[38:41], v[218:221], v[164:167], 0
	v_mfma_f32_16x16x32_bf16 v[34:37], v[218:221], v[172:175], 0
	v_mfma_f32_16x16x32_bf16 v[62:65], v[184:187], v[168:171], v[62:65]
	v_mfma_f32_16x16x32_bf16 v[58:61], v[184:187], v[176:179], v[58:61]
	v_mfma_f32_16x16x32_bf16 v[54:57], v[192:195], v[168:171], v[54:57]
	v_mfma_f32_16x16x32_bf16 v[50:53], v[192:195], v[176:179], v[50:53]
	v_mfma_f32_16x16x32_bf16 v[46:49], v[214:217], v[168:171], v[46:49]
	v_mfma_f32_16x16x32_bf16 v[42:45], v[214:217], v[176:179], v[42:45]
	v_mfma_f32_16x16x32_bf16 v[38:41], v[222:225], v[168:171], v[38:41]
	v_mfma_f32_16x16x32_bf16 v[34:37], v[222:225], v[176:179], v[34:37]
	s_nop 0
	s_barrier
	s_add_u32 s31, s10, s14
	s_addc_u32 s34, s11, s15
	s_add_u32 s26, s31, 0x100
	s_addc_u32 s27, s34, 0
	v_readfirstlane_b32 s35, v148
	s_mov_b32 m0, s35
	v_lshl_add_u64 v[164:165], s[26:27], 0, v[134:135]
	global_load_lds_dwordx4 v[164:165], off
	v_lshl_add_u64 v[164:165], s[26:27], 0, v[136:137]
	v_readfirstlane_b32 s26, v149
	s_mov_b32 m0, s26
	s_nop 0
	global_load_lds_dwordx4 v[164:165], off
	s_waitcnt vmcnt(6)
	s_barrier
	s_nop 0
	v_mfma_f32_16x16x32_bf16 v[30:33], v[180:183], v[226:229], 0
	v_mfma_f32_16x16x32_bf16 v[26:29], v[180:183], v[234:237], 0
	v_mfma_f32_16x16x32_bf16 v[22:25], v[188:191], v[226:229], 0
	v_mfma_f32_16x16x32_bf16 v[18:21], v[188:191], v[234:237], 0
	v_mfma_f32_16x16x32_bf16 v[14:17], v[196:199], v[226:229], 0
	v_mfma_f32_16x16x32_bf16 v[10:13], v[196:199], v[234:237], 0
	v_mfma_f32_16x16x32_bf16 v[6:9], v[218:221], v[226:229], 0
	v_mfma_f32_16x16x32_bf16 v[2:5], v[218:221], v[234:237], 0
	v_mfma_f32_16x16x32_bf16 v[30:33], v[184:187], v[230:233], v[30:33]
	v_mfma_f32_16x16x32_bf16 v[26:29], v[184:187], v[238:241], v[26:29]
	v_mfma_f32_16x16x32_bf16 v[22:25], v[192:195], v[230:233], v[22:25]
	v_mfma_f32_16x16x32_bf16 v[18:21], v[192:195], v[238:241], v[18:21]
	v_mfma_f32_16x16x32_bf16 v[14:17], v[214:217], v[230:233], v[14:17]
	v_mfma_f32_16x16x32_bf16 v[10:13], v[214:217], v[238:241], v[10:13]
	v_mfma_f32_16x16x32_bf16 v[6:9], v[222:225], v[230:233], v[6:9]
	v_mfma_f32_16x16x32_bf16 v[2:5], v[222:225], v[238:241], v[2:5]
	s_nop 0
	s_barrier
	s_branch .Lgemm1_p5
.LBB0_59:
	s_nop 0
	ds_read_b128 v[164:167], v142
	ds_read_b128 v[168:171], v142 offset:1024
	ds_read_b128 v[172:175], v142 offset:2048
	ds_read_b128 v[176:179], v142 offset:3072
	s_add_u32 s25, s16, s14
	s_addc_u32 s27, s17, s15
	s_add_u32 s26, s25, 0x80
	v_add_u32_e32 v162, 0xc000, v138
	s_addc_u32 s27, s27, 0
	v_readfirstlane_b32 s25, v162
	v_add_u32_e32 v163, 0xe000, v138
	ds_read_b128 v[180:183], v140
	ds_read_b128 v[184:187], v140 offset:1024
	ds_read_b128 v[188:191], v140 offset:2048
	ds_read_b128 v[192:195], v140 offset:3072
	ds_read_b128 v[196:199], v140 offset:4096
	ds_read_b128 v[214:217], v140 offset:5120
	ds_read_b128 v[218:221], v140 offset:6144
	ds_read_b128 v[222:225], v140 offset:7168
	s_mov_b32 m0, s25
	v_lshl_add_u64 v[226:227], s[26:27], 0, v[134:135]
	v_readfirstlane_b32 s25, v163
	global_load_lds_dwordx4 v[226:227], off
	v_lshl_add_u64 v[226:227], s[26:27], 0, v[136:137]
	s_mov_b32 m0, s25
	s_nop 0
	global_load_lds_dwordx4 v[226:227], off
	s_waitcnt lgkmcnt(8)
	s_barrier
	s_waitcnt lgkmcnt(0)
	s_nop 0
	s_waitcnt lgkmcnt(0)
	v_mfma_f32_16x16x32_bf16 v[126:129], v[180:183], v[164:167], v[126:129]
	v_mfma_f32_16x16x32_bf16 v[122:125], v[180:183], v[172:175], v[122:125]
	v_mfma_f32_16x16x32_bf16 v[118:121], v[188:191], v[164:167], v[118:121]
	v_mfma_f32_16x16x32_bf16 v[114:117], v[188:191], v[172:175], v[114:117]
	v_mfma_f32_16x16x32_bf16 v[110:113], v[196:199], v[164:167], v[110:113]
	v_mfma_f32_16x16x32_bf16 v[106:109], v[196:199], v[172:175], v[106:109]
	v_mfma_f32_16x16x32_bf16 v[102:105], v[218:221], v[164:167], v[102:105]
	v_mfma_f32_16x16x32_bf16 v[98:101], v[218:221], v[172:175], v[98:101]
	v_mfma_f32_16x16x32_bf16 v[126:129], v[184:187], v[168:171], v[126:129]
	v_mfma_f32_16x16x32_bf16 v[122:125], v[184:187], v[176:179], v[122:125]
	v_mfma_f32_16x16x32_bf16 v[118:121], v[192:195], v[168:171], v[118:121]
	v_mfma_f32_16x16x32_bf16 v[114:117], v[192:195], v[176:179], v[114:117]
	v_mfma_f32_16x16x32_bf16 v[110:113], v[214:217], v[168:171], v[110:113]
	v_mfma_f32_16x16x32_bf16 v[106:109], v[214:217], v[176:179], v[106:109]
	v_mfma_f32_16x16x32_bf16 v[102:105], v[222:225], v[168:171], v[102:105]
	v_mfma_f32_16x16x32_bf16 v[98:101], v[222:225], v[176:179], v[98:101]
	s_nop 0
	s_barrier
; #define STAGE(P, BASE, br, kt) do { const bf16_t* _gb = (BASE) + (long)(br) * K + (long)(kt) * 64; asm volatile("" : "+s"(_gb)); \
;     __builtin_amdgcn_global_load_lds((const unsigned*)(_gb + go0), (lds_u32*)((char*)(P) + tid * 16), 16, 0, 0); \
;     __builtin_amdgcn_global_load_lds((const unsigned*)(_gb + go1), (lds_u32*)((char*)(P) + tid * 16 + 8192), 16, 0, 0); } while (0)
; #define LDA(dst, b, h) _Pragma("unroll") for (int m = 0; m < 4; ++m) _Pragma("unroll") for (int k = 0; k < 2; ++k) \
;     dst[m][k] = *(const __attribute__((address_space(3))) bf16x8*)(aB + (((b) * 2 + (h)) * 16384 + m * 2048 + k * 1024))
; #define LDB(dst, b, h) _Pragma("unroll") for (int n = 0; n < 2; ++n) _Pragma("unroll") for (int k = 0; k < 2; ++k) \
;     dst[n][k] = *(const __attribute__((address_space(3))) bf16x8*)(bB + (((b) * 2 + (h)) * 16384 + n * 2048 + k * 1024))
; #define MMA(ai, bj, At, Bq) do { __builtin_amdgcn_s_setprio(1); \
;     _Pragma("unroll") for (int m = 0; m < 4; ++m) _Pragma("unroll") for (int n = 0; n < 2; ++n) _Pragma("unroll") for (int k = 0; k < 2; ++k) \
;       acc[ai][bj][m][n] = __builtin_amdgcn_mfma_f32_16x16x32_bf16(At[m][k], Bq[n][k], acc[ai][bj][m][n], 0, 0, 0); \
;     __builtin_amdgcn_s_setprio(0); } while (0)
; #define WAIT_V(n) asm volatile("s_waitcnt vmcnt(" #n ")" ::: "memory")
; #define WAIT_L(n) asm volatile("s_waitcnt lgkmcnt(" #n ")" ::: "memory")
; #define BAR __builtin_amdgcn_s_barrier()
; #define SCHED __builtin_amdgcn_sched_barrier(0)
; template <int MODE>
; DI void gemm_tile(const Params& p, const bf16_t* __restrict__ A, const bf16_t* __restrict__ Bt, int K, int brow, int bcol, int mp, int nt, bool vt, char* smem) {
;     ...
;     LDB(B1, 0, 1); STAGE(SB(0, 0), Bt, bcol, t + 2);
;     BAR; WAIT_L(0); MMA(0, 1, At, B1); BAR;
;     LDA(At, 0, 1); STAGE(SA(0, 0), A, brow, t + 2);
;     BAR; WAIT_L(0); MMA(1, 0, At, B0); BAR; SCHED;
;     STAGE(SB(0, 1), Bt, bcol + 128, t + 2);
;     WAIT_V(6); BAR; MMA(1, 1, At, B1); BAR;
	s_add_u32 s25, s6, s14
	s_addc_u32 s28, s7, s15
	s_add_u32 s26, s25, 0x100
	s_addc_u32 s27, s28, 0
	v_readfirstlane_b32 s29, v141
	s_nop 0
	ds_read_b128 v[226:229], v142 offset:16384
	ds_read_b128 v[230:233], v142 offset:17408
	ds_read_b128 v[234:237], v142 offset:18432
	ds_read_b128 v[238:241], v142 offset:19456
	s_mov_b32 m0, s29
	v_lshl_add_u64 v[242:243], s[26:27], 0, v[134:135]
	global_load_lds_dwordx4 v[242:243], off
	v_lshl_add_u64 v[242:243], s[26:27], 0, v[136:137]
	v_readfirstlane_b32 s26, v143
	s_mov_b32 m0, s26
	s_nop 0
	global_load_lds_dwordx4 v[242:243], off
	s_barrier
	s_waitcnt lgkmcnt(0)
	s_nop 0
	s_waitcnt lgkmcnt(0)
	v_mfma_f32_16x16x32_bf16 v[94:97], v[180:183], v[226:229], v[94:97]
	v_mfma_f32_16x16x32_bf16 v[90:93], v[180:183], v[234:237], v[90:93]
	v_mfma_f32_16x16x32_bf16 v[86:89], v[188:191], v[226:229], v[86:89]
	v_mfma_f32_16x16x32_bf16 v[82:85], v[188:191], v[234:237], v[82:85]
	v_mfma_f32_16x16x32_bf16 v[78:81], v[196:199], v[226:229], v[78:81]
	v_mfma_f32_16x16x32_bf16 v[74:77], v[196:199], v[234:237], v[74:77]
	v_mfma_f32_16x16x32_bf16 v[70:73], v[218:221], v[226:229], v[70:73]
	v_mfma_f32_16x16x32_bf16 v[66:69], v[218:221], v[234:237], v[66:69]
	v_mfma_f32_16x16x32_bf16 v[94:97], v[184:187], v[230:233], v[94:97]
	v_mfma_f32_16x16x32_bf16 v[90:93], v[184:187], v[238:241], v[90:93]
	v_mfma_f32_16x16x32_bf16 v[86:89], v[192:195], v[230:233], v[86:89]
	v_mfma_f32_16x16x32_bf16 v[82:85], v[192:195], v[238:241], v[82:85]
	v_mfma_f32_16x16x32_bf16 v[78:81], v[214:217], v[230:233], v[78:81]
	v_mfma_f32_16x16x32_bf16 v[74:77], v[214:217], v[238:241], v[74:77]
	v_mfma_f32_16x16x32_bf16 v[70:73], v[222:225], v[230:233], v[70:73]
	v_mfma_f32_16x16x32_bf16 v[66:69], v[222:225], v[238:241], v[66:69]
	s_nop 0
	s_add_u32 s29, s8, s14
	s_addc_u32 s30, s9, s15
	s_add_u32 s26, s29, 0x100
	s_addc_u32 s27, s30, 0
	v_readfirstlane_b32 s31, v138
	s_barrier
	s_nop 0
	ds_read_b128 v[180:183], v140 offset:16384
	ds_read_b128 v[184:187], v140 offset:17408
	ds_read_b128 v[188:191], v140 offset:18432
	ds_read_b128 v[192:195], v140 offset:19456
	ds_read_b128 v[196:199], v140 offset:20480
	ds_read_b128 v[214:217], v140 offset:21504
	ds_read_b128 v[218:221], v140 offset:22528
	ds_read_b128 v[222:225], v140 offset:23552
	s_mov_b32 m0, s31
	v_lshl_add_u64 v[242:243], s[26:27], 0, v[134:135]
	global_load_lds_dwordx4 v[242:243], off
	v_lshl_add_u64 v[242:243], s[26:27], 0, v[136:137]
	v_readfirstlane_b32 s26, v139
	s_mov_b32 m0, s26
	s_nop 0
	global_load_lds_dwordx4 v[242:243], off
	s_barrier
	s_waitcnt lgkmcnt(0)
	s_nop 0
	s_waitcnt lgkmcnt(0)
	v_mfma_f32_16x16x32_bf16 v[62:65], v[180:183], v[164:167], v[62:65]
	v_mfma_f32_16x16x32_bf16 v[58:61], v[180:183], v[172:175], v[58:61]
	v_mfma_f32_16x16x32_bf16 v[54:57], v[188:191], v[164:167], v[54:57]
	v_mfma_f32_16x16x32_bf16 v[50:53], v[188:191], v[172:175], v[50:53]
	v_mfma_f32_16x16x32_bf16 v[46:49], v[196:199], v[164:167], v[46:49]
	v_mfma_f32_16x16x32_bf16 v[42:45], v[196:199], v[172:175], v[42:45]
	v_mfma_f32_16x16x32_bf16 v[38:41], v[218:221], v[164:167], v[38:41]
	v_mfma_f32_16x16x32_bf16 v[34:37], v[218:221], v[172:175], v[34:37]
	v_mfma_f32_16x16x32_bf16 v[62:65], v[184:187], v[168:171], v[62:65]
	v_mfma_f32_16x16x32_bf16 v[58:61], v[184:187], v[176:179], v[58:61]
	v_mfma_f32_16x16x32_bf16 v[54:57], v[192:195], v[168:171], v[54:57]
	v_mfma_f32_16x16x32_bf16 v[50:53], v[192:195], v[176:179], v[50:53]
	v_mfma_f32_16x16x32_bf16 v[46:49], v[214:217], v[168:171], v[46:49]
	v_mfma_f32_16x16x32_bf16 v[42:45], v[214:217], v[176:179], v[42:45]
	v_mfma_f32_16x16x32_bf16 v[38:41], v[222:225], v[168:171], v[38:41]
	v_mfma_f32_16x16x32_bf16 v[34:37], v[222:225], v[176:179], v[34:37]
	s_nop 0
	s_barrier
	s_add_u32 s31, s10, s14
	s_addc_u32 s34, s11, s15
	s_add_u32 s26, s31, 0x100
	s_addc_u32 s27, s34, 0
	v_readfirstlane_b32 s35, v148
	s_mov_b32 m0, s35
	v_lshl_add_u64 v[164:165], s[26:27], 0, v[134:135]
	global_load_lds_dwordx4 v[164:165], off
	v_lshl_add_u64 v[164:165], s[26:27], 0, v[136:137]
	v_readfirstlane_b32 s26, v149
	s_mov_b32 m0, s26
	s_nop 0
	global_load_lds_dwordx4 v[164:165], off
	s_waitcnt vmcnt(6)
	s_barrier
	s_nop 0
	v_mfma_f32_16x16x32_bf16 v[30:33], v[180:183], v[226:229], v[30:33]
	v_mfma_f32_16x16x32_bf16 v[26:29], v[180:183], v[234:237], v[26:29]
	v_mfma_f32_16x16x32_bf16 v[22:25], v[188:191], v[226:229], v[22:25]
	v_mfma_f32_16x16x32_bf16 v[18:21], v[188:191], v[234:237], v[18:21]
	v_mfma_f32_16x16x32_bf16 v[14:17], v[196:199], v[226:229], v[14:17]
	v_mfma_f32_16x16x32_bf16 v[10:13], v[196:199], v[234:237], v[10:13]
	v_mfma_f32_16x16x32_bf16 v[6:9], v[218:221], v[226:229], v[6:9]
	v_mfma_f32_16x16x32_bf16 v[2:5], v[218:221], v[234:237], v[2:5]
	v_mfma_f32_16x16x32_bf16 v[30:33], v[184:187], v[230:233], v[30:33]
	v_mfma_f32_16x16x32_bf16 v[26:29], v[184:187], v[238:241], v[26:29]
	v_mfma_f32_16x16x32_bf16 v[22:25], v[192:195], v[230:233], v[22:25]
	v_mfma_f32_16x16x32_bf16 v[18:21], v[192:195], v[238:241], v[18:21]
	v_mfma_f32_16x16x32_bf16 v[14:17], v[214:217], v[230:233], v[14:17]
	v_mfma_f32_16x16x32_bf16 v[10:13], v[214:217], v[238:241], v[10:13]
	v_mfma_f32_16x16x32_bf16 v[6:9], v[222:225], v[230:233], v[6:9]
	v_mfma_f32_16x16x32_bf16 v[2:5], v[222:225], v[238:241], v[2:5]
	s_nop 0
	s_barrier
; #define STAGE(P, BASE, br, kt) do { const bf16_t* _gb = (BASE) + (long)(br) * K + (long)(kt) * 64; asm volatile("" : "+s"(_gb)); \
;     __builtin_amdgcn_global_load_lds((const unsigned*)(_gb + go0), (lds_u32*)((char*)(P) + tid * 16), 16, 0, 0); \
;     __builtin_amdgcn_global_load_lds((const unsigned*)(_gb + go1), (lds_u32*)((char*)(P) + tid * 16 + 8192), 16, 0, 0); } while (0)
; #define LDA(dst, b, h) _Pragma("unroll") for (int m = 0; m < 4; ++m) _Pragma("unroll") for (int k = 0; k < 2; ++k) \
;     dst[m][k] = *(const __attribute__((address_space(3))) bf16x8*)(aB + (((b) * 2 + (h)) * 16384 + m * 2048 + k * 1024))
; #define LDB(dst, b, h) _Pragma("unroll") for (int n = 0; n < 2; ++n) _Pragma("unroll") for (int k = 0; k < 2; ++k) \
;     dst[n][k] = *(const __attribute__((address_space(3))) bf16x8*)(bB + (((b) * 2 + (h)) * 16384 + n * 2048 + k * 1024))
; #define MMA(ai, bj, At, Bq) do { __builtin_amdgcn_s_setprio(1); \
;     _Pragma("unroll") for (int m = 0; m < 4; ++m) _Pragma("unroll") for (int n = 0; n < 2; ++n) _Pragma("unroll") for (int k = 0; k < 2; ++k) \
;       acc[ai][bj][m][n] = __builtin_amdgcn_mfma_f32_16x16x32_bf16(At[m][k], Bq[n][k], acc[ai][bj][m][n], 0, 0, 0); \
;     __builtin_amdgcn_s_setprio(0); } while (0)
; #define WAIT_L(n) asm volatile("s_waitcnt lgkmcnt(" #n ")" ::: "memory")
; #define BAR __builtin_amdgcn_s_barrier()
; #define SCHED __builtin_amdgcn_sched_barrier(0)
; template <int MODE>
; DI void gemm_tile(const Params& p, const bf16_t* __restrict__ A, const bf16_t* __restrict__ Bt, int K, int brow, int bcol, int mp, int nt, bool vt, char* smem) {
;     ...
;     LDB(B0, 1, 0); SCHED; LDA(At, 1, 0); STAGE(SA(0, 1), A, brow + 128, t + 2);
;     WAIT_L(8); BAR; WAIT_L(0); MMA(0, 0, At, B0); BAR; SCHED;
;     LDB(B1, 1, 1); STAGE(SB(1, 0), Bt, bcol, t + 3);
;     BAR; WAIT_L(0); MMA(0, 1, At, B1); BAR;
;     LDA(At, 1, 1); STAGE(SA(1, 0), A, brow, t + 3);
;     BAR; WAIT_L(0); MMA(1, 0, At, B0); BAR; SCHED;
.Lgemm1_p5:
	s_nop 0
	ds_read_b128 v[164:167], v142 offset:32768
	ds_read_b128 v[168:171], v142 offset:33792
	ds_read_b128 v[172:175], v142 offset:34816
	ds_read_b128 v[176:179], v142 offset:35840
	s_add_u32 s26, s1, s14
	s_addc_u32 s27, s5, s15
	v_readfirstlane_b32 s35, v150
	ds_read_b128 v[180:183], v140 offset:32768
	ds_read_b128 v[184:187], v140 offset:33792
	ds_read_b128 v[188:191], v140 offset:34816
	ds_read_b128 v[192:195], v140 offset:35840
	ds_read_b128 v[196:199], v140 offset:36864
	ds_read_b128 v[214:217], v140 offset:37888
	ds_read_b128 v[218:221], v140 offset:38912
	ds_read_b128 v[222:225], v140 offset:39936
	s_mov_b32 m0, s35
	v_lshl_add_u64 v[226:227], s[26:27], 0, v[134:135]
	global_load_lds_dwordx4 v[226:227], off
	v_lshl_add_u64 v[226:227], s[26:27], 0, v[136:137]
	v_readfirstlane_b32 s26, v151
	s_mov_b32 m0, s26
	s_nop 0
	global_load_lds_dwordx4 v[226:227], off
	s_waitcnt lgkmcnt(8)
	s_barrier
	s_waitcnt lgkmcnt(0)
	s_nop 0
	s_waitcnt lgkmcnt(0)
	v_mfma_f32_16x16x32_bf16 v[126:129], v[180:183], v[164:167], v[126:129]
	v_mfma_f32_16x16x32_bf16 v[122:125], v[180:183], v[172:175], v[122:125]
	v_mfma_f32_16x16x32_bf16 v[118:121], v[188:191], v[164:167], v[118:121]
	v_mfma_f32_16x16x32_bf16 v[114:117], v[188:191], v[172:175], v[114:117]
	v_mfma_f32_16x16x32_bf16 v[110:113], v[196:199], v[164:167], v[110:113]
	v_mfma_f32_16x16x32_bf16 v[106:109], v[196:199], v[172:175], v[106:109]
	v_mfma_f32_16x16x32_bf16 v[102:105], v[218:221], v[164:167], v[102:105]
	v_mfma_f32_16x16x32_bf16 v[98:101], v[218:221], v[172:175], v[98:101]
	v_mfma_f32_16x16x32_bf16 v[126:129], v[184:187], v[168:171], v[126:129]
	v_mfma_f32_16x16x32_bf16 v[122:125], v[184:187], v[176:179], v[122:125]
	v_mfma_f32_16x16x32_bf16 v[118:121], v[192:195], v[168:171], v[118:121]
	v_mfma_f32_16x16x32_bf16 v[114:117], v[192:195], v[176:179], v[114:117]
	v_mfma_f32_16x16x32_bf16 v[110:113], v[214:217], v[168:171], v[110:113]
	v_mfma_f32_16x16x32_bf16 v[106:109], v[214:217], v[176:179], v[106:109]
	v_mfma_f32_16x16x32_bf16 v[102:105], v[222:225], v[168:171], v[102:105]
	v_mfma_f32_16x16x32_bf16 v[98:101], v[222:225], v[176:179], v[98:101]
	s_nop 0
	s_barrier
	s_add_u32 s26, s25, 0x180
	s_addc_u32 s27, s28, 0
	v_readfirstlane_b32 s25, v156
	s_nop 0
	ds_read_b128 v[226:229], v142 offset:49152
	ds_read_b128 v[230:233], v142 offset:50176
	ds_read_b128 v[234:237], v142 offset:51200
	ds_read_b128 v[238:241], v142 offset:52224
	s_mov_b32 m0, s25
	v_lshl_add_u64 v[242:243], s[26:27], 0, v[134:135]
	v_readfirstlane_b32 s25, v157
	global_load_lds_dwordx4 v[242:243], off
	v_lshl_add_u64 v[242:243], s[26:27], 0, v[136:137]
	s_mov_b32 m0, s25
	s_nop 0
	global_load_lds_dwordx4 v[242:243], off
	s_barrier
	s_waitcnt lgkmcnt(0)
	s_nop 0
	s_waitcnt lgkmcnt(0)
	v_mfma_f32_16x16x32_bf16 v[94:97], v[180:183], v[226:229], v[94:97]
	v_mfma_f32_16x16x32_bf16 v[90:93], v[180:183], v[234:237], v[90:93]
	v_mfma_f32_16x16x32_bf16 v[86:89], v[188:191], v[226:229], v[86:89]
	v_mfma_f32_16x16x32_bf16 v[82:85], v[188:191], v[234:237], v[82:85]
	v_mfma_f32_16x16x32_bf16 v[78:81], v[196:199], v[226:229], v[78:81]
	v_mfma_f32_16x16x32_bf16 v[74:77], v[196:199], v[234:237], v[74:77]
	v_mfma_f32_16x16x32_bf16 v[70:73], v[218:221], v[226:229], v[70:73]
	v_mfma_f32_16x16x32_bf16 v[66:69], v[218:221], v[234:237], v[66:69]
	v_mfma_f32_16x16x32_bf16 v[94:97], v[184:187], v[230:233], v[94:97]
	v_mfma_f32_16x16x32_bf16 v[90:93], v[184:187], v[238:241], v[90:93]
	v_mfma_f32_16x16x32_bf16 v[86:89], v[192:195], v[230:233], v[86:89]
	v_mfma_f32_16x16x32_bf16 v[82:85], v[192:195], v[238:241], v[82:85]
	v_mfma_f32_16x16x32_bf16 v[78:81], v[214:217], v[230:233], v[78:81]
	v_mfma_f32_16x16x32_bf16 v[74:77], v[214:217], v[238:241], v[74:77]
	v_mfma_f32_16x16x32_bf16 v[70:73], v[222:225], v[230:233], v[70:73]
	v_mfma_f32_16x16x32_bf16 v[66:69], v[222:225], v[238:241], v[66:69]
	s_nop 0
	s_add_u32 s26, s29, 0x180
	s_addc_u32 s27, s30, 0
	v_readfirstlane_b32 s25, v158
	s_barrier
	s_nop 0
	ds_read_b128 v[180:183], v140 offset:49152
	ds_read_b128 v[184:187], v140 offset:50176
	ds_read_b128 v[188:191], v140 offset:51200
	ds_read_b128 v[192:195], v140 offset:52224
	ds_read_b128 v[196:199], v140 offset:53248
	ds_read_b128 v[214:217], v140 offset:54272
	ds_read_b128 v[218:221], v140 offset:55296
	ds_read_b128 v[222:225], v140 offset:56320
	s_mov_b32 m0, s25
	v_lshl_add_u64 v[242:243], s[26:27], 0, v[134:135]
	v_readfirstlane_b32 s25, v159
	global_load_lds_dwordx4 v[242:243], off
	v_lshl_add_u64 v[242:243], s[26:27], 0, v[136:137]
	s_mov_b32 m0, s25
	s_nop 0
	global_load_lds_dwordx4 v[242:243], off
	s_barrier
	s_waitcnt lgkmcnt(0)
	s_nop 0
	s_waitcnt lgkmcnt(0)
	v_mfma_f32_16x16x32_bf16 v[62:65], v[180:183], v[164:167], v[62:65]
	v_mfma_f32_16x16x32_bf16 v[58:61], v[180:183], v[172:175], v[58:61]
	v_mfma_f32_16x16x32_bf16 v[54:57], v[188:191], v[164:167], v[54:57]
	v_mfma_f32_16x16x32_bf16 v[50:53], v[188:191], v[172:175], v[50:53]
	v_mfma_f32_16x16x32_bf16 v[46:49], v[196:199], v[164:167], v[46:49]
	v_mfma_f32_16x16x32_bf16 v[42:45], v[196:199], v[172:175], v[42:45]
	v_mfma_f32_16x16x32_bf16 v[38:41], v[218:221], v[164:167], v[38:41]
	v_mfma_f32_16x16x32_bf16 v[34:37], v[218:221], v[172:175], v[34:37]
	v_mfma_f32_16x16x32_bf16 v[62:65], v[184:187], v[168:171], v[62:65]
	v_mfma_f32_16x16x32_bf16 v[58:61], v[184:187], v[176:179], v[58:61]
	v_mfma_f32_16x16x32_bf16 v[54:57], v[192:195], v[168:171], v[54:57]
	v_mfma_f32_16x16x32_bf16 v[50:53], v[192:195], v[176:179], v[50:53]
	v_mfma_f32_16x16x32_bf16 v[46:49], v[214:217], v[168:171], v[46:49]
	v_mfma_f32_16x16x32_bf16 v[42:45], v[214:217], v[176:179], v[42:45]
	v_mfma_f32_16x16x32_bf16 v[38:41], v[222:225], v[168:171], v[38:41]
	v_mfma_f32_16x16x32_bf16 v[34:37], v[222:225], v[176:179], v[34:37]
	s_nop 0
	s_barrier
; #define STAGE(P, BASE, br, kt) do { const bf16_t* _gb = (BASE) + (long)(br) * K + (long)(kt) * 64; asm volatile("" : "+s"(_gb)); \
;     __builtin_amdgcn_global_load_lds((const unsigned*)(_gb + go0), (lds_u32*)((char*)(P) + tid * 16), 16, 0, 0); \
;     __builtin_amdgcn_global_load_lds((const unsigned*)(_gb + go1), (lds_u32*)((char*)(P) + tid * 16 + 8192), 16, 0, 0); } while (0)
; #define LDA(dst, b, h) _Pragma("unroll") for (int m = 0; m < 4; ++m) _Pragma("unroll") for (int k = 0; k < 2; ++k) \
;     dst[m][k] = *(const __attribute__((address_space(3))) bf16x8*)(aB + (((b) * 2 + (h)) * 16384 + m * 2048 + k * 1024))
; #define LDB(dst, b, h) _Pragma("unroll") for (int n = 0; n < 2; ++n) _Pragma("unroll") for (int k = 0; k < 2; ++k) \
;     dst[n][k] = *(const __attribute__((address_space(3))) bf16x8*)(bB + (((b) * 2 + (h)) * 16384 + n * 2048 + k * 1024))
; #define MMA(ai, bj, At, Bq) do { __builtin_amdgcn_s_setprio(1); \
;     _Pragma("unroll") for (int m = 0; m < 4; ++m) _Pragma("unroll") for (int n = 0; n < 2; ++n) _Pragma("unroll") for (int k = 0; k < 2; ++k) \
;       acc[ai][bj][m][n] = __builtin_amdgcn_mfma_f32_16x16x32_bf16(At[m][k], Bq[n][k], acc[ai][bj][m][n], 0, 0, 0); \
;     __builtin_amdgcn_s_setprio(0); } while (0)
; #define WAIT_V(n) asm volatile("s_waitcnt vmcnt(" #n ")" ::: "memory")
; #define WAIT_L(n) asm volatile("s_waitcnt lgkmcnt(" #n ")" ::: "memory")
; #define BAR __builtin_amdgcn_s_barrier()
; template <int MODE>
; DI void gemm_tile(const Params& p, const bf16_t* __restrict__ A, const bf16_t* __restrict__ Bt, int K, int brow, int bcol, int mp, int nt, bool vt, char* smem) {
;     ...
;     STAGE(SB(1, 1), Bt, bcol + 128, t + 3);
;     WAIT_V(6); BAR; MMA(1, 1, At, B1); BAR;
;   }
;   { LDB(B0, 0, 0); LDA(At, 0, 0); STAGE(SA(1, 1), A, brow + 128, ntk - 1);
;     BAR; WAIT_L(0); MMA(0, 0, At, B0); BAR;
;     LDB(B1, 0, 1); BAR; WAIT_L(0); MMA(0, 1, At, B1); BAR;
;     LDA(At, 0, 1); WAIT_V(4); BAR; WAIT_L(0); MMA(1, 0, At, B0); MMA(1, 1, At, B1); BAR; }
	s_add_u32 s26, s31, 0x180
	s_addc_u32 s27, s34, 0
	v_readfirstlane_b32 s25, v160
	s_mov_b32 m0, s25
	v_lshl_add_u64 v[164:165], s[26:27], 0, v[134:135]
	v_readfirstlane_b32 s25, v161
	global_load_lds_dwordx4 v[164:165], off
	v_lshl_add_u64 v[164:165], s[26:27], 0, v[136:137]
	s_mov_b32 m0, s25
	s_nop 0
	global_load_lds_dwordx4 v[164:165], off
	s_waitcnt vmcnt(6)
	s_barrier
	s_nop 0
	v_mfma_f32_16x16x32_bf16 v[30:33], v[180:183], v[226:229], v[30:33]
	v_mfma_f32_16x16x32_bf16 v[26:29], v[180:183], v[234:237], v[26:29]
	v_mfma_f32_16x16x32_bf16 v[22:25], v[188:191], v[226:229], v[22:25]
	v_mfma_f32_16x16x32_bf16 v[18:21], v[188:191], v[234:237], v[18:21]
	v_mfma_f32_16x16x32_bf16 v[14:17], v[196:199], v[226:229], v[14:17]
	v_mfma_f32_16x16x32_bf16 v[10:13], v[196:199], v[234:237], v[10:13]
	v_mfma_f32_16x16x32_bf16 v[6:9], v[218:221], v[226:229], v[6:9]
	v_mfma_f32_16x16x32_bf16 v[2:5], v[218:221], v[234:237], v[2:5]
	v_mfma_f32_16x16x32_bf16 v[30:33], v[184:187], v[230:233], v[30:33]
	v_mfma_f32_16x16x32_bf16 v[26:29], v[184:187], v[238:241], v[26:29]
	v_mfma_f32_16x16x32_bf16 v[22:25], v[192:195], v[230:233], v[22:25]
	v_mfma_f32_16x16x32_bf16 v[18:21], v[192:195], v[238:241], v[18:21]
	v_mfma_f32_16x16x32_bf16 v[14:17], v[214:217], v[230:233], v[14:17]
	v_mfma_f32_16x16x32_bf16 v[10:13], v[214:217], v[238:241], v[10:13]
	v_mfma_f32_16x16x32_bf16 v[6:9], v[222:225], v[230:233], v[6:9]
	v_mfma_f32_16x16x32_bf16 v[2:5], v[222:225], v[238:241], v[2:5]
	s_nop 0
	s_add_i32 s24, s24, 2
	s_add_u32 s14, s14, 0x100
	s_addc_u32 s15, s15, 0
	s_cmp_lt_u32 s24, 12
	s_barrier
	s_cbranch_scc1 .LBB0_59
	s_add_u32 s6, s12, 0x780
	s_addc_u32 s7, s13, 0
	v_readfirstlane_b32 s1, v162
	s_nop 0
	ds_read_b128 v[134:137], v142
	ds_read_b128 v[148:151], v142 offset:1024
	ds_read_b128 v[156:159], v142 offset:2048
	ds_read_b128 v[164:167], v142 offset:3072
	ds_read_b128 v[168:171], v140
	ds_read_b128 v[172:175], v140 offset:1024
	ds_read_b128 v[176:179], v140 offset:2048
	ds_read_b128 v[180:183], v140 offset:3072
	ds_read_b128 v[184:187], v140 offset:4096
	ds_read_b128 v[188:191], v140 offset:5120
	ds_read_b128 v[192:195], v140 offset:6144
	ds_read_b128 v[196:199], v140 offset:7168
	s_mov_b32 m0, s1
	v_lshl_add_u64 v[132:133], v[132:133], 1, s[6:7]
	v_readfirstlane_b32 s1, v163
	global_load_lds_dwordx4 v[132:133], off
	v_lshl_add_u64 v[130:131], v[130:131], 1, s[6:7]
	s_mov_b32 m0, s1
	s_nop 0
	global_load_lds_dwordx4 v[130:131], off
	s_barrier
	s_waitcnt lgkmcnt(0)
	s_nop 0
	s_waitcnt lgkmcnt(0)
	v_mfma_f32_16x16x32_bf16 v[126:129], v[168:171], v[134:137], v[126:129]
	v_mfma_f32_16x16x32_bf16 v[122:125], v[168:171], v[156:159], v[122:125]
	v_mfma_f32_16x16x32_bf16 v[118:121], v[176:179], v[134:137], v[118:121]
	v_mfma_f32_16x16x32_bf16 v[114:117], v[176:179], v[156:159], v[114:117]
	v_mfma_f32_16x16x32_bf16 v[126:129], v[172:175], v[148:151], v[126:129]
	v_mfma_f32_16x16x32_bf16 v[122:125], v[172:175], v[164:167], v[122:125]
	v_mfma_f32_16x16x32_bf16 v[118:121], v[180:183], v[148:151], v[118:121]
	v_mfma_f32_16x16x32_bf16 v[114:117], v[180:183], v[164:167], v[114:117]
	v_mfma_f32_16x16x32_bf16 v[110:113], v[184:187], v[134:137], v[110:113]
	v_mfma_f32_16x16x32_bf16 v[106:109], v[184:187], v[156:159], v[106:109]
	v_mfma_f32_16x16x32_bf16 v[102:105], v[192:195], v[134:137], v[102:105]
	v_mfma_f32_16x16x32_bf16 v[98:101], v[192:195], v[156:159], v[98:101]
	v_mfma_f32_16x16x32_bf16 v[130:133], v[188:191], v[148:151], v[110:113]
	v_mfma_f32_16x16x32_bf16 v[160:163], v[188:191], v[164:167], v[106:109]
	v_mfma_f32_16x16x32_bf16 v[214:217], v[196:199], v[148:151], v[102:105]
	v_mfma_f32_16x16x32_bf16 v[218:221], v[196:199], v[164:167], v[98:101]
	s_nop 0
	s_barrier
	s_nop 0
	s_nop 0
	ds_read_b128 v[98:101], v142 offset:16384
	ds_read_b128 v[102:105], v142 offset:17408
	ds_read_b128 v[106:109], v142 offset:18432
	ds_read_b128 v[110:113], v142 offset:19456
	s_barrier
	s_waitcnt lgkmcnt(0)
	s_nop 0
	s_waitcnt lgkmcnt(3)
	v_mfma_f32_16x16x32_bf16 v[94:97], v[168:171], v[98:101], v[94:97]
	s_waitcnt lgkmcnt(1)
	v_mfma_f32_16x16x32_bf16 v[90:93], v[168:171], v[106:109], v[90:93]
	v_mfma_f32_16x16x32_bf16 v[86:89], v[176:179], v[98:101], v[86:89]
	v_mfma_f32_16x16x32_bf16 v[82:85], v[176:179], v[106:109], v[82:85]
	v_mfma_f32_16x16x32_bf16 v[94:97], v[172:175], v[102:105], v[94:97]
	s_waitcnt lgkmcnt(0)
	v_mfma_f32_16x16x32_bf16 v[90:93], v[172:175], v[110:113], v[90:93]
	v_mfma_f32_16x16x32_bf16 v[86:89], v[180:183], v[102:105], v[86:89]
	v_mfma_f32_16x16x32_bf16 v[82:85], v[180:183], v[110:113], v[82:85]
	v_mfma_f32_16x16x32_bf16 v[78:81], v[184:187], v[98:101], v[78:81]
	v_mfma_f32_16x16x32_bf16 v[74:77], v[184:187], v[106:109], v[74:77]
	v_mfma_f32_16x16x32_bf16 v[70:73], v[192:195], v[98:101], v[70:73]
	v_mfma_f32_16x16x32_bf16 v[66:69], v[192:195], v[106:109], v[66:69]
	v_mfma_f32_16x16x32_bf16 v[168:171], v[188:191], v[102:105], v[78:81]
	v_mfma_f32_16x16x32_bf16 v[172:175], v[188:191], v[110:113], v[74:77]
	v_mfma_f32_16x16x32_bf16 v[176:179], v[196:199], v[102:105], v[70:73]
	v_mfma_f32_16x16x32_bf16 v[180:183], v[196:199], v[110:113], v[66:69]
	s_nop 0
	s_barrier
	s_nop 1
	ds_read_b128 v[66:69], v140 offset:16384
	ds_read_b128 v[70:73], v140 offset:17408
	ds_read_b128 v[74:77], v140 offset:18432
	ds_read_b128 v[78:81], v140 offset:19456
	ds_read_b128 v[184:187], v140 offset:20480
	ds_read_b128 v[188:191], v140 offset:21504
	ds_read_b128 v[192:195], v140 offset:22528
	ds_read_b128 v[196:199], v140 offset:23552
	s_waitcnt vmcnt(4)
	s_barrier
; #define LDA(dst, b, h) _Pragma("unroll") for (int m = 0; m < 4; ++m) _Pragma("unroll") for (int k = 0; k < 2; ++k) \
;     dst[m][k] = *(const __attribute__((address_space(3))) bf16x8*)(aB + (((b) * 2 + (h)) * 16384 + m * 2048 + k * 1024))
; #define LDB(dst, b, h) _Pragma("unroll") for (int n = 0; n < 2; ++n) _Pragma("unroll") for (int k = 0; k < 2; ++k) \
;     dst[n][k] = *(const __attribute__((address_space(3))) bf16x8*)(bB + (((b) * 2 + (h)) * 16384 + n * 2048 + k * 1024))
; #define MMA(ai, bj, At, Bq) do { __builtin_amdgcn_s_setprio(1); \
;     _Pragma("unroll") for (int m = 0; m < 4; ++m) _Pragma("unroll") for (int n = 0; n < 2; ++n) _Pragma("unroll") for (int k = 0; k < 2; ++k) \
;       acc[ai][bj][m][n] = __builtin_amdgcn_mfma_f32_16x16x32_bf16(At[m][k], Bq[n][k], acc[ai][bj][m][n], 0, 0, 0); \
;     __builtin_amdgcn_s_setprio(0); } while (0)
; #define WAIT_V(n) asm volatile("s_waitcnt vmcnt(" #n ")" ::: "memory")
; #define WAIT_L(n) asm volatile("s_waitcnt lgkmcnt(" #n ")" ::: "memory")
; #define BAR __builtin_amdgcn_s_barrier()
; template <int MODE>
; DI void gemm_tile(const Params& p, const bf16_t* __restrict__ A, const bf16_t* __restrict__ Bt, int K, int brow, int bcol, int mp, int nt, bool vt, char* smem) {
;     ...
;     LDA(At, 0, 1); WAIT_V(4); BAR; WAIT_L(0); MMA(1, 0, At, B0); MMA(1, 1, At, B1); BAR; }
;   { LDB(B0, 1, 0); LDA(At, 1, 0); WAIT_V(2); BAR; WAIT_L(0); MMA(0, 0, At, B0); BAR;
	s_waitcnt lgkmcnt(0)
	s_nop 0
	s_waitcnt lgkmcnt(7)
	v_mfma_f32_16x16x32_bf16 v[62:65], v[66:69], v[134:137], v[62:65]
	v_mfma_f32_16x16x32_bf16 v[58:61], v[66:69], v[156:159], v[58:61]
	s_waitcnt lgkmcnt(5)
	v_mfma_f32_16x16x32_bf16 v[54:57], v[74:77], v[134:137], v[54:57]
	v_mfma_f32_16x16x32_bf16 v[50:53], v[74:77], v[156:159], v[50:53]
	v_mfma_f32_16x16x32_bf16 v[62:65], v[70:73], v[148:151], v[62:65]
	v_mfma_f32_16x16x32_bf16 v[58:61], v[70:73], v[164:167], v[58:61]
	s_waitcnt lgkmcnt(4)
	v_mfma_f32_16x16x32_bf16 v[54:57], v[78:81], v[148:151], v[54:57]
	v_mfma_f32_16x16x32_bf16 v[50:53], v[78:81], v[164:167], v[50:53]
	s_waitcnt lgkmcnt(3)
	v_mfma_f32_16x16x32_bf16 v[46:49], v[184:187], v[134:137], v[46:49]
	v_mfma_f32_16x16x32_bf16 v[42:45], v[184:187], v[156:159], v[42:45]
	s_waitcnt lgkmcnt(1)
	v_mfma_f32_16x16x32_bf16 v[38:41], v[192:195], v[134:137], v[38:41]
	v_mfma_f32_16x16x32_bf16 v[34:37], v[192:195], v[156:159], v[34:37]
	v_mfma_f32_16x16x32_bf16 v[222:225], v[188:191], v[148:151], v[46:49]
	v_mfma_f32_16x16x32_bf16 v[226:229], v[188:191], v[164:167], v[42:45]
	s_waitcnt lgkmcnt(0)
	v_mfma_f32_16x16x32_bf16 v[134:137], v[196:199], v[148:151], v[38:41]
	v_mfma_f32_16x16x32_bf16 v[148:151], v[196:199], v[164:167], v[34:37]
	s_nop 0
	s_nop 0
	v_mfma_f32_16x16x32_bf16 v[30:33], v[66:69], v[98:101], v[30:33]
	v_mfma_f32_16x16x32_bf16 v[26:29], v[66:69], v[106:109], v[26:29]
	v_mfma_f32_16x16x32_bf16 v[22:25], v[74:77], v[98:101], v[22:25]
	v_mfma_f32_16x16x32_bf16 v[18:21], v[74:77], v[106:109], v[18:21]
	v_mfma_f32_16x16x32_bf16 v[30:33], v[70:73], v[102:105], v[30:33]
	v_mfma_f32_16x16x32_bf16 v[26:29], v[70:73], v[110:113], v[26:29]
	v_mfma_f32_16x16x32_bf16 v[22:25], v[78:81], v[102:105], v[22:25]
	v_mfma_f32_16x16x32_bf16 v[18:21], v[78:81], v[110:113], v[18:21]
	v_mfma_f32_16x16x32_bf16 v[14:17], v[184:187], v[98:101], v[14:17]
	v_mfma_f32_16x16x32_bf16 v[10:13], v[184:187], v[106:109], v[10:13]
	v_mfma_f32_16x16x32_bf16 v[6:9], v[192:195], v[98:101], v[6:9]
	v_mfma_f32_16x16x32_bf16 v[2:5], v[192:195], v[106:109], v[2:5]
	v_mfma_f32_16x16x32_bf16 v[156:159], v[188:191], v[102:105], v[14:17]
	v_mfma_f32_16x16x32_bf16 v[164:167], v[188:191], v[110:113], v[10:13]
	v_mfma_f32_16x16x32_bf16 v[184:187], v[196:199], v[102:105], v[6:9]
	v_mfma_f32_16x16x32_bf16 v[188:191], v[196:199], v[110:113], v[2:5]
	s_nop 0
	s_barrier
	s_nop 1
	ds_read_b128 v[2:5], v142 offset:32768
	ds_read_b128 v[6:9], v142 offset:33792
	ds_read_b128 v[10:13], v142 offset:34816
	ds_read_b128 v[14:17], v142 offset:35840
	ds_read_b128 v[34:37], v140 offset:32768
	ds_read_b128 v[38:41], v140 offset:33792
	ds_read_b128 v[42:45], v140 offset:34816
	ds_read_b128 v[46:49], v140 offset:35840
	ds_read_b128 v[192:195], v140 offset:36864
	ds_read_b128 v[196:199], v140 offset:37888
	ds_read_b128 v[230:233], v140 offset:38912
	ds_read_b128 v[234:237], v140 offset:39936
	s_waitcnt vmcnt(2)
	s_barrier
	s_waitcnt lgkmcnt(0)
	s_nop 0
	s_waitcnt lgkmcnt(7)
	v_mfma_f32_16x16x32_bf16 v[66:69], v[34:37], v[2:5], v[126:129]
	s_waitcnt lgkmcnt(6)
	v_mfma_f32_16x16x32_bf16 v[98:101], v[38:41], v[6:9], v[66:69]
	v_mfma_f32_16x16x32_bf16 v[66:69], v[34:37], v[10:13], v[122:125]
	v_mfma_f32_16x16x32_bf16 v[102:105], v[38:41], v[14:17], v[66:69]
	s_waitcnt lgkmcnt(5)
	v_mfma_f32_16x16x32_bf16 v[66:69], v[42:45], v[2:5], v[118:121]
	s_waitcnt lgkmcnt(4)
	v_mfma_f32_16x16x32_bf16 v[106:109], v[46:49], v[6:9], v[66:69]
	v_mfma_f32_16x16x32_bf16 v[66:69], v[42:45], v[10:13], v[114:117]
	v_mfma_f32_16x16x32_bf16 v[110:113], v[46:49], v[14:17], v[66:69]
	s_waitcnt lgkmcnt(3)
	v_mfma_f32_16x16x32_bf16 v[66:69], v[192:195], v[2:5], v[130:133]
	s_waitcnt lgkmcnt(2)
	v_mfma_f32_16x16x32_bf16 v[114:117], v[196:199], v[6:9], v[66:69]
	v_mfma_f32_16x16x32_bf16 v[66:69], v[192:195], v[10:13], v[160:163]
	v_mfma_f32_16x16x32_bf16 v[118:121], v[196:199], v[14:17], v[66:69]
	s_waitcnt lgkmcnt(1)
	v_mfma_f32_16x16x32_bf16 v[66:69], v[230:233], v[2:5], v[214:217]
	s_waitcnt lgkmcnt(0)
	v_mfma_f32_16x16x32_bf16 v[122:125], v[234:237], v[6:9], v[66:69]
	v_mfma_f32_16x16x32_bf16 v[66:69], v[230:233], v[10:13], v[218:221]
	v_mfma_f32_16x16x32_bf16 v[126:129], v[234:237], v[14:17], v[66:69]
	s_nop 0
	s_barrier
; #define LDA(dst, b, h) _Pragma("unroll") for (int m = 0; m < 4; ++m) _Pragma("unroll") for (int k = 0; k < 2; ++k) \
;     dst[m][k] = *(const __attribute__((address_space(3))) bf16x8*)(aB + (((b) * 2 + (h)) * 16384 + m * 2048 + k * 1024))
; #define LDB(dst, b, h) _Pragma("unroll") for (int n = 0; n < 2; ++n) _Pragma("unroll") for (int k = 0; k < 2; ++k) \
;     dst[n][k] = *(const __attribute__((address_space(3))) bf16x8*)(bB + (((b) * 2 + (h)) * 16384 + n * 2048 + k * 1024))
; #define MMA(ai, bj, At, Bq) do { __builtin_amdgcn_s_setprio(1); \
;     _Pragma("unroll") for (int m = 0; m < 4; ++m) _Pragma("unroll") for (int n = 0; n < 2; ++n) _Pragma("unroll") for (int k = 0; k < 2; ++k) \
;       acc[ai][bj][m][n] = __builtin_amdgcn_mfma_f32_16x16x32_bf16(At[m][k], Bq[n][k], acc[ai][bj][m][n], 0, 0, 0); \
;     __builtin_amdgcn_s_setprio(0); } while (0)
; #define WAIT_V(n) asm volatile("s_waitcnt vmcnt(" #n ")" ::: "memory")
; #define WAIT_L(n) asm volatile("s_waitcnt lgkmcnt(" #n ")" ::: "memory")
; #define BAR __builtin_amdgcn_s_barrier()
; template <int MODE>
; DI void gemm_tile(const Params& p, const bf16_t* __restrict__ A, const bf16_t* __restrict__ Bt, int K, int brow, int bcol, int mp, int nt, bool vt, char* smem) {
;     ...
;   { LDB(B0, 1, 0); LDA(At, 1, 0); WAIT_V(2); BAR; WAIT_L(0); MMA(0, 0, At, B0); BAR;
;     LDB(B1, 1, 1); WAIT_V(0); BAR; WAIT_L(0); MMA(0, 1, At, B1); BAR;
;     LDA(At, 1, 1); BAR; WAIT_L(0); MMA(1, 0, At, B0); MMA(1, 1, At, B1); BAR; }
;   if (wr == 0) BAR;
	ds_read_b128 v[130:133], v142 offset:49152
	ds_read_b128 v[160:163], v142 offset:50176
	ds_read_b128 v[214:217], v142 offset:51200
	ds_read_b128 v[218:221], v142 offset:52224
	s_waitcnt vmcnt(0)
	s_barrier
	s_waitcnt lgkmcnt(0)
	s_nop 0
	s_waitcnt lgkmcnt(3)
	v_mfma_f32_16x16x32_bf16 v[66:69], v[34:37], v[130:133], v[94:97]
	s_waitcnt lgkmcnt(1)
	v_mfma_f32_16x16x32_bf16 v[34:37], v[34:37], v[214:217], v[90:93]
	s_waitcnt lgkmcnt(0)
	v_mfma_f32_16x16x32_bf16 v[70:73], v[38:41], v[218:221], v[34:37]
	v_mfma_f32_16x16x32_bf16 v[34:37], v[42:45], v[130:133], v[86:89]
	v_mfma_f32_16x16x32_bf16 v[74:77], v[46:49], v[160:163], v[34:37]
	v_mfma_f32_16x16x32_bf16 v[34:37], v[42:45], v[214:217], v[82:85]
	v_mfma_f32_16x16x32_bf16 v[78:81], v[46:49], v[218:221], v[34:37]
	v_mfma_f32_16x16x32_bf16 v[34:37], v[192:195], v[130:133], v[168:171]
	v_mfma_f32_16x16x32_bf16 v[82:85], v[196:199], v[160:163], v[34:37]
	v_mfma_f32_16x16x32_bf16 v[34:37], v[192:195], v[214:217], v[172:175]
	v_mfma_f32_16x16x32_bf16 v[86:89], v[196:199], v[218:221], v[34:37]
	v_mfma_f32_16x16x32_bf16 v[34:37], v[230:233], v[130:133], v[176:179]
	v_mfma_f32_16x16x32_bf16 v[90:93], v[234:237], v[160:163], v[34:37]
	v_mfma_f32_16x16x32_bf16 v[34:37], v[230:233], v[214:217], v[180:183]
	v_mfma_f32_16x16x32_bf16 v[66:69], v[38:41], v[160:163], v[66:69]
	v_mfma_f32_16x16x32_bf16 v[94:97], v[234:237], v[218:221], v[34:37]
	s_nop 0
	s_barrier
	ds_read_b128 v[168:171], v140 offset:49152
	ds_read_b128 v[172:175], v140 offset:50176
	ds_read_b128 v[176:179], v140 offset:51200
	ds_read_b128 v[180:183], v140 offset:52224
	ds_read_b128 v[192:195], v140 offset:53248
	ds_read_b128 v[196:199], v140 offset:54272
	ds_read_b128 v[230:233], v140 offset:55296
	ds_read_b128 v[138:141], v140 offset:56320
	s_barrier
	s_waitcnt lgkmcnt(0)
	s_nop 0
	s_waitcnt lgkmcnt(7)
	v_mfma_f32_16x16x32_bf16 v[34:37], v[168:171], v[2:5], v[62:65]
	s_waitcnt lgkmcnt(5)
	v_mfma_f32_16x16x32_bf16 v[42:45], v[176:179], v[2:5], v[54:57]
	v_mfma_f32_16x16x32_bf16 v[46:49], v[176:179], v[10:13], v[50:53]
	s_waitcnt lgkmcnt(3)
	v_mfma_f32_16x16x32_bf16 v[50:53], v[192:195], v[2:5], v[222:225]
	s_waitcnt lgkmcnt(1)
	v_mfma_f32_16x16x32_bf16 v[2:5], v[230:233], v[2:5], v[134:137]
	v_mfma_f32_16x16x32_bf16 v[38:41], v[168:171], v[10:13], v[58:61]
	v_mfma_f32_16x16x32_bf16 v[54:57], v[192:195], v[10:13], v[226:229]
	s_waitcnt lgkmcnt(0)
	v_mfma_f32_16x16x32_bf16 v[58:61], v[138:141], v[6:9], v[2:5]
	v_mfma_f32_16x16x32_bf16 v[2:5], v[230:233], v[10:13], v[148:151]
	v_mfma_f32_16x16x32_bf16 v[34:37], v[172:175], v[6:9], v[34:37]
	v_mfma_f32_16x16x32_bf16 v[38:41], v[172:175], v[14:17], v[38:41]
	v_mfma_f32_16x16x32_bf16 v[42:45], v[180:183], v[6:9], v[42:45]
	v_mfma_f32_16x16x32_bf16 v[46:49], v[180:183], v[14:17], v[46:49]
	v_mfma_f32_16x16x32_bf16 v[50:53], v[196:199], v[6:9], v[50:53]
	v_mfma_f32_16x16x32_bf16 v[54:57], v[196:199], v[14:17], v[54:57]
	v_mfma_f32_16x16x32_bf16 v[62:65], v[138:141], v[14:17], v[2:5]
	s_nop 0
	s_nop 0
	v_mfma_f32_16x16x32_bf16 v[2:5], v[168:171], v[130:133], v[30:33]
	v_mfma_f32_16x16x32_bf16 v[6:9], v[168:171], v[214:217], v[26:29]
	v_mfma_f32_16x16x32_bf16 v[10:13], v[176:179], v[130:133], v[22:25]
	v_mfma_f32_16x16x32_bf16 v[14:17], v[176:179], v[214:217], v[18:21]
	v_mfma_f32_16x16x32_bf16 v[18:21], v[192:195], v[130:133], v[156:159]
	v_mfma_f32_16x16x32_bf16 v[22:25], v[192:195], v[214:217], v[164:167]
	v_mfma_f32_16x16x32_bf16 v[26:29], v[230:233], v[130:133], v[184:187]
	v_mfma_f32_16x16x32_bf16 v[30:33], v[230:233], v[214:217], v[188:191]
	v_mfma_f32_16x16x32_bf16 v[2:5], v[172:175], v[160:163], v[2:5]
	v_mfma_f32_16x16x32_bf16 v[6:9], v[172:175], v[218:221], v[6:9]
	v_mfma_f32_16x16x32_bf16 v[10:13], v[180:183], v[160:163], v[10:13]
	v_mfma_f32_16x16x32_bf16 v[14:17], v[180:183], v[218:221], v[14:17]
	v_mfma_f32_16x16x32_bf16 v[18:21], v[196:199], v[160:163], v[18:21]
	v_mfma_f32_16x16x32_bf16 v[22:25], v[196:199], v[218:221], v[22:25]
	v_mfma_f32_16x16x32_bf16 v[26:29], v[138:141], v[160:163], v[26:29]
	v_mfma_f32_16x16x32_bf16 v[30:33], v[138:141], v[218:221], v[30:33]
	s_nop 0
	s_movk_i32 s1, 0x100
	v_cmp_gt_u32_e32 vcc, s1, v144
	s_barrier
	s_and_saveexec_b64 s[6:7], vcc
	s_cbranch_execz .LBB0_62
	s_barrier

; #define STAGE(P, BASE, br, kt) do { const bf16_t* _gb = (BASE) + (long)(br) * K + (long)(kt) * 64; asm volatile("" : "+s"(_gb)); \
;     __builtin_amdgcn_global_load_lds((const unsigned*)(_gb + go0), (lds_u32*)((char*)(P) + tid * 16), 16, 0, 0); \
;     __builtin_amdgcn_global_load_lds((const unsigned*)(_gb + go1), (lds_u32*)((char*)(P) + tid * 16 + 8192), 16, 0, 0); } while (0)
; #define LDA(dst, b, h) _Pragma("unroll") for (int m = 0; m < 4; ++m) _Pragma("unroll") for (int k = 0; k < 2; ++k) \
;     dst[m][k] = *(const __attribute__((address_space(3))) bf16x8*)(aB + (((b) * 2 + (h)) * 16384 + m * 2048 + k * 1024))
; #define LDB(dst, b, h) _Pragma("unroll") for (int n = 0; n < 2; ++n) _Pragma("unroll") for (int k = 0; k < 2; ++k) \
;     dst[n][k] = *(const __attribute__((address_space(3))) bf16x8*)(bB + (((b) * 2 + (h)) * 16384 + n * 2048 + k * 1024))
; #define MMA(ai, bj, At, Bq) do { __builtin_amdgcn_s_setprio(1); \
;     _Pragma("unroll") for (int m = 0; m < 4; ++m) _Pragma("unroll") for (int n = 0; n < 2; ++n) _Pragma("unroll") for (int k = 0; k < 2; ++k) \
;       acc[ai][bj][m][n] = __builtin_amdgcn_mfma_f32_16x16x32_bf16(At[m][k], Bq[n][k], acc[ai][bj][m][n], 0, 0, 0); \
;     __builtin_amdgcn_s_setprio(0); } while (0)
; #define WAIT_L(n) asm volatile("s_waitcnt lgkmcnt(" #n ")" ::: "memory")
; #define BAR __builtin_amdgcn_s_barrier()
; #define SCHED __builtin_amdgcn_sched_barrier(0)
; template <int MODE>
; DI void gemm_tile(const Params& p, const bf16_t* __restrict__ A, const bf16_t* __restrict__ Bt, int K, int brow, int bcol, int mp, int nt, bool vt, char* smem) {
;     ...
;     LDB(B0, 1, 0); SCHED; LDA(At, 1, 0); STAGE(SA(0, 1), A, brow + 128, t + 2);
;     WAIT_L(8); BAR; WAIT_L(0); MMA(0, 0, At, B0); BAR; SCHED;
;     LDB(B1, 1, 1); STAGE(SB(1, 0), Bt, bcol, t + 3);
;     BAR; WAIT_L(0); MMA(0, 1, At, B1); BAR;
;     LDA(At, 1, 1); STAGE(SA(1, 0), A, brow, t + 3);
;     BAR; WAIT_L(0); MMA(1, 0, At, B0); BAR; SCHED;
.Lgemm2_p5:
	s_nop 0
	ds_read_b128 v[164:167], v142 offset:32768
	ds_read_b128 v[168:171], v142 offset:33792
	ds_read_b128 v[172:175], v142 offset:34816
	ds_read_b128 v[176:179], v142 offset:35840
	s_add_u32 s26, s1, s14
	s_addc_u32 s27, s5, s15
	v_readfirstlane_b32 s35, v150
	ds_read_b128 v[180:183], v140 offset:32768
	ds_read_b128 v[184:187], v140 offset:33792
	ds_read_b128 v[188:191], v140 offset:34816
	ds_read_b128 v[192:195], v140 offset:35840
	ds_read_b128 v[196:199], v140 offset:36864
	ds_read_b128 v[214:217], v140 offset:37888
	ds_read_b128 v[218:221], v140 offset:38912
	ds_read_b128 v[222:225], v140 offset:39936
	s_mov_b32 m0, s35
	v_lshl_add_u64 v[226:227], s[26:27], 0, v[134:135]
	global_load_lds_dwordx4 v[226:227], off
	v_lshl_add_u64 v[226:227], s[26:27], 0, v[136:137]
	v_readfirstlane_b32 s26, v151
	s_mov_b32 m0, s26
	s_nop 0
	global_load_lds_dwordx4 v[226:227], off
	s_waitcnt lgkmcnt(8)
	s_barrier
	s_waitcnt lgkmcnt(0)
	s_nop 0
	s_waitcnt lgkmcnt(0)
	v_mfma_f32_16x16x32_bf16 v[126:129], v[180:183], v[164:167], v[126:129]
	v_mfma_f32_16x16x32_bf16 v[122:125], v[180:183], v[172:175], v[122:125]
	v_mfma_f32_16x16x32_bf16 v[118:121], v[188:191], v[164:167], v[118:121]
	v_mfma_f32_16x16x32_bf16 v[114:117], v[188:191], v[172:175], v[114:117]
	v_mfma_f32_16x16x32_bf16 v[110:113], v[196:199], v[164:167], v[110:113]
	v_mfma_f32_16x16x32_bf16 v[106:109], v[196:199], v[172:175], v[106:109]
	v_mfma_f32_16x16x32_bf16 v[102:105], v[218:221], v[164:167], v[102:105]
	v_mfma_f32_16x16x32_bf16 v[98:101], v[218:221], v[172:175], v[98:101]
	v_mfma_f32_16x16x32_bf16 v[126:129], v[184:187], v[168:171], v[126:129]
	v_mfma_f32_16x16x32_bf16 v[122:125], v[184:187], v[176:179], v[122:125]
	v_mfma_f32_16x16x32_bf16 v[118:121], v[192:195], v[168:171], v[118:121]
	v_mfma_f32_16x16x32_bf16 v[114:117], v[192:195], v[176:179], v[114:117]
	v_mfma_f32_16x16x32_bf16 v[110:113], v[214:217], v[168:171], v[110:113]
	v_mfma_f32_16x16x32_bf16 v[106:109], v[214:217], v[176:179], v[106:109]
	v_mfma_f32_16x16x32_bf16 v[102:105], v[222:225], v[168:171], v[102:105]
	v_mfma_f32_16x16x32_bf16 v[98:101], v[222:225], v[176:179], v[98:101]
	s_nop 0
	s_barrier
	s_add_u32 s26, s25, 0x180
	s_addc_u32 s27, s28, 0
	v_readfirstlane_b32 s25, v156
	s_nop 0
	ds_read_b128 v[226:229], v142 offset:49152
	ds_read_b128 v[230:233], v142 offset:50176
	ds_read_b128 v[234:237], v142 offset:51200
	ds_read_b128 v[238:241], v142 offset:52224
	s_mov_b32 m0, s25
	v_lshl_add_u64 v[242:243], s[26:27], 0, v[134:135]
	v_readfirstlane_b32 s25, v157
	global_load_lds_dwordx4 v[242:243], off
	v_lshl_add_u64 v[242:243], s[26:27], 0, v[136:137]
	s_mov_b32 m0, s25
	s_nop 0
	global_load_lds_dwordx4 v[242:243], off
	s_barrier
	s_waitcnt lgkmcnt(0)
	s_nop 0
	s_waitcnt lgkmcnt(0)
	v_mfma_f32_16x16x32_bf16 v[94:97], v[180:183], v[226:229], v[94:97]
	v_mfma_f32_16x16x32_bf16 v[90:93], v[180:183], v[234:237], v[90:93]
	v_mfma_f32_16x16x32_bf16 v[86:89], v[188:191], v[226:229], v[86:89]
	v_mfma_f32_16x16x32_bf16 v[82:85], v[188:191], v[234:237], v[82:85]
	v_mfma_f32_16x16x32_bf16 v[78:81], v[196:199], v[226:229], v[78:81]
	v_mfma_f32_16x16x32_bf16 v[74:77], v[196:199], v[234:237], v[74:77]
	v_mfma_f32_16x16x32_bf16 v[70:73], v[218:221], v[226:229], v[70:73]
	v_mfma_f32_16x16x32_bf16 v[66:69], v[218:221], v[234:237], v[66:69]
	v_mfma_f32_16x16x32_bf16 v[94:97], v[184:187], v[230:233], v[94:97]
	v_mfma_f32_16x16x32_bf16 v[90:93], v[184:187], v[238:241], v[90:93]
	v_mfma_f32_16x16x32_bf16 v[86:89], v[192:195], v[230:233], v[86:89]
	v_mfma_f32_16x16x32_bf16 v[82:85], v[192:195], v[238:241], v[82:85]
	v_mfma_f32_16x16x32_bf16 v[78:81], v[214:217], v[230:233], v[78:81]
	v_mfma_f32_16x16x32_bf16 v[74:77], v[214:217], v[238:241], v[74:77]
	v_mfma_f32_16x16x32_bf16 v[70:73], v[222:225], v[230:233], v[70:73]
	v_mfma_f32_16x16x32_bf16 v[66:69], v[222:225], v[238:241], v[66:69]
	s_nop 0
	s_add_u32 s26, s29, 0x180
	s_addc_u32 s27, s30, 0
	v_readfirstlane_b32 s25, v158
	s_barrier
	s_nop 0
	ds_read_b128 v[180:183], v140 offset:49152
	ds_read_b128 v[184:187], v140 offset:50176
	ds_read_b128 v[188:191], v140 offset:51200
	ds_read_b128 v[192:195], v140 offset:52224
	ds_read_b128 v[196:199], v140 offset:53248
	ds_read_b128 v[214:217], v140 offset:54272
	ds_read_b128 v[218:221], v140 offset:55296
	ds_read_b128 v[222:225], v140 offset:56320
	s_mov_b32 m0, s25
	v_lshl_add_u64 v[242:243], s[26:27], 0, v[134:135]
	v_readfirstlane_b32 s25, v159
	global_load_lds_dwordx4 v[242:243], off
	v_lshl_add_u64 v[242:243], s[26:27], 0, v[136:137]
	s_mov_b32 m0, s25
	s_nop 0
	global_load_lds_dwordx4 v[242:243], off
	s_barrier
	s_waitcnt lgkmcnt(0)
	s_nop 0
	s_waitcnt lgkmcnt(0)
	v_mfma_f32_16x16x32_bf16 v[62:65], v[180:183], v[164:167], v[62:65]
	v_mfma_f32_16x16x32_bf16 v[58:61], v[180:183], v[172:175], v[58:61]
	v_mfma_f32_16x16x32_bf16 v[54:57], v[188:191], v[164:167], v[54:57]
	v_mfma_f32_16x16x32_bf16 v[50:53], v[188:191], v[172:175], v[50:53]
	v_mfma_f32_16x16x32_bf16 v[46:49], v[196:199], v[164:167], v[46:49]
	v_mfma_f32_16x16x32_bf16 v[42:45], v[196:199], v[172:175], v[42:45]
	v_mfma_f32_16x16x32_bf16 v[38:41], v[218:221], v[164:167], v[38:41]
	v_mfma_f32_16x16x32_bf16 v[34:37], v[218:221], v[172:175], v[34:37]
	v_mfma_f32_16x16x32_bf16 v[62:65], v[184:187], v[168:171], v[62:65]
	v_mfma_f32_16x16x32_bf16 v[58:61], v[184:187], v[176:179], v[58:61]
	v_mfma_f32_16x16x32_bf16 v[54:57], v[192:195], v[168:171], v[54:57]
	v_mfma_f32_16x16x32_bf16 v[50:53], v[192:195], v[176:179], v[50:53]
	v_mfma_f32_16x16x32_bf16 v[46:49], v[214:217], v[168:171], v[46:49]
	v_mfma_f32_16x16x32_bf16 v[42:45], v[214:217], v[176:179], v[42:45]
	v_mfma_f32_16x16x32_bf16 v[38:41], v[222:225], v[168:171], v[38:41]
	v_mfma_f32_16x16x32_bf16 v[34:37], v[222:225], v[176:179], v[34:37]
	s_nop 0
	s_barrier
; #define STAGE(P, BASE, br, kt) do { const bf16_t* _gb = (BASE) + (long)(br) * K + (long)(kt) * 64; asm volatile("" : "+s"(_gb)); \
;     __builtin_amdgcn_global_load_lds((const unsigned*)(_gb + go0), (lds_u32*)((char*)(P) + tid * 16), 16, 0, 0); \
;     __builtin_amdgcn_global_load_lds((const unsigned*)(_gb + go1), (lds_u32*)((char*)(P) + tid * 16 + 8192), 16, 0, 0); } while (0)
; #define LDA(dst, b, h) _Pragma("unroll") for (int m = 0; m < 4; ++m) _Pragma("unroll") for (int k = 0; k < 2; ++k) \
;     dst[m][k] = *(const __attribute__((address_space(3))) bf16x8*)(aB + (((b) * 2 + (h)) * 16384 + m * 2048 + k * 1024))
; #define LDB(dst, b, h) _Pragma("unroll") for (int n = 0; n < 2; ++n) _Pragma("unroll") for (int k = 0; k < 2; ++k) \
;     dst[n][k] = *(const __attribute__((address_space(3))) bf16x8*)(bB + (((b) * 2 + (h)) * 16384 + n * 2048 + k * 1024))
; #define MMA(ai, bj, At, Bq) do { __builtin_amdgcn_s_setprio(1); \
;     _Pragma("unroll") for (int m = 0; m < 4; ++m) _Pragma("unroll") for (int n = 0; n < 2; ++n) _Pragma("unroll") for (int k = 0; k < 2; ++k) \
;       acc[ai][bj][m][n] = __builtin_amdgcn_mfma_f32_16x16x32_bf16(At[m][k], Bq[n][k], acc[ai][bj][m][n], 0, 0, 0); \
;     __builtin_amdgcn_s_setprio(0); } while (0)
; #define WAIT_V(n) asm volatile("s_waitcnt vmcnt(" #n ")" ::: "memory")
; #define WAIT_L(n) asm volatile("s_waitcnt lgkmcnt(" #n ")" ::: "memory")
; #define BAR __builtin_amdgcn_s_barrier()
; template <int MODE>
; DI void gemm_tile(const Params& p, const bf16_t* __restrict__ A, const bf16_t* __restrict__ Bt, int K, int brow, int bcol, int mp, int nt, bool vt, char* smem) {
;     ...
;     STAGE(SB(1, 1), Bt, bcol + 128, t + 3);
;     WAIT_V(6); BAR; MMA(1, 1, At, B1); BAR;
;   }
;   { LDB(B0, 0, 0); LDA(At, 0, 0); STAGE(SA(1, 1), A, brow + 128, ntk - 1);
;     BAR; WAIT_L(0); MMA(0, 0, At, B0); BAR;
;     LDB(B1, 0, 1); BAR; WAIT_L(0); MMA(0, 1, At, B1); BAR;
;     LDA(At, 0, 1); WAIT_V(4); BAR; WAIT_L(0); MMA(1, 0, At, B0); MMA(1, 1, At, B1); BAR; }
	s_add_u32 s26, s31, 0x180
	s_addc_u32 s27, s34, 0
	v_readfirstlane_b32 s25, v160
	s_mov_b32 m0, s25
	v_lshl_add_u64 v[164:165], s[26:27], 0, v[134:135]
	v_readfirstlane_b32 s25, v161
	global_load_lds_dwordx4 v[164:165], off
	v_lshl_add_u64 v[164:165], s[26:27], 0, v[136:137]
	s_mov_b32 m0, s25
	s_nop 0
	global_load_lds_dwordx4 v[164:165], off
	s_waitcnt vmcnt(6)
	s_barrier
	s_nop 0
	v_mfma_f32_16x16x32_bf16 v[30:33], v[180:183], v[226:229], v[30:33]
	v_mfma_f32_16x16x32_bf16 v[26:29], v[180:183], v[234:237], v[26:29]
	v_mfma_f32_16x16x32_bf16 v[22:25], v[188:191], v[226:229], v[22:25]
	v_mfma_f32_16x16x32_bf16 v[18:21], v[188:191], v[234:237], v[18:21]
	v_mfma_f32_16x16x32_bf16 v[14:17], v[196:199], v[226:229], v[14:17]
	v_mfma_f32_16x16x32_bf16 v[10:13], v[196:199], v[234:237], v[10:13]
	v_mfma_f32_16x16x32_bf16 v[6:9], v[218:221], v[226:229], v[6:9]
	v_mfma_f32_16x16x32_bf16 v[2:5], v[218:221], v[234:237], v[2:5]
	v_mfma_f32_16x16x32_bf16 v[30:33], v[184:187], v[230:233], v[30:33]
	v_mfma_f32_16x16x32_bf16 v[26:29], v[184:187], v[238:241], v[26:29]
	v_mfma_f32_16x16x32_bf16 v[22:25], v[192:195], v[230:233], v[22:25]
	v_mfma_f32_16x16x32_bf16 v[18:21], v[192:195], v[238:241], v[18:21]
	v_mfma_f32_16x16x32_bf16 v[14:17], v[214:217], v[230:233], v[14:17]
	v_mfma_f32_16x16x32_bf16 v[10:13], v[214:217], v[238:241], v[10:13]
	v_mfma_f32_16x16x32_bf16 v[6:9], v[222:225], v[230:233], v[6:9]
	v_mfma_f32_16x16x32_bf16 v[2:5], v[222:225], v[238:241], v[2:5]
	s_nop 0
	s_add_i32 s24, s24, 2
	s_add_u32 s14, s14, 0x100
	s_addc_u32 s15, s15, 0
	s_cmp_lt_u32 s24, 60
	s_barrier
	s_cbranch_scc1 .LBB0_526
	s_add_u32 s6, s12, 0x1f80
	s_addc_u32 s7, s13, 0
	v_readfirstlane_b32 s1, v162
	s_nop 0
	ds_read_b128 v[134:137], v142
	ds_read_b128 v[148:151], v142 offset:1024
	ds_read_b128 v[156:159], v142 offset:2048
	ds_read_b128 v[164:167], v142 offset:3072
	ds_read_b128 v[168:171], v140
	ds_read_b128 v[172:175], v140 offset:1024
	ds_read_b128 v[176:179], v140 offset:2048
	ds_read_b128 v[180:183], v140 offset:3072
	ds_read_b128 v[184:187], v140 offset:4096
	ds_read_b128 v[188:191], v140 offset:5120
	ds_read_b128 v[192:195], v140 offset:6144
	ds_read_b128 v[196:199], v140 offset:7168
	s_mov_b32 m0, s1
	v_lshl_add_u64 v[132:133], v[132:133], 1, s[6:7]
	v_readfirstlane_b32 s1, v163
	global_load_lds_dwordx4 v[132:133], off
	v_lshl_add_u64 v[130:131], v[130:131], 1, s[6:7]
	s_mov_b32 m0, s1
	s_nop 0
	global_load_lds_dwordx4 v[130:131], off
	s_barrier
	s_waitcnt lgkmcnt(0)
	s_nop 0
	s_waitcnt lgkmcnt(0)
	v_mfma_f32_16x16x32_bf16 v[126:129], v[168:171], v[134:137], v[126:129]
	v_mfma_f32_16x16x32_bf16 v[122:125], v[168:171], v[156:159], v[122:125]
	v_mfma_f32_16x16x32_bf16 v[118:121], v[176:179], v[134:137], v[118:121]
	v_mfma_f32_16x16x32_bf16 v[114:117], v[176:179], v[156:159], v[114:117]
	v_mfma_f32_16x16x32_bf16 v[126:129], v[172:175], v[148:151], v[126:129]
	v_mfma_f32_16x16x32_bf16 v[122:125], v[172:175], v[164:167], v[122:125]
	v_mfma_f32_16x16x32_bf16 v[118:121], v[180:183], v[148:151], v[118:121]
	v_mfma_f32_16x16x32_bf16 v[114:117], v[180:183], v[164:167], v[114:117]
	v_mfma_f32_16x16x32_bf16 v[110:113], v[184:187], v[134:137], v[110:113]
	v_mfma_f32_16x16x32_bf16 v[106:109], v[184:187], v[156:159], v[106:109]
	v_mfma_f32_16x16x32_bf16 v[102:105], v[192:195], v[134:137], v[102:105]
	v_mfma_f32_16x16x32_bf16 v[98:101], v[192:195], v[156:159], v[98:101]
	v_mfma_f32_16x16x32_bf16 v[130:133], v[188:191], v[148:151], v[110:113]
	v_mfma_f32_16x16x32_bf16 v[160:163], v[188:191], v[164:167], v[106:109]
	v_mfma_f32_16x16x32_bf16 v[214:217], v[196:199], v[148:151], v[102:105]
	v_mfma_f32_16x16x32_bf16 v[218:221], v[196:199], v[164:167], v[98:101]
	s_nop 0
	s_barrier
	s_nop 0
	s_nop 0
	ds_read_b128 v[98:101], v142 offset:16384
	ds_read_b128 v[102:105], v142 offset:17408
	ds_read_b128 v[106:109], v142 offset:18432
	ds_read_b128 v[110:113], v142 offset:19456
	s_barrier
	s_waitcnt lgkmcnt(0)
	s_nop 0
	s_waitcnt lgkmcnt(3)
	v_mfma_f32_16x16x32_bf16 v[94:97], v[168:171], v[98:101], v[94:97]
	s_waitcnt lgkmcnt(1)
	v_mfma_f32_16x16x32_bf16 v[90:93], v[168:171], v[106:109], v[90:93]
	v_mfma_f32_16x16x32_bf16 v[86:89], v[176:179], v[98:101], v[86:89]
	v_mfma_f32_16x16x32_bf16 v[82:85], v[176:179], v[106:109], v[82:85]
	v_mfma_f32_16x16x32_bf16 v[94:97], v[172:175], v[102:105], v[94:97]
	s_waitcnt lgkmcnt(0)
	v_mfma_f32_16x16x32_bf16 v[90:93], v[172:175], v[110:113], v[90:93]
	v_mfma_f32_16x16x32_bf16 v[86:89], v[180:183], v[102:105], v[86:89]
	v_mfma_f32_16x16x32_bf16 v[82:85], v[180:183], v[110:113], v[82:85]
	v_mfma_f32_16x16x32_bf16 v[78:81], v[184:187], v[98:101], v[78:81]
	v_mfma_f32_16x16x32_bf16 v[74:77], v[184:187], v[106:109], v[74:77]
	v_mfma_f32_16x16x32_bf16 v[70:73], v[192:195], v[98:101], v[70:73]
	v_mfma_f32_16x16x32_bf16 v[66:69], v[192:195], v[106:109], v[66:69]
	v_mfma_f32_16x16x32_bf16 v[168:171], v[188:191], v[102:105], v[78:81]
	v_mfma_f32_16x16x32_bf16 v[172:175], v[188:191], v[110:113], v[74:77]
	v_mfma_f32_16x16x32_bf16 v[176:179], v[196:199], v[102:105], v[70:73]
	v_mfma_f32_16x16x32_bf16 v[180:183], v[196:199], v[110:113], v[66:69]
	s_nop 0
	s_barrier
	s_nop 1
	ds_read_b128 v[66:69], v140 offset:16384
	ds_read_b128 v[70:73], v140 offset:17408
	ds_read_b128 v[74:77], v140 offset:18432
	ds_read_b128 v[78:81], v140 offset:19456
	ds_read_b128 v[184:187], v140 offset:20480
	ds_read_b128 v[188:191], v140 offset:21504
	ds_read_b128 v[192:195], v140 offset:22528
	ds_read_b128 v[196:199], v140 offset:23552
	s_waitcnt vmcnt(4)
	s_barrier
; #define LDA(dst, b, h) _Pragma("unroll") for (int m = 0; m < 4; ++m) _Pragma("unroll") for (int k = 0; k < 2; ++k) \
;     dst[m][k] = *(const __attribute__((address_space(3))) bf16x8*)(aB + (((b) * 2 + (h)) * 16384 + m * 2048 + k * 1024))
; #define LDB(dst, b, h) _Pragma("unroll") for (int n = 0; n < 2; ++n) _Pragma("unroll") for (int k = 0; k < 2; ++k) \
;     dst[n][k] = *(const __attribute__((address_space(3))) bf16x8*)(bB + (((b) * 2 + (h)) * 16384 + n * 2048 + k * 1024))
; #define MMA(ai, bj, At, Bq) do { __builtin_amdgcn_s_setprio(1); \
;     _Pragma("unroll") for (int m = 0; m < 4; ++m) _Pragma("unroll") for (int n = 0; n < 2; ++n) _Pragma("unroll") for (int k = 0; k < 2; ++k) \
;       acc[ai][bj][m][n] = __builtin_amdgcn_mfma_f32_16x16x32_bf16(At[m][k], Bq[n][k], acc[ai][bj][m][n], 0, 0, 0); \
;     __builtin_amdgcn_s_setprio(0); } while (0)
; #define WAIT_V(n) asm volatile("s_waitcnt vmcnt(" #n ")" ::: "memory")
; #define WAIT_L(n) asm volatile("s_waitcnt lgkmcnt(" #n ")" ::: "memory")
; #define BAR __builtin_amdgcn_s_barrier()
; template <int MODE>
; DI void gemm_tile(const Params& p, const bf16_t* __restrict__ A, const bf16_t* __restrict__ Bt, int K, int brow, int bcol, int mp, int nt, bool vt, char* smem) {
;     ...
;     LDA(At, 0, 1); WAIT_V(4); BAR; WAIT_L(0); MMA(1, 0, At, B0); MMA(1, 1, At, B1); BAR; }
;   { LDB(B0, 1, 0); LDA(At, 1, 0); WAIT_V(2); BAR; WAIT_L(0); MMA(0, 0, At, B0); BAR;
	s_waitcnt lgkmcnt(0)
	s_nop 0
	s_waitcnt lgkmcnt(7)
	v_mfma_f32_16x16x32_bf16 v[62:65], v[66:69], v[134:137], v[62:65]
	v_mfma_f32_16x16x32_bf16 v[58:61], v[66:69], v[156:159], v[58:61]
	s_waitcnt lgkmcnt(5)
	v_mfma_f32_16x16x32_bf16 v[54:57], v[74:77], v[134:137], v[54:57]
	v_mfma_f32_16x16x32_bf16 v[50:53], v[74:77], v[156:159], v[50:53]
	v_mfma_f32_16x16x32_bf16 v[62:65], v[70:73], v[148:151], v[62:65]
	v_mfma_f32_16x16x32_bf16 v[58:61], v[70:73], v[164:167], v[58:61]
	s_waitcnt lgkmcnt(4)
	v_mfma_f32_16x16x32_bf16 v[54:57], v[78:81], v[148:151], v[54:57]
	v_mfma_f32_16x16x32_bf16 v[50:53], v[78:81], v[164:167], v[50:53]
	s_waitcnt lgkmcnt(3)
	v_mfma_f32_16x16x32_bf16 v[46:49], v[184:187], v[134:137], v[46:49]
	v_mfma_f32_16x16x32_bf16 v[42:45], v[184:187], v[156:159], v[42:45]
	s_waitcnt lgkmcnt(1)
	v_mfma_f32_16x16x32_bf16 v[38:41], v[192:195], v[134:137], v[38:41]
	v_mfma_f32_16x16x32_bf16 v[34:37], v[192:195], v[156:159], v[34:37]
	v_mfma_f32_16x16x32_bf16 v[222:225], v[188:191], v[148:151], v[46:49]
	v_mfma_f32_16x16x32_bf16 v[226:229], v[188:191], v[164:167], v[42:45]
	s_waitcnt lgkmcnt(0)
	v_mfma_f32_16x16x32_bf16 v[134:137], v[196:199], v[148:151], v[38:41]
	v_mfma_f32_16x16x32_bf16 v[148:151], v[196:199], v[164:167], v[34:37]
	s_nop 0
	s_nop 0
	v_mfma_f32_16x16x32_bf16 v[30:33], v[66:69], v[98:101], v[30:33]
	v_mfma_f32_16x16x32_bf16 v[26:29], v[66:69], v[106:109], v[26:29]
	v_mfma_f32_16x16x32_bf16 v[22:25], v[74:77], v[98:101], v[22:25]
	v_mfma_f32_16x16x32_bf16 v[18:21], v[74:77], v[106:109], v[18:21]
	v_mfma_f32_16x16x32_bf16 v[30:33], v[70:73], v[102:105], v[30:33]
	v_mfma_f32_16x16x32_bf16 v[26:29], v[70:73], v[110:113], v[26:29]
	v_mfma_f32_16x16x32_bf16 v[22:25], v[78:81], v[102:105], v[22:25]
	v_mfma_f32_16x16x32_bf16 v[18:21], v[78:81], v[110:113], v[18:21]
	v_mfma_f32_16x16x32_bf16 v[14:17], v[184:187], v[98:101], v[14:17]
	v_mfma_f32_16x16x32_bf16 v[10:13], v[184:187], v[106:109], v[10:13]
	v_mfma_f32_16x16x32_bf16 v[6:9], v[192:195], v[98:101], v[6:9]
	v_mfma_f32_16x16x32_bf16 v[2:5], v[192:195], v[106:109], v[2:5]
	v_mfma_f32_16x16x32_bf16 v[156:159], v[188:191], v[102:105], v[14:17]
	v_mfma_f32_16x16x32_bf16 v[164:167], v[188:191], v[110:113], v[10:13]
	v_mfma_f32_16x16x32_bf16 v[184:187], v[196:199], v[102:105], v[6:9]
	v_mfma_f32_16x16x32_bf16 v[188:191], v[196:199], v[110:113], v[2:5]
	s_nop 0
	s_barrier
	s_nop 1
	ds_read_b128 v[2:5], v142 offset:32768
	ds_read_b128 v[6:9], v142 offset:33792
	ds_read_b128 v[10:13], v142 offset:34816
	ds_read_b128 v[14:17], v142 offset:35840
	ds_read_b128 v[34:37], v140 offset:32768
	ds_read_b128 v[38:41], v140 offset:33792
	ds_read_b128 v[42:45], v140 offset:34816
	ds_read_b128 v[46:49], v140 offset:35840
	ds_read_b128 v[192:195], v140 offset:36864
	ds_read_b128 v[196:199], v140 offset:37888
	ds_read_b128 v[230:233], v140 offset:38912
	ds_read_b128 v[234:237], v140 offset:39936
	s_waitcnt vmcnt(2)
	s_barrier
	s_waitcnt lgkmcnt(0)
	s_nop 0
	s_waitcnt lgkmcnt(7)
	v_mfma_f32_16x16x32_bf16 v[66:69], v[34:37], v[2:5], v[126:129]
	s_waitcnt lgkmcnt(6)
	v_mfma_f32_16x16x32_bf16 v[98:101], v[38:41], v[6:9], v[66:69]
	v_mfma_f32_16x16x32_bf16 v[66:69], v[34:37], v[10:13], v[122:125]
	v_mfma_f32_16x16x32_bf16 v[102:105], v[38:41], v[14:17], v[66:69]
	s_waitcnt lgkmcnt(5)
	v_mfma_f32_16x16x32_bf16 v[66:69], v[42:45], v[2:5], v[118:121]
	s_waitcnt lgkmcnt(4)
	v_mfma_f32_16x16x32_bf16 v[106:109], v[46:49], v[6:9], v[66:69]
	v_mfma_f32_16x16x32_bf16 v[66:69], v[42:45], v[10:13], v[114:117]
	v_mfma_f32_16x16x32_bf16 v[110:113], v[46:49], v[14:17], v[66:69]
	s_waitcnt lgkmcnt(3)
	v_mfma_f32_16x16x32_bf16 v[66:69], v[192:195], v[2:5], v[130:133]
	s_waitcnt lgkmcnt(2)
	v_mfma_f32_16x16x32_bf16 v[114:117], v[196:199], v[6:9], v[66:69]
	v_mfma_f32_16x16x32_bf16 v[66:69], v[192:195], v[10:13], v[160:163]
	v_mfma_f32_16x16x32_bf16 v[118:121], v[196:199], v[14:17], v[66:69]
	s_waitcnt lgkmcnt(1)
	v_mfma_f32_16x16x32_bf16 v[66:69], v[230:233], v[2:5], v[214:217]
	s_waitcnt lgkmcnt(0)
	v_mfma_f32_16x16x32_bf16 v[122:125], v[234:237], v[6:9], v[66:69]
	v_mfma_f32_16x16x32_bf16 v[66:69], v[230:233], v[10:13], v[218:221]
	v_mfma_f32_16x16x32_bf16 v[126:129], v[234:237], v[14:17], v[66:69]
	s_nop 0
	s_barrier
; #define LDA(dst, b, h) _Pragma("unroll") for (int m = 0; m < 4; ++m) _Pragma("unroll") for (int k = 0; k < 2; ++k) \
;     dst[m][k] = *(const __attribute__((address_space(3))) bf16x8*)(aB + (((b) * 2 + (h)) * 16384 + m * 2048 + k * 1024))
; #define LDB(dst, b, h) _Pragma("unroll") for (int n = 0; n < 2; ++n) _Pragma("unroll") for (int k = 0; k < 2; ++k) \
;     dst[n][k] = *(const __attribute__((address_space(3))) bf16x8*)(bB + (((b) * 2 + (h)) * 16384 + n * 2048 + k * 1024))
; #define MMA(ai, bj, At, Bq) do { __builtin_amdgcn_s_setprio(1); \
;     _Pragma("unroll") for (int m = 0; m < 4; ++m) _Pragma("unroll") for (int n = 0; n < 2; ++n) _Pragma("unroll") for (int k = 0; k < 2; ++k) \
;       acc[ai][bj][m][n] = __builtin_amdgcn_mfma_f32_16x16x32_bf16(At[m][k], Bq[n][k], acc[ai][bj][m][n], 0, 0, 0); \
;     __builtin_amdgcn_s_setprio(0); } while (0)
; #define WAIT_V(n) asm volatile("s_waitcnt vmcnt(" #n ")" ::: "memory")
; #define WAIT_L(n) asm volatile("s_waitcnt lgkmcnt(" #n ")" ::: "memory")
; #define BAR __builtin_amdgcn_s_barrier()
; template <int MODE>
; DI void gemm_tile(const Params& p, const bf16_t* __restrict__ A, const bf16_t* __restrict__ Bt, int K, int brow, int bcol, int mp, int nt, bool vt, char* smem) {
;     ...
;   { LDB(B0, 1, 0); LDA(At, 1, 0); WAIT_V(2); BAR; WAIT_L(0); MMA(0, 0, At, B0); BAR;
;     LDB(B1, 1, 1); WAIT_V(0); BAR; WAIT_L(0); MMA(0, 1, At, B1); BAR;
;     LDA(At, 1, 1); BAR; WAIT_L(0); MMA(1, 0, At, B0); MMA(1, 1, At, B1); BAR; }
;   if (wr == 0) BAR;
	ds_read_b128 v[130:133], v142 offset:49152
	ds_read_b128 v[160:163], v142 offset:50176
	ds_read_b128 v[214:217], v142 offset:51200
	ds_read_b128 v[218:221], v142 offset:52224
	s_waitcnt vmcnt(0)
	s_barrier
	s_waitcnt lgkmcnt(0)
	s_nop 0
	s_waitcnt lgkmcnt(3)
	v_mfma_f32_16x16x32_bf16 v[66:69], v[34:37], v[130:133], v[94:97]
	s_waitcnt lgkmcnt(1)
	v_mfma_f32_16x16x32_bf16 v[34:37], v[34:37], v[214:217], v[90:93]
	s_waitcnt lgkmcnt(0)
	v_mfma_f32_16x16x32_bf16 v[70:73], v[38:41], v[218:221], v[34:37]
	v_mfma_f32_16x16x32_bf16 v[34:37], v[42:45], v[130:133], v[86:89]
	v_mfma_f32_16x16x32_bf16 v[74:77], v[46:49], v[160:163], v[34:37]
	v_mfma_f32_16x16x32_bf16 v[34:37], v[42:45], v[214:217], v[82:85]
	v_mfma_f32_16x16x32_bf16 v[78:81], v[46:49], v[218:221], v[34:37]
	v_mfma_f32_16x16x32_bf16 v[34:37], v[192:195], v[130:133], v[168:171]
	v_mfma_f32_16x16x32_bf16 v[82:85], v[196:199], v[160:163], v[34:37]
	v_mfma_f32_16x16x32_bf16 v[34:37], v[192:195], v[214:217], v[172:175]
	v_mfma_f32_16x16x32_bf16 v[86:89], v[196:199], v[218:221], v[34:37]
	v_mfma_f32_16x16x32_bf16 v[34:37], v[230:233], v[130:133], v[176:179]
	v_mfma_f32_16x16x32_bf16 v[90:93], v[234:237], v[160:163], v[34:37]
	v_mfma_f32_16x16x32_bf16 v[34:37], v[230:233], v[214:217], v[180:183]
	v_mfma_f32_16x16x32_bf16 v[66:69], v[38:41], v[160:163], v[66:69]
	v_mfma_f32_16x16x32_bf16 v[94:97], v[234:237], v[218:221], v[34:37]
	s_nop 0
	s_barrier
	ds_read_b128 v[168:171], v140 offset:49152
	ds_read_b128 v[172:175], v140 offset:50176
	ds_read_b128 v[176:179], v140 offset:51200
	ds_read_b128 v[180:183], v140 offset:52224
	ds_read_b128 v[192:195], v140 offset:53248
	ds_read_b128 v[196:199], v140 offset:54272
	ds_read_b128 v[230:233], v140 offset:55296
	ds_read_b128 v[138:141], v140 offset:56320
	s_barrier
	s_waitcnt lgkmcnt(0)
	s_nop 0
	s_waitcnt lgkmcnt(7)
	v_mfma_f32_16x16x32_bf16 v[34:37], v[168:171], v[2:5], v[62:65]
	s_waitcnt lgkmcnt(5)
	v_mfma_f32_16x16x32_bf16 v[42:45], v[176:179], v[2:5], v[54:57]
	v_mfma_f32_16x16x32_bf16 v[46:49], v[176:179], v[10:13], v[50:53]
	s_waitcnt lgkmcnt(3)
	v_mfma_f32_16x16x32_bf16 v[50:53], v[192:195], v[2:5], v[222:225]
	s_waitcnt lgkmcnt(1)
	v_mfma_f32_16x16x32_bf16 v[2:5], v[230:233], v[2:5], v[134:137]
	v_mfma_f32_16x16x32_bf16 v[38:41], v[168:171], v[10:13], v[58:61]
	v_mfma_f32_16x16x32_bf16 v[54:57], v[192:195], v[10:13], v[226:229]
	s_waitcnt lgkmcnt(0)
	v_mfma_f32_16x16x32_bf16 v[58:61], v[138:141], v[6:9], v[2:5]
	v_mfma_f32_16x16x32_bf16 v[2:5], v[230:233], v[10:13], v[148:151]
	v_mfma_f32_16x16x32_bf16 v[34:37], v[172:175], v[6:9], v[34:37]
	v_mfma_f32_16x16x32_bf16 v[38:41], v[172:175], v[14:17], v[38:41]
	v_mfma_f32_16x16x32_bf16 v[42:45], v[180:183], v[6:9], v[42:45]
	v_mfma_f32_16x16x32_bf16 v[46:49], v[180:183], v[14:17], v[46:49]
	v_mfma_f32_16x16x32_bf16 v[50:53], v[196:199], v[6:9], v[50:53]
	v_mfma_f32_16x16x32_bf16 v[54:57], v[196:199], v[14:17], v[54:57]
	v_mfma_f32_16x16x32_bf16 v[62:65], v[138:141], v[14:17], v[2:5]
	s_nop 0
	s_nop 0
	v_mfma_f32_16x16x32_bf16 v[2:5], v[168:171], v[130:133], v[30:33]
	v_mfma_f32_16x16x32_bf16 v[6:9], v[168:171], v[214:217], v[26:29]
	v_mfma_f32_16x16x32_bf16 v[10:13], v[176:179], v[130:133], v[22:25]
	v_mfma_f32_16x16x32_bf16 v[14:17], v[176:179], v[214:217], v[18:21]
	v_mfma_f32_16x16x32_bf16 v[18:21], v[192:195], v[130:133], v[156:159]
	v_mfma_f32_16x16x32_bf16 v[22:25], v[192:195], v[214:217], v[164:167]
	v_mfma_f32_16x16x32_bf16 v[26:29], v[230:233], v[130:133], v[184:187]
	v_mfma_f32_16x16x32_bf16 v[30:33], v[230:233], v[214:217], v[188:191]
	v_mfma_f32_16x16x32_bf16 v[2:5], v[172:175], v[160:163], v[2:5]
	v_mfma_f32_16x16x32_bf16 v[6:9], v[172:175], v[218:221], v[6:9]
	v_mfma_f32_16x16x32_bf16 v[10:13], v[180:183], v[160:163], v[10:13]
	v_mfma_f32_16x16x32_bf16 v[14:17], v[180:183], v[218:221], v[14:17]
	v_mfma_f32_16x16x32_bf16 v[18:21], v[196:199], v[160:163], v[18:21]
	v_mfma_f32_16x16x32_bf16 v[22:25], v[196:199], v[218:221], v[22:25]
	v_mfma_f32_16x16x32_bf16 v[26:29], v[138:141], v[160:163], v[26:29]
	v_mfma_f32_16x16x32_bf16 v[30:33], v[138:141], v[218:221], v[30:33]
	s_nop 0
	s_movk_i32 s1, 0x100
	v_cmp_gt_u32_e32 vcc, s1, v144
	s_barrier
	s_and_saveexec_b64 s[6:7], vcc
	s_cbranch_execz .LBB0_529
	s_barrier

; #define LDA(dst, b, h) _Pragma("unroll") for (int m = 0; m < 4; ++m) _Pragma("unroll") for (int k = 0; k < 2; ++k) \
;     dst[m][k] = *(const __attribute__((address_space(3))) bf16x8*)(aB + (((b) * 2 + (h)) * 16384 + m * 2048 + k * 1024))
; #define WAIT_V(n) asm volatile("s_waitcnt vmcnt(" #n ")" ::: "memory")
; template <int MODE>
; DI void gemm_tile(const Params& p, const bf16_t* __restrict__ A, const bf16_t* __restrict__ Bt, int K, int brow, int bcol, int mp, int nt, bool vt, char* smem) {
;     ...
;   const int wid = tid >> 6, lane = tid & 63, wr = wid >> 2, wc = wid & 3, fr = lane & 15, fq = lane >> 4;
;   const int laneoff = (fr * 64 + fq * 16) ^ ((fr >> 3) << 5);
;   const __attribute__((address_space(3))) char* aB = (const __attribute__((address_space(3))) char*)smem + wr * 8192 + laneoff;
;   const __attribute__((address_space(3))) char* bB = (const __attribute__((address_space(3))) char*)smem + 65536 + wc * 4096 + laneoff;
;   f32x4 acc[2][2][4][2];
; #pragma unroll
;   for (int a = 0; a < 2; ++a)
; #pragma unroll
;     for (int b = 0; b < 2; ++b)
; #pragma unroll
;       for (int m = 0; m < 4; ++m)
; #pragma unroll
;         for (int n = 0; n < 2; ++n) acc[a][b][m][n] = (f32x4){0.f, 0.f, 0.f, 0.f};
;   bf16x8 At[4][2], B0[2][2], B1[2][2];
;   const int ntk = K / 64;
;   const int m0 = mp * 256, n0 = nt * 256;
;   float* rsl = (float*)(smem + 131072);
;   float4 ssa = make_float4(0.f, 0.f, 0.f, 0.f);
;   if (MODE == MODE_PROJ || MODE == MODE_UP)
;     ssa = *(const float4*)((const float*)(p.ws + (MODE == MODE_UP ? OFF_SSB : OFF_SSA)) + (size_t)m0 * 8 + tid * 4);
;   STAGE(SB(0, 0), Bt, bcol, 0); STAGE(SA(0, 0), A, brow, 0);
;   STAGE(SB(0, 1), Bt, bcol + 128, 0); STAGE(SA(0, 1), A, brow + 128, 0);
;   if (wr == 1) BAR;
;   WAIT_V(4); BAR;
;   STAGE(SB(1, 0), Bt, bcol, 1); STAGE(SA(1, 0), A, brow, 1); STAGE(SB(1, 1), Bt, bcol + 128, 1);
;   WAIT_V(6); BAR;
;   if (MODE == MODE_PROJ || MODE == MODE_UP) {
;     float t = (ssa.x + ssa.y) + (ssa.z + ssa.w);
;     t += __shfl_xor(t, 1);
;     if ((tid & 1) == 0) rsl[tid >> 1] = rsqrtf(t * (1.f / 1024.f) + 1e-6f);
;   }
;   for (int t = 0; t < ntk - 2; t += 2) {
;     LDB(B0, 0, 0); SCHED; LDA(At, 0, 0); STAGE(SA(1, 1), A, brow + 128, t + 1);
;     WAIT_L(8); BAR; WAIT_L(0); MMA(0, 0, At, B0); BAR; SCHED;
;     LDB(B1, 0, 1); STAGE(SB(0, 0), Bt, bcol, t + 2);
;     BAR; WAIT_L(0); MMA(0, 1, At, B1); BAR;
.LBB0_586:
	s_or_b64 exec, exec, s[14:15]
	s_add_u32 s1, s10, 0x100
	s_addc_u32 s14, s11, 0
	v_and_b32_e32 v142, 15, v0
	s_add_u32 s12, s22, s12
	v_bfe_u32 v131, v0, 6, 2
	v_and_b32_e32 v141, 48, v0
	v_and_b32_e32 v2, 32, v130
	v_lshlrev_b32_e32 v5, 6, v142
	s_addc_u32 s13, s21, s13
	s_waitcnt lgkmcnt(0)
	v_lshlrev_b32_e32 v3, 13, v6
	v_lshl_or_b32 v4, v131, 12, v205
	v_bitop3_b32 v5, v5, v2, v141 bitop3:0x36
	s_add_u32 s15, s12, 0x40000
	s_addc_u32 s21, s13, 0
	s_mov_b32 s22, -2
	s_mov_b64 s[12:13], 0
	v_add_u32_e32 v147, v4, v5
	v_add_u32_e32 v145, v3, v5
	s_nop 0
	ds_read_b128 v[164:167], v147
	ds_read_b128 v[168:171], v147 offset:1024
	ds_read_b128 v[172:175], v147 offset:2048
	ds_read_b128 v[176:179], v147 offset:3072
	s_add_u32 s23, s15, s12
	s_addc_u32 s25, s21, s13
	s_add_u32 s24, s23, 0x80
	v_add_u32_e32 v162, 0xc000, v140
	s_addc_u32 s25, s25, 0
	v_readfirstlane_b32 s23, v162
	v_add_u32_e32 v163, 0xe000, v140
	ds_read_b128 v[180:183], v145
	ds_read_b128 v[184:187], v145 offset:1024
	ds_read_b128 v[188:191], v145 offset:2048
	ds_read_b128 v[192:195], v145 offset:3072
	ds_read_b128 v[196:199], v145 offset:4096
	ds_read_b128 v[214:217], v145 offset:5120
	ds_read_b128 v[218:221], v145 offset:6144
	ds_read_b128 v[222:225], v145 offset:7168
	s_mov_b32 m0, s23
	v_lshl_add_u64 v[226:227], s[24:25], 0, v[136:137]
	v_readfirstlane_b32 s23, v163
	global_load_lds_dwordx4 v[226:227], off
	v_lshl_add_u64 v[226:227], s[24:25], 0, v[138:139]
	s_mov_b32 m0, s23
	s_nop 0
	global_load_lds_dwordx4 v[226:227], off
	s_waitcnt lgkmcnt(8)
	s_barrier
	s_waitcnt lgkmcnt(0)
	s_nop 0
	s_waitcnt lgkmcnt(0)
	v_mfma_f32_16x16x32_bf16 v[126:129], v[180:183], v[164:167], 0
	v_mfma_f32_16x16x32_bf16 v[122:125], v[180:183], v[172:175], 0
	v_mfma_f32_16x16x32_bf16 v[118:121], v[188:191], v[164:167], 0
	v_mfma_f32_16x16x32_bf16 v[114:117], v[188:191], v[172:175], 0
	v_mfma_f32_16x16x32_bf16 v[110:113], v[196:199], v[164:167], 0
	v_mfma_f32_16x16x32_bf16 v[106:109], v[196:199], v[172:175], 0
	v_mfma_f32_16x16x32_bf16 v[102:105], v[218:221], v[164:167], 0
	v_mfma_f32_16x16x32_bf16 v[98:101], v[218:221], v[172:175], 0
	v_mfma_f32_16x16x32_bf16 v[126:129], v[184:187], v[168:171], v[126:129]
	v_mfma_f32_16x16x32_bf16 v[122:125], v[184:187], v[176:179], v[122:125]
	v_mfma_f32_16x16x32_bf16 v[118:121], v[192:195], v[168:171], v[118:121]
	v_mfma_f32_16x16x32_bf16 v[114:117], v[192:195], v[176:179], v[114:117]
	v_mfma_f32_16x16x32_bf16 v[110:113], v[214:217], v[168:171], v[110:113]
	v_mfma_f32_16x16x32_bf16 v[106:109], v[214:217], v[176:179], v[106:109]
	v_mfma_f32_16x16x32_bf16 v[102:105], v[222:225], v[168:171], v[102:105]
	v_mfma_f32_16x16x32_bf16 v[98:101], v[222:225], v[176:179], v[98:101]
	s_nop 0
	s_barrier
	s_add_u32 s23, s2, s12
	s_addc_u32 s26, s3, s13
	s_add_u32 s24, s23, 0x100
	s_addc_u32 s25, s26, 0
	v_readfirstlane_b32 s27, v144
	s_nop 0
	ds_read_b128 v[226:229], v147 offset:16384
	ds_read_b128 v[230:233], v147 offset:17408
	ds_read_b128 v[234:237], v147 offset:18432
	ds_read_b128 v[238:241], v147 offset:19456
	s_mov_b32 m0, s27
	v_lshl_add_u64 v[242:243], s[24:25], 0, v[136:137]
	global_load_lds_dwordx4 v[242:243], off
	v_lshl_add_u64 v[242:243], s[24:25], 0, v[138:139]
	v_readfirstlane_b32 s24, v146
	s_mov_b32 m0, s24
	s_nop 0
	global_load_lds_dwordx4 v[242:243], off
	s_barrier
	s_waitcnt lgkmcnt(0)
	s_nop 0
	s_waitcnt lgkmcnt(0)
	v_mfma_f32_16x16x32_bf16 v[94:97], v[180:183], v[226:229], 0
	v_mfma_f32_16x16x32_bf16 v[90:93], v[180:183], v[234:237], 0
	v_mfma_f32_16x16x32_bf16 v[86:89], v[188:191], v[226:229], 0
	v_mfma_f32_16x16x32_bf16 v[82:85], v[188:191], v[234:237], 0
	v_mfma_f32_16x16x32_bf16 v[78:81], v[196:199], v[226:229], 0
	v_mfma_f32_16x16x32_bf16 v[74:77], v[196:199], v[234:237], 0
	v_mfma_f32_16x16x32_bf16 v[70:73], v[218:221], v[226:229], 0
	v_mfma_f32_16x16x32_bf16 v[66:69], v[218:221], v[234:237], 0
	v_mfma_f32_16x16x32_bf16 v[94:97], v[184:187], v[230:233], v[94:97]
	v_mfma_f32_16x16x32_bf16 v[90:93], v[184:187], v[238:241], v[90:93]
	v_mfma_f32_16x16x32_bf16 v[86:89], v[192:195], v[230:233], v[86:89]
	v_mfma_f32_16x16x32_bf16 v[82:85], v[192:195], v[238:241], v[82:85]
	v_mfma_f32_16x16x32_bf16 v[78:81], v[214:217], v[230:233], v[78:81]
	v_mfma_f32_16x16x32_bf16 v[74:77], v[214:217], v[238:241], v[74:77]
	v_mfma_f32_16x16x32_bf16 v[70:73], v[222:225], v[230:233], v[70:73]
	v_mfma_f32_16x16x32_bf16 v[66:69], v[222:225], v[238:241], v[66:69]
	s_nop 0
	s_add_u32 s27, s4, s12
	s_addc_u32 s28, s5, s13
	s_add_u32 s24, s27, 0x100
	s_addc_u32 s25, s28, 0
	v_readfirstlane_b32 s29, v140
	s_barrier
	s_nop 0
	ds_read_b128 v[180:183], v145 offset:16384
	ds_read_b128 v[184:187], v145 offset:17408
	ds_read_b128 v[188:191], v145 offset:18432
	ds_read_b128 v[192:195], v145 offset:19456
	ds_read_b128 v[196:199], v145 offset:20480
	ds_read_b128 v[214:217], v145 offset:21504
	ds_read_b128 v[218:221], v145 offset:22528
	ds_read_b128 v[222:225], v145 offset:23552
	s_mov_b32 m0, s29
	v_lshl_add_u64 v[242:243], s[24:25], 0, v[136:137]
	global_load_lds_dwordx4 v[242:243], off
	v_lshl_add_u64 v[242:243], s[24:25], 0, v[138:139]
	v_readfirstlane_b32 s24, v143
	s_mov_b32 m0, s24
	s_nop 0
	global_load_lds_dwordx4 v[242:243], off
	s_barrier
; #define STAGE(P, BASE, br, kt) do { const bf16_t* _gb = (BASE) + (long)(br) * K + (long)(kt) * 64; asm volatile("" : "+s"(_gb)); \
;     __builtin_amdgcn_global_load_lds((const unsigned*)(_gb + go0), (lds_u32*)((char*)(P) + tid * 16), 16, 0, 0); \
;     __builtin_amdgcn_global_load_lds((const unsigned*)(_gb + go1), (lds_u32*)((char*)(P) + tid * 16 + 8192), 16, 0, 0); } while (0)
; #define LDA(dst, b, h) _Pragma("unroll") for (int m = 0; m < 4; ++m) _Pragma("unroll") for (int k = 0; k < 2; ++k) \
;     dst[m][k] = *(const __attribute__((address_space(3))) bf16x8*)(aB + (((b) * 2 + (h)) * 16384 + m * 2048 + k * 1024))
; #define LDB(dst, b, h) _Pragma("unroll") for (int n = 0; n < 2; ++n) _Pragma("unroll") for (int k = 0; k < 2; ++k) \
;     dst[n][k] = *(const __attribute__((address_space(3))) bf16x8*)(bB + (((b) * 2 + (h)) * 16384 + n * 2048 + k * 1024))
; #define MMA(ai, bj, At, Bq) do { __builtin_amdgcn_s_setprio(1); \
;     _Pragma("unroll") for (int m = 0; m < 4; ++m) _Pragma("unroll") for (int n = 0; n < 2; ++n) _Pragma("unroll") for (int k = 0; k < 2; ++k) \
;       acc[ai][bj][m][n] = __builtin_amdgcn_mfma_f32_16x16x32_bf16(At[m][k], Bq[n][k], acc[ai][bj][m][n], 0, 0, 0); \
;     __builtin_amdgcn_s_setprio(0); } while (0)
; #define WAIT_V(n) asm volatile("s_waitcnt vmcnt(" #n ")" ::: "memory")
; #define WAIT_L(n) asm volatile("s_waitcnt lgkmcnt(" #n ")" ::: "memory")
; #define BAR __builtin_amdgcn_s_barrier()
; #define SCHED __builtin_amdgcn_sched_barrier(0)
; template <int MODE>
; DI void gemm_tile(const Params& p, const bf16_t* __restrict__ A, const bf16_t* __restrict__ Bt, int K, int brow, int bcol, int mp, int nt, bool vt, char* smem) {
;     ...
;     LDB(B0, 0, 0); SCHED; LDA(At, 0, 0); STAGE(SA(1, 1), A, brow + 128, t + 1);
;     WAIT_L(8); BAR; WAIT_L(0); MMA(0, 0, At, B0); BAR; SCHED;
;     LDB(B1, 0, 1); STAGE(SB(0, 0), Bt, bcol, t + 2);
;     BAR; WAIT_L(0); MMA(0, 1, At, B1); BAR;
;     LDA(At, 0, 1); STAGE(SA(0, 0), A, brow, t + 2);
;     BAR; WAIT_L(0); MMA(1, 0, At, B0); BAR; SCHED;
;     STAGE(SB(0, 1), Bt, bcol + 128, t + 2);
;     WAIT_V(6); BAR; MMA(1, 1, At, B1); BAR;
	s_waitcnt lgkmcnt(0)
	s_nop 0
	s_waitcnt lgkmcnt(0)
	v_mfma_f32_16x16x32_bf16 v[62:65], v[180:183], v[164:167], 0
	v_mfma_f32_16x16x32_bf16 v[58:61], v[180:183], v[172:175], 0
	v_mfma_f32_16x16x32_bf16 v[54:57], v[188:191], v[164:167], 0
	v_mfma_f32_16x16x32_bf16 v[50:53], v[188:191], v[172:175], 0
	v_mfma_f32_16x16x32_bf16 v[46:49], v[196:199], v[164:167], 0
	v_mfma_f32_16x16x32_bf16 v[42:45], v[196:199], v[172:175], 0
	v_mfma_f32_16x16x32_bf16 v[38:41], v[218:221], v[164:167], 0
	v_mfma_f32_16x16x32_bf16 v[34:37], v[218:221], v[172:175], 0
	v_mfma_f32_16x16x32_bf16 v[62:65], v[184:187], v[168:171], v[62:65]
	v_mfma_f32_16x16x32_bf16 v[58:61], v[184:187], v[176:179], v[58:61]
	v_mfma_f32_16x16x32_bf16 v[54:57], v[192:195], v[168:171], v[54:57]
	v_mfma_f32_16x16x32_bf16 v[50:53], v[192:195], v[176:179], v[50:53]
	v_mfma_f32_16x16x32_bf16 v[46:49], v[214:217], v[168:171], v[46:49]
	v_mfma_f32_16x16x32_bf16 v[42:45], v[214:217], v[176:179], v[42:45]
	v_mfma_f32_16x16x32_bf16 v[38:41], v[222:225], v[168:171], v[38:41]
	v_mfma_f32_16x16x32_bf16 v[34:37], v[222:225], v[176:179], v[34:37]
	s_nop 0
	s_barrier
	s_add_u32 s29, s6, s12
	s_addc_u32 s30, s7, s13
	s_add_u32 s24, s29, 0x100
	s_addc_u32 s25, s30, 0
	v_readfirstlane_b32 s31, v148
	s_mov_b32 m0, s31
	v_lshl_add_u64 v[164:165], s[24:25], 0, v[136:137]
	global_load_lds_dwordx4 v[164:165], off
	v_lshl_add_u64 v[164:165], s[24:25], 0, v[138:139]
	v_readfirstlane_b32 s24, v149
	s_mov_b32 m0, s24
	s_nop 0
	global_load_lds_dwordx4 v[164:165], off
	s_waitcnt vmcnt(6)
	s_barrier
	s_nop 0
	v_mfma_f32_16x16x32_bf16 v[30:33], v[180:183], v[226:229], 0
	v_mfma_f32_16x16x32_bf16 v[26:29], v[180:183], v[234:237], 0
	v_mfma_f32_16x16x32_bf16 v[22:25], v[188:191], v[226:229], 0
	v_mfma_f32_16x16x32_bf16 v[18:21], v[188:191], v[234:237], 0
	v_mfma_f32_16x16x32_bf16 v[14:17], v[196:199], v[226:229], 0
	v_mfma_f32_16x16x32_bf16 v[10:13], v[196:199], v[234:237], 0
	v_mfma_f32_16x16x32_bf16 v[6:9], v[218:221], v[226:229], 0
	v_mfma_f32_16x16x32_bf16 v[2:5], v[218:221], v[234:237], 0
	v_mfma_f32_16x16x32_bf16 v[30:33], v[184:187], v[230:233], v[30:33]
	v_mfma_f32_16x16x32_bf16 v[26:29], v[184:187], v[238:241], v[26:29]
	v_mfma_f32_16x16x32_bf16 v[22:25], v[192:195], v[230:233], v[22:25]
	v_mfma_f32_16x16x32_bf16 v[18:21], v[192:195], v[238:241], v[18:21]
	v_mfma_f32_16x16x32_bf16 v[14:17], v[214:217], v[230:233], v[14:17]
	v_mfma_f32_16x16x32_bf16 v[10:13], v[214:217], v[238:241], v[10:13]
	v_mfma_f32_16x16x32_bf16 v[6:9], v[222:225], v[230:233], v[6:9]
	v_mfma_f32_16x16x32_bf16 v[2:5], v[222:225], v[238:241], v[2:5]
	s_nop 0
	s_barrier
	s_branch .Lgemm3_p5
.LBB0_587:
	s_nop 0
	ds_read_b128 v[164:167], v147
	ds_read_b128 v[168:171], v147 offset:1024
	ds_read_b128 v[172:175], v147 offset:2048
	ds_read_b128 v[176:179], v147 offset:3072
	s_add_u32 s23, s15, s12
	s_addc_u32 s25, s21, s13
	s_add_u32 s24, s23, 0x80
	v_add_u32_e32 v162, 0xc000, v140
	s_addc_u32 s25, s25, 0
	v_readfirstlane_b32 s23, v162
	v_add_u32_e32 v163, 0xe000, v140
	ds_read_b128 v[180:183], v145
	ds_read_b128 v[184:187], v145 offset:1024
	ds_read_b128 v[188:191], v145 offset:2048
	ds_read_b128 v[192:195], v145 offset:3072
	ds_read_b128 v[196:199], v145 offset:4096
	ds_read_b128 v[214:217], v145 offset:5120
	ds_read_b128 v[218:221], v145 offset:6144
	ds_read_b128 v[222:225], v145 offset:7168
	s_mov_b32 m0, s23
	v_lshl_add_u64 v[226:227], s[24:25], 0, v[136:137]
	v_readfirstlane_b32 s23, v163
	global_load_lds_dwordx4 v[226:227], off
	v_lshl_add_u64 v[226:227], s[24:25], 0, v[138:139]
	s_mov_b32 m0, s23
	s_nop 0
	global_load_lds_dwordx4 v[226:227], off
	s_waitcnt lgkmcnt(8)
	s_barrier
	s_waitcnt lgkmcnt(0)
	s_nop 0
	s_waitcnt lgkmcnt(0)
	v_mfma_f32_16x16x32_bf16 v[126:129], v[180:183], v[164:167], v[126:129]
	v_mfma_f32_16x16x32_bf16 v[122:125], v[180:183], v[172:175], v[122:125]
	v_mfma_f32_16x16x32_bf16 v[118:121], v[188:191], v[164:167], v[118:121]
	v_mfma_f32_16x16x32_bf16 v[114:117], v[188:191], v[172:175], v[114:117]
	v_mfma_f32_16x16x32_bf16 v[110:113], v[196:199], v[164:167], v[110:113]
	v_mfma_f32_16x16x32_bf16 v[106:109], v[196:199], v[172:175], v[106:109]
	v_mfma_f32_16x16x32_bf16 v[102:105], v[218:221], v[164:167], v[102:105]
	v_mfma_f32_16x16x32_bf16 v[98:101], v[218:221], v[172:175], v[98:101]
	v_mfma_f32_16x16x32_bf16 v[126:129], v[184:187], v[168:171], v[126:129]
	v_mfma_f32_16x16x32_bf16 v[122:125], v[184:187], v[176:179], v[122:125]
	v_mfma_f32_16x16x32_bf16 v[118:121], v[192:195], v[168:171], v[118:121]
	v_mfma_f32_16x16x32_bf16 v[114:117], v[192:195], v[176:179], v[114:117]
	v_mfma_f32_16x16x32_bf16 v[110:113], v[214:217], v[168:171], v[110:113]
	v_mfma_f32_16x16x32_bf16 v[106:109], v[214:217], v[176:179], v[106:109]
	v_mfma_f32_16x16x32_bf16 v[102:105], v[222:225], v[168:171], v[102:105]
	v_mfma_f32_16x16x32_bf16 v[98:101], v[222:225], v[176:179], v[98:101]
	s_nop 0
	s_barrier
	s_add_u32 s23, s2, s12
	s_addc_u32 s26, s3, s13
	s_add_u32 s24, s23, 0x100
	s_addc_u32 s25, s26, 0
	v_readfirstlane_b32 s27, v144
	s_nop 0
	ds_read_b128 v[226:229], v147 offset:16384
	ds_read_b128 v[230:233], v147 offset:17408
	ds_read_b128 v[234:237], v147 offset:18432
	ds_read_b128 v[238:241], v147 offset:19456
	s_mov_b32 m0, s27
	v_lshl_add_u64 v[242:243], s[24:25], 0, v[136:137]
	global_load_lds_dwordx4 v[242:243], off
	v_lshl_add_u64 v[242:243], s[24:25], 0, v[138:139]
	v_readfirstlane_b32 s24, v146
	s_mov_b32 m0, s24
	s_nop 0
	global_load_lds_dwordx4 v[242:243], off
	s_barrier
; #define STAGE(P, BASE, br, kt) do { const bf16_t* _gb = (BASE) + (long)(br) * K + (long)(kt) * 64; asm volatile("" : "+s"(_gb)); \
;     __builtin_amdgcn_global_load_lds((const unsigned*)(_gb + go0), (lds_u32*)((char*)(P) + tid * 16), 16, 0, 0); \
;     __builtin_amdgcn_global_load_lds((const unsigned*)(_gb + go1), (lds_u32*)((char*)(P) + tid * 16 + 8192), 16, 0, 0); } while (0)
; #define LDA(dst, b, h) _Pragma("unroll") for (int m = 0; m < 4; ++m) _Pragma("unroll") for (int k = 0; k < 2; ++k) \
;     dst[m][k] = *(const __attribute__((address_space(3))) bf16x8*)(aB + (((b) * 2 + (h)) * 16384 + m * 2048 + k * 1024))
; #define LDB(dst, b, h) _Pragma("unroll") for (int n = 0; n < 2; ++n) _Pragma("unroll") for (int k = 0; k < 2; ++k) \
;     dst[n][k] = *(const __attribute__((address_space(3))) bf16x8*)(bB + (((b) * 2 + (h)) * 16384 + n * 2048 + k * 1024))
; #define MMA(ai, bj, At, Bq) do { __builtin_amdgcn_s_setprio(1); \
;     _Pragma("unroll") for (int m = 0; m < 4; ++m) _Pragma("unroll") for (int n = 0; n < 2; ++n) _Pragma("unroll") for (int k = 0; k < 2; ++k) \
;       acc[ai][bj][m][n] = __builtin_amdgcn_mfma_f32_16x16x32_bf16(At[m][k], Bq[n][k], acc[ai][bj][m][n], 0, 0, 0); \
;     __builtin_amdgcn_s_setprio(0); } while (0)
; #define WAIT_V(n) asm volatile("s_waitcnt vmcnt(" #n ")" ::: "memory")
; #define WAIT_L(n) asm volatile("s_waitcnt lgkmcnt(" #n ")" ::: "memory")
; #define BAR __builtin_amdgcn_s_barrier()
; #define SCHED __builtin_amdgcn_sched_barrier(0)
; template <int MODE>
; DI void gemm_tile(const Params& p, const bf16_t* __restrict__ A, const bf16_t* __restrict__ Bt, int K, int brow, int bcol, int mp, int nt, bool vt, char* smem) {
;     ...
;     LDB(B1, 0, 1); STAGE(SB(0, 0), Bt, bcol, t + 2);
;     BAR; WAIT_L(0); MMA(0, 1, At, B1); BAR;
;     LDA(At, 0, 1); STAGE(SA(0, 0), A, brow, t + 2);
;     BAR; WAIT_L(0); MMA(1, 0, At, B0); BAR; SCHED;
;     STAGE(SB(0, 1), Bt, bcol + 128, t + 2);
;     WAIT_V(6); BAR; MMA(1, 1, At, B1); BAR;
	s_waitcnt lgkmcnt(0)
	s_nop 0
	s_waitcnt lgkmcnt(0)
	v_mfma_f32_16x16x32_bf16 v[94:97], v[180:183], v[226:229], v[94:97]
	v_mfma_f32_16x16x32_bf16 v[90:93], v[180:183], v[234:237], v[90:93]
	v_mfma_f32_16x16x32_bf16 v[86:89], v[188:191], v[226:229], v[86:89]
	v_mfma_f32_16x16x32_bf16 v[82:85], v[188:191], v[234:237], v[82:85]
	v_mfma_f32_16x16x32_bf16 v[78:81], v[196:199], v[226:229], v[78:81]
	v_mfma_f32_16x16x32_bf16 v[74:77], v[196:199], v[234:237], v[74:77]
	v_mfma_f32_16x16x32_bf16 v[70:73], v[218:221], v[226:229], v[70:73]
	v_mfma_f32_16x16x32_bf16 v[66:69], v[218:221], v[234:237], v[66:69]
	v_mfma_f32_16x16x32_bf16 v[94:97], v[184:187], v[230:233], v[94:97]
	v_mfma_f32_16x16x32_bf16 v[90:93], v[184:187], v[238:241], v[90:93]
	v_mfma_f32_16x16x32_bf16 v[86:89], v[192:195], v[230:233], v[86:89]
	v_mfma_f32_16x16x32_bf16 v[82:85], v[192:195], v[238:241], v[82:85]
	v_mfma_f32_16x16x32_bf16 v[78:81], v[214:217], v[230:233], v[78:81]
	v_mfma_f32_16x16x32_bf16 v[74:77], v[214:217], v[238:241], v[74:77]
	v_mfma_f32_16x16x32_bf16 v[70:73], v[222:225], v[230:233], v[70:73]
	v_mfma_f32_16x16x32_bf16 v[66:69], v[222:225], v[238:241], v[66:69]
	s_nop 0
	s_add_u32 s27, s4, s12
	s_addc_u32 s28, s5, s13
	s_add_u32 s24, s27, 0x100
	s_addc_u32 s25, s28, 0
	v_readfirstlane_b32 s29, v140
	s_barrier
	s_nop 0
	ds_read_b128 v[180:183], v145 offset:16384
	ds_read_b128 v[184:187], v145 offset:17408
	ds_read_b128 v[188:191], v145 offset:18432
	ds_read_b128 v[192:195], v145 offset:19456
	ds_read_b128 v[196:199], v145 offset:20480
	ds_read_b128 v[214:217], v145 offset:21504
	ds_read_b128 v[218:221], v145 offset:22528
	ds_read_b128 v[222:225], v145 offset:23552
	s_mov_b32 m0, s29
	v_lshl_add_u64 v[242:243], s[24:25], 0, v[136:137]
	global_load_lds_dwordx4 v[242:243], off
	v_lshl_add_u64 v[242:243], s[24:25], 0, v[138:139]
	v_readfirstlane_b32 s24, v143
	s_mov_b32 m0, s24
	s_nop 0
	global_load_lds_dwordx4 v[242:243], off
	s_barrier
	s_waitcnt lgkmcnt(0)
	s_nop 0
	s_waitcnt lgkmcnt(0)
	v_mfma_f32_16x16x32_bf16 v[62:65], v[180:183], v[164:167], v[62:65]
	v_mfma_f32_16x16x32_bf16 v[58:61], v[180:183], v[172:175], v[58:61]
	v_mfma_f32_16x16x32_bf16 v[54:57], v[188:191], v[164:167], v[54:57]
	v_mfma_f32_16x16x32_bf16 v[50:53], v[188:191], v[172:175], v[50:53]
	v_mfma_f32_16x16x32_bf16 v[46:49], v[196:199], v[164:167], v[46:49]
	v_mfma_f32_16x16x32_bf16 v[42:45], v[196:199], v[172:175], v[42:45]
	v_mfma_f32_16x16x32_bf16 v[38:41], v[218:221], v[164:167], v[38:41]
	v_mfma_f32_16x16x32_bf16 v[34:37], v[218:221], v[172:175], v[34:37]
	v_mfma_f32_16x16x32_bf16 v[62:65], v[184:187], v[168:171], v[62:65]
	v_mfma_f32_16x16x32_bf16 v[58:61], v[184:187], v[176:179], v[58:61]
	v_mfma_f32_16x16x32_bf16 v[54:57], v[192:195], v[168:171], v[54:57]
	v_mfma_f32_16x16x32_bf16 v[50:53], v[192:195], v[176:179], v[50:53]
	v_mfma_f32_16x16x32_bf16 v[46:49], v[214:217], v[168:171], v[46:49]
	v_mfma_f32_16x16x32_bf16 v[42:45], v[214:217], v[176:179], v[42:45]
	v_mfma_f32_16x16x32_bf16 v[38:41], v[222:225], v[168:171], v[38:41]
	v_mfma_f32_16x16x32_bf16 v[34:37], v[222:225], v[176:179], v[34:37]
	s_nop 0
	s_barrier
	s_add_u32 s29, s6, s12
	s_addc_u32 s30, s7, s13
	s_add_u32 s24, s29, 0x100
	s_addc_u32 s25, s30, 0
	v_readfirstlane_b32 s31, v148
	s_mov_b32 m0, s31
	v_lshl_add_u64 v[164:165], s[24:25], 0, v[136:137]
	global_load_lds_dwordx4 v[164:165], off
	v_lshl_add_u64 v[164:165], s[24:25], 0, v[138:139]
	v_readfirstlane_b32 s24, v149
	s_mov_b32 m0, s24
	s_nop 0
	global_load_lds_dwordx4 v[164:165], off
	s_waitcnt vmcnt(6)
	s_barrier
	s_nop 0
	v_mfma_f32_16x16x32_bf16 v[30:33], v[180:183], v[226:229], v[30:33]
	v_mfma_f32_16x16x32_bf16 v[26:29], v[180:183], v[234:237], v[26:29]
	v_mfma_f32_16x16x32_bf16 v[22:25], v[188:191], v[226:229], v[22:25]
	v_mfma_f32_16x16x32_bf16 v[18:21], v[188:191], v[234:237], v[18:21]
	v_mfma_f32_16x16x32_bf16 v[14:17], v[196:199], v[226:229], v[14:17]
	v_mfma_f32_16x16x32_bf16 v[10:13], v[196:199], v[234:237], v[10:13]
	v_mfma_f32_16x16x32_bf16 v[6:9], v[218:221], v[226:229], v[6:9]
	v_mfma_f32_16x16x32_bf16 v[2:5], v[218:221], v[234:237], v[2:5]
	v_mfma_f32_16x16x32_bf16 v[30:33], v[184:187], v[230:233], v[30:33]
	v_mfma_f32_16x16x32_bf16 v[26:29], v[184:187], v[238:241], v[26:29]
	v_mfma_f32_16x16x32_bf16 v[22:25], v[192:195], v[230:233], v[22:25]
	v_mfma_f32_16x16x32_bf16 v[18:21], v[192:195], v[238:241], v[18:21]
	v_mfma_f32_16x16x32_bf16 v[14:17], v[214:217], v[230:233], v[14:17]
	v_mfma_f32_16x16x32_bf16 v[10:13], v[214:217], v[238:241], v[10:13]
	v_mfma_f32_16x16x32_bf16 v[6:9], v[222:225], v[230:233], v[6:9]
	v_mfma_f32_16x16x32_bf16 v[2:5], v[222:225], v[238:241], v[2:5]
	s_nop 0
	s_barrier
; #define STAGE(P, BASE, br, kt) do { const bf16_t* _gb = (BASE) + (long)(br) * K + (long)(kt) * 64; asm volatile("" : "+s"(_gb)); \
;     __builtin_amdgcn_global_load_lds((const unsigned*)(_gb + go0), (lds_u32*)((char*)(P) + tid * 16), 16, 0, 0); \
;     __builtin_amdgcn_global_load_lds((const unsigned*)(_gb + go1), (lds_u32*)((char*)(P) + tid * 16 + 8192), 16, 0, 0); } while (0)
; #define LDA(dst, b, h) _Pragma("unroll") for (int m = 0; m < 4; ++m) _Pragma("unroll") for (int k = 0; k < 2; ++k) \
;     dst[m][k] = *(const __attribute__((address_space(3))) bf16x8*)(aB + (((b) * 2 + (h)) * 16384 + m * 2048 + k * 1024))
; #define LDB(dst, b, h) _Pragma("unroll") for (int n = 0; n < 2; ++n) _Pragma("unroll") for (int k = 0; k < 2; ++k) \
;     dst[n][k] = *(const __attribute__((address_space(3))) bf16x8*)(bB + (((b) * 2 + (h)) * 16384 + n * 2048 + k * 1024))
; #define MMA(ai, bj, At, Bq) do { __builtin_amdgcn_s_setprio(1); \
;     _Pragma("unroll") for (int m = 0; m < 4; ++m) _Pragma("unroll") for (int n = 0; n < 2; ++n) _Pragma("unroll") for (int k = 0; k < 2; ++k) \
;       acc[ai][bj][m][n] = __builtin_amdgcn_mfma_f32_16x16x32_bf16(At[m][k], Bq[n][k], acc[ai][bj][m][n], 0, 0, 0); \
;     __builtin_amdgcn_s_setprio(0); } while (0)
; #define WAIT_L(n) asm volatile("s_waitcnt lgkmcnt(" #n ")" ::: "memory")
; #define BAR __builtin_amdgcn_s_barrier()
; #define SCHED __builtin_amdgcn_sched_barrier(0)
; template <int MODE>
; DI void gemm_tile(const Params& p, const bf16_t* __restrict__ A, const bf16_t* __restrict__ Bt, int K, int brow, int bcol, int mp, int nt, bool vt, char* smem) {
;     ...
;     LDB(B0, 1, 0); SCHED; LDA(At, 1, 0); STAGE(SA(0, 1), A, brow + 128, t + 2);
;     WAIT_L(8); BAR; WAIT_L(0); MMA(0, 0, At, B0); BAR; SCHED;
;     LDB(B1, 1, 1); STAGE(SB(1, 0), Bt, bcol, t + 3);
;     BAR; WAIT_L(0); MMA(0, 1, At, B1); BAR;
;     LDA(At, 1, 1); STAGE(SA(1, 0), A, brow, t + 3);
;     BAR; WAIT_L(0); MMA(1, 0, At, B0); BAR; SCHED;
.Lgemm3_p5:
	s_nop 0
	ds_read_b128 v[164:167], v147 offset:32768
	ds_read_b128 v[168:171], v147 offset:33792
	ds_read_b128 v[172:175], v147 offset:34816
	ds_read_b128 v[176:179], v147 offset:35840
	s_add_u32 s24, s1, s12
	s_addc_u32 s25, s14, s13
	v_readfirstlane_b32 s31, v150
	ds_read_b128 v[180:183], v145 offset:32768
	ds_read_b128 v[184:187], v145 offset:33792
	ds_read_b128 v[188:191], v145 offset:34816
	ds_read_b128 v[192:195], v145 offset:35840
	ds_read_b128 v[196:199], v145 offset:36864
	ds_read_b128 v[214:217], v145 offset:37888
	ds_read_b128 v[218:221], v145 offset:38912
	ds_read_b128 v[222:225], v145 offset:39936
	s_mov_b32 m0, s31
	v_lshl_add_u64 v[226:227], s[24:25], 0, v[136:137]
	global_load_lds_dwordx4 v[226:227], off
	v_lshl_add_u64 v[226:227], s[24:25], 0, v[138:139]
	v_readfirstlane_b32 s24, v151
	s_mov_b32 m0, s24
	s_nop 0
	global_load_lds_dwordx4 v[226:227], off
	s_waitcnt lgkmcnt(8)
	s_barrier
	s_waitcnt lgkmcnt(0)
	s_nop 0
	s_waitcnt lgkmcnt(0)
	v_mfma_f32_16x16x32_bf16 v[126:129], v[180:183], v[164:167], v[126:129]
	v_mfma_f32_16x16x32_bf16 v[122:125], v[180:183], v[172:175], v[122:125]
	v_mfma_f32_16x16x32_bf16 v[118:121], v[188:191], v[164:167], v[118:121]
	v_mfma_f32_16x16x32_bf16 v[114:117], v[188:191], v[172:175], v[114:117]
	v_mfma_f32_16x16x32_bf16 v[110:113], v[196:199], v[164:167], v[110:113]
	v_mfma_f32_16x16x32_bf16 v[106:109], v[196:199], v[172:175], v[106:109]
	v_mfma_f32_16x16x32_bf16 v[102:105], v[218:221], v[164:167], v[102:105]
	v_mfma_f32_16x16x32_bf16 v[98:101], v[218:221], v[172:175], v[98:101]
	v_mfma_f32_16x16x32_bf16 v[126:129], v[184:187], v[168:171], v[126:129]
	v_mfma_f32_16x16x32_bf16 v[122:125], v[184:187], v[176:179], v[122:125]
	v_mfma_f32_16x16x32_bf16 v[118:121], v[192:195], v[168:171], v[118:121]
	v_mfma_f32_16x16x32_bf16 v[114:117], v[192:195], v[176:179], v[114:117]
	v_mfma_f32_16x16x32_bf16 v[110:113], v[214:217], v[168:171], v[110:113]
	v_mfma_f32_16x16x32_bf16 v[106:109], v[214:217], v[176:179], v[106:109]
	v_mfma_f32_16x16x32_bf16 v[102:105], v[222:225], v[168:171], v[102:105]
	v_mfma_f32_16x16x32_bf16 v[98:101], v[222:225], v[176:179], v[98:101]
	s_nop 0
	s_barrier
	s_add_u32 s24, s23, 0x180
	s_addc_u32 s25, s26, 0
	v_readfirstlane_b32 s23, v156
	s_nop 0
	ds_read_b128 v[226:229], v147 offset:49152
	ds_read_b128 v[230:233], v147 offset:50176
	ds_read_b128 v[234:237], v147 offset:51200
	ds_read_b128 v[238:241], v147 offset:52224
	s_mov_b32 m0, s23
	v_lshl_add_u64 v[242:243], s[24:25], 0, v[136:137]
	v_readfirstlane_b32 s23, v157
	global_load_lds_dwordx4 v[242:243], off
	v_lshl_add_u64 v[242:243], s[24:25], 0, v[138:139]
	s_mov_b32 m0, s23
	s_nop 0
	global_load_lds_dwordx4 v[242:243], off
	s_barrier
	s_waitcnt lgkmcnt(0)
	s_nop 0
	s_waitcnt lgkmcnt(0)
	v_mfma_f32_16x16x32_bf16 v[94:97], v[180:183], v[226:229], v[94:97]
	v_mfma_f32_16x16x32_bf16 v[90:93], v[180:183], v[234:237], v[90:93]
	v_mfma_f32_16x16x32_bf16 v[86:89], v[188:191], v[226:229], v[86:89]
	v_mfma_f32_16x16x32_bf16 v[82:85], v[188:191], v[234:237], v[82:85]
	v_mfma_f32_16x16x32_bf16 v[78:81], v[196:199], v[226:229], v[78:81]
	v_mfma_f32_16x16x32_bf16 v[74:77], v[196:199], v[234:237], v[74:77]
	v_mfma_f32_16x16x32_bf16 v[70:73], v[218:221], v[226:229], v[70:73]
	v_mfma_f32_16x16x32_bf16 v[66:69], v[218:221], v[234:237], v[66:69]
	v_mfma_f32_16x16x32_bf16 v[94:97], v[184:187], v[230:233], v[94:97]
	v_mfma_f32_16x16x32_bf16 v[90:93], v[184:187], v[238:241], v[90:93]
	v_mfma_f32_16x16x32_bf16 v[86:89], v[192:195], v[230:233], v[86:89]
	v_mfma_f32_16x16x32_bf16 v[82:85], v[192:195], v[238:241], v[82:85]
	v_mfma_f32_16x16x32_bf16 v[78:81], v[214:217], v[230:233], v[78:81]
	v_mfma_f32_16x16x32_bf16 v[74:77], v[214:217], v[238:241], v[74:77]
	v_mfma_f32_16x16x32_bf16 v[70:73], v[222:225], v[230:233], v[70:73]
	v_mfma_f32_16x16x32_bf16 v[66:69], v[222:225], v[238:241], v[66:69]
	s_nop 0
	s_add_u32 s24, s27, 0x180
	s_addc_u32 s25, s28, 0
	v_readfirstlane_b32 s23, v158
	s_barrier
	s_nop 0
	ds_read_b128 v[180:183], v145 offset:49152
	ds_read_b128 v[184:187], v145 offset:50176
	ds_read_b128 v[188:191], v145 offset:51200
	ds_read_b128 v[192:195], v145 offset:52224
	ds_read_b128 v[196:199], v145 offset:53248
	ds_read_b128 v[214:217], v145 offset:54272
	ds_read_b128 v[218:221], v145 offset:55296
	ds_read_b128 v[222:225], v145 offset:56320
	s_mov_b32 m0, s23
	v_lshl_add_u64 v[242:243], s[24:25], 0, v[136:137]
	v_readfirstlane_b32 s23, v159
	global_load_lds_dwordx4 v[242:243], off
	v_lshl_add_u64 v[242:243], s[24:25], 0, v[138:139]
	s_mov_b32 m0, s23
	s_nop 0
	global_load_lds_dwordx4 v[242:243], off
	s_barrier
	s_waitcnt lgkmcnt(0)
	s_nop 0
	s_waitcnt lgkmcnt(0)
	v_mfma_f32_16x16x32_bf16 v[62:65], v[180:183], v[164:167], v[62:65]
	v_mfma_f32_16x16x32_bf16 v[58:61], v[180:183], v[172:175], v[58:61]
	v_mfma_f32_16x16x32_bf16 v[54:57], v[188:191], v[164:167], v[54:57]
	v_mfma_f32_16x16x32_bf16 v[50:53], v[188:191], v[172:175], v[50:53]
	v_mfma_f32_16x16x32_bf16 v[46:49], v[196:199], v[164:167], v[46:49]
	v_mfma_f32_16x16x32_bf16 v[42:45], v[196:199], v[172:175], v[42:45]
	v_mfma_f32_16x16x32_bf16 v[38:41], v[218:221], v[164:167], v[38:41]
	v_mfma_f32_16x16x32_bf16 v[34:37], v[218:221], v[172:175], v[34:37]
	v_mfma_f32_16x16x32_bf16 v[62:65], v[184:187], v[168:171], v[62:65]
	v_mfma_f32_16x16x32_bf16 v[58:61], v[184:187], v[176:179], v[58:61]
	v_mfma_f32_16x16x32_bf16 v[54:57], v[192:195], v[168:171], v[54:57]
	v_mfma_f32_16x16x32_bf16 v[50:53], v[192:195], v[176:179], v[50:53]
	v_mfma_f32_16x16x32_bf16 v[46:49], v[214:217], v[168:171], v[46:49]
	v_mfma_f32_16x16x32_bf16 v[42:45], v[214:217], v[176:179], v[42:45]
	v_mfma_f32_16x16x32_bf16 v[38:41], v[222:225], v[168:171], v[38:41]
	v_mfma_f32_16x16x32_bf16 v[34:37], v[222:225], v[176:179], v[34:37]
	s_nop 0
	s_barrier
; #define STAGE(P, BASE, br, kt) do { const bf16_t* _gb = (BASE) + (long)(br) * K + (long)(kt) * 64; asm volatile("" : "+s"(_gb)); \
;     __builtin_amdgcn_global_load_lds((const unsigned*)(_gb + go0), (lds_u32*)((char*)(P) + tid * 16), 16, 0, 0); \
;     __builtin_amdgcn_global_load_lds((const unsigned*)(_gb + go1), (lds_u32*)((char*)(P) + tid * 16 + 8192), 16, 0, 0); } while (0)
; #define LDA(dst, b, h) _Pragma("unroll") for (int m = 0; m < 4; ++m) _Pragma("unroll") for (int k = 0; k < 2; ++k) \
;     dst[m][k] = *(const __attribute__((address_space(3))) bf16x8*)(aB + (((b) * 2 + (h)) * 16384 + m * 2048 + k * 1024))
; #define LDB(dst, b, h) _Pragma("unroll") for (int n = 0; n < 2; ++n) _Pragma("unroll") for (int k = 0; k < 2; ++k) \
;     dst[n][k] = *(const __attribute__((address_space(3))) bf16x8*)(bB + (((b) * 2 + (h)) * 16384 + n * 2048 + k * 1024))
; #define MMA(ai, bj, At, Bq) do { __builtin_amdgcn_s_setprio(1); \
;     _Pragma("unroll") for (int m = 0; m < 4; ++m) _Pragma("unroll") for (int n = 0; n < 2; ++n) _Pragma("unroll") for (int k = 0; k < 2; ++k) \
;       acc[ai][bj][m][n] = __builtin_amdgcn_mfma_f32_16x16x32_bf16(At[m][k], Bq[n][k], acc[ai][bj][m][n], 0, 0, 0); \
;     __builtin_amdgcn_s_setprio(0); } while (0)
; #define WAIT_V(n) asm volatile("s_waitcnt vmcnt(" #n ")" ::: "memory")
; #define WAIT_L(n) asm volatile("s_waitcnt lgkmcnt(" #n ")" ::: "memory")
; #define BAR __builtin_amdgcn_s_barrier()
; template <int MODE>
; DI void gemm_tile(const Params& p, const bf16_t* __restrict__ A, const bf16_t* __restrict__ Bt, int K, int brow, int bcol, int mp, int nt, bool vt, char* smem) {
;     ...
;     STAGE(SB(1, 1), Bt, bcol + 128, t + 3);
;     WAIT_V(6); BAR; MMA(1, 1, At, B1); BAR;
;   }
;   { LDB(B0, 0, 0); LDA(At, 0, 0); STAGE(SA(1, 1), A, brow + 128, ntk - 1);
;     BAR; WAIT_L(0); MMA(0, 0, At, B0); BAR;
;     LDB(B1, 0, 1); BAR; WAIT_L(0); MMA(0, 1, At, B1); BAR;
;     LDA(At, 0, 1); WAIT_V(4); BAR; WAIT_L(0); MMA(1, 0, At, B0); MMA(1, 1, At, B1); BAR; }
	s_add_u32 s24, s29, 0x180
	s_addc_u32 s25, s30, 0
	v_readfirstlane_b32 s23, v160
	s_mov_b32 m0, s23
	v_lshl_add_u64 v[164:165], s[24:25], 0, v[136:137]
	v_readfirstlane_b32 s23, v161
	global_load_lds_dwordx4 v[164:165], off
	v_lshl_add_u64 v[164:165], s[24:25], 0, v[138:139]
	s_mov_b32 m0, s23
	s_nop 0
	global_load_lds_dwordx4 v[164:165], off
	s_waitcnt vmcnt(6)
	s_barrier
	s_nop 0
	v_mfma_f32_16x16x32_bf16 v[30:33], v[180:183], v[226:229], v[30:33]
	v_mfma_f32_16x16x32_bf16 v[26:29], v[180:183], v[234:237], v[26:29]
	v_mfma_f32_16x16x32_bf16 v[22:25], v[188:191], v[226:229], v[22:25]
	v_mfma_f32_16x16x32_bf16 v[18:21], v[188:191], v[234:237], v[18:21]
	v_mfma_f32_16x16x32_bf16 v[14:17], v[196:199], v[226:229], v[14:17]
	v_mfma_f32_16x16x32_bf16 v[10:13], v[196:199], v[234:237], v[10:13]
	v_mfma_f32_16x16x32_bf16 v[6:9], v[218:221], v[226:229], v[6:9]
	v_mfma_f32_16x16x32_bf16 v[2:5], v[218:221], v[234:237], v[2:5]
	v_mfma_f32_16x16x32_bf16 v[30:33], v[184:187], v[230:233], v[30:33]
	v_mfma_f32_16x16x32_bf16 v[26:29], v[184:187], v[238:241], v[26:29]
	v_mfma_f32_16x16x32_bf16 v[22:25], v[192:195], v[230:233], v[22:25]
	v_mfma_f32_16x16x32_bf16 v[18:21], v[192:195], v[238:241], v[18:21]
	v_mfma_f32_16x16x32_bf16 v[14:17], v[214:217], v[230:233], v[14:17]
	v_mfma_f32_16x16x32_bf16 v[10:13], v[214:217], v[238:241], v[10:13]
	v_mfma_f32_16x16x32_bf16 v[6:9], v[222:225], v[230:233], v[6:9]
	v_mfma_f32_16x16x32_bf16 v[2:5], v[222:225], v[238:241], v[2:5]
	s_nop 0
	s_add_i32 s22, s22, 2
	s_add_u32 s12, s12, 0x100
	s_addc_u32 s13, s13, 0
	s_cmp_lt_u32 s22, 12
	s_barrier
	s_cbranch_scc1 .LBB0_587
	s_add_u32 s2, s10, 0x780
	s_addc_u32 s3, s11, 0
	v_readfirstlane_b32 s1, v162
	s_nop 0
	ds_read_b128 v[136:139], v147
	ds_read_b128 v[148:151], v147 offset:1024
	ds_read_b128 v[156:159], v147 offset:2048
	ds_read_b128 v[164:167], v147 offset:3072
	ds_read_b128 v[168:171], v145
	ds_read_b128 v[172:175], v145 offset:1024
	ds_read_b128 v[176:179], v145 offset:2048
	ds_read_b128 v[180:183], v145 offset:3072
	ds_read_b128 v[184:187], v145 offset:4096
	ds_read_b128 v[188:191], v145 offset:5120
	ds_read_b128 v[192:195], v145 offset:6144
	ds_read_b128 v[196:199], v145 offset:7168
	s_mov_b32 m0, s1
	v_lshl_add_u64 v[134:135], v[134:135], 1, s[2:3]
	v_readfirstlane_b32 s1, v163
	global_load_lds_dwordx4 v[134:135], off
	v_lshl_add_u64 v[132:133], v[132:133], 1, s[2:3]
	s_mov_b32 m0, s1
	s_nop 0
	global_load_lds_dwordx4 v[132:133], off
	s_barrier
	s_waitcnt lgkmcnt(0)
	s_nop 0
	s_waitcnt lgkmcnt(0)
	v_mfma_f32_16x16x32_bf16 v[126:129], v[168:171], v[136:139], v[126:129]
	v_mfma_f32_16x16x32_bf16 v[122:125], v[168:171], v[156:159], v[122:125]
	v_mfma_f32_16x16x32_bf16 v[118:121], v[176:179], v[136:139], v[118:121]
	v_mfma_f32_16x16x32_bf16 v[114:117], v[176:179], v[156:159], v[114:117]
	v_mfma_f32_16x16x32_bf16 v[126:129], v[172:175], v[148:151], v[126:129]
	v_mfma_f32_16x16x32_bf16 v[122:125], v[172:175], v[164:167], v[122:125]
	v_mfma_f32_16x16x32_bf16 v[118:121], v[180:183], v[148:151], v[118:121]
	v_mfma_f32_16x16x32_bf16 v[114:117], v[180:183], v[164:167], v[114:117]
	v_mfma_f32_16x16x32_bf16 v[110:113], v[184:187], v[136:139], v[110:113]
	v_mfma_f32_16x16x32_bf16 v[106:109], v[184:187], v[156:159], v[106:109]
	v_mfma_f32_16x16x32_bf16 v[102:105], v[192:195], v[136:139], v[102:105]
	v_mfma_f32_16x16x32_bf16 v[98:101], v[192:195], v[156:159], v[98:101]
	v_mfma_f32_16x16x32_bf16 v[132:135], v[188:191], v[148:151], v[110:113]
	v_mfma_f32_16x16x32_bf16 v[160:163], v[188:191], v[164:167], v[106:109]
	v_mfma_f32_16x16x32_bf16 v[214:217], v[196:199], v[148:151], v[102:105]
	v_mfma_f32_16x16x32_bf16 v[218:221], v[196:199], v[164:167], v[98:101]
	s_nop 0
	s_barrier
	s_nop 0
	s_nop 0
	ds_read_b128 v[98:101], v147 offset:16384
	ds_read_b128 v[102:105], v147 offset:17408
	ds_read_b128 v[106:109], v147 offset:18432
	ds_read_b128 v[110:113], v147 offset:19456
	s_barrier
	s_waitcnt lgkmcnt(0)
	s_nop 0
	s_waitcnt lgkmcnt(3)
	v_mfma_f32_16x16x32_bf16 v[94:97], v[168:171], v[98:101], v[94:97]
	s_waitcnt lgkmcnt(1)
	v_mfma_f32_16x16x32_bf16 v[90:93], v[168:171], v[106:109], v[90:93]
	v_mfma_f32_16x16x32_bf16 v[86:89], v[176:179], v[98:101], v[86:89]
	v_mfma_f32_16x16x32_bf16 v[82:85], v[176:179], v[106:109], v[82:85]
	v_mfma_f32_16x16x32_bf16 v[94:97], v[172:175], v[102:105], v[94:97]
	s_waitcnt lgkmcnt(0)
	v_mfma_f32_16x16x32_bf16 v[90:93], v[172:175], v[110:113], v[90:93]
	v_mfma_f32_16x16x32_bf16 v[86:89], v[180:183], v[102:105], v[86:89]
	v_mfma_f32_16x16x32_bf16 v[82:85], v[180:183], v[110:113], v[82:85]
	v_mfma_f32_16x16x32_bf16 v[78:81], v[184:187], v[98:101], v[78:81]
	v_mfma_f32_16x16x32_bf16 v[74:77], v[184:187], v[106:109], v[74:77]
	v_mfma_f32_16x16x32_bf16 v[70:73], v[192:195], v[98:101], v[70:73]
	v_mfma_f32_16x16x32_bf16 v[66:69], v[192:195], v[106:109], v[66:69]
	v_mfma_f32_16x16x32_bf16 v[168:171], v[188:191], v[102:105], v[78:81]
	v_mfma_f32_16x16x32_bf16 v[172:175], v[188:191], v[110:113], v[74:77]
	v_mfma_f32_16x16x32_bf16 v[176:179], v[196:199], v[102:105], v[70:73]
	v_mfma_f32_16x16x32_bf16 v[180:183], v[196:199], v[110:113], v[66:69]
	s_nop 0
	s_barrier
	s_nop 1
	ds_read_b128 v[66:69], v145 offset:16384
	ds_read_b128 v[70:73], v145 offset:17408
	ds_read_b128 v[74:77], v145 offset:18432
	ds_read_b128 v[78:81], v145 offset:19456
	ds_read_b128 v[184:187], v145 offset:20480
	ds_read_b128 v[188:191], v145 offset:21504
	ds_read_b128 v[192:195], v145 offset:22528
	ds_read_b128 v[196:199], v145 offset:23552
	s_waitcnt vmcnt(4)
	s_barrier
; #define LDA(dst, b, h) _Pragma("unroll") for (int m = 0; m < 4; ++m) _Pragma("unroll") for (int k = 0; k < 2; ++k) \
;     dst[m][k] = *(const __attribute__((address_space(3))) bf16x8*)(aB + (((b) * 2 + (h)) * 16384 + m * 2048 + k * 1024))
; #define LDB(dst, b, h) _Pragma("unroll") for (int n = 0; n < 2; ++n) _Pragma("unroll") for (int k = 0; k < 2; ++k) \
;     dst[n][k] = *(const __attribute__((address_space(3))) bf16x8*)(bB + (((b) * 2 + (h)) * 16384 + n * 2048 + k * 1024))
; #define MMA(ai, bj, At, Bq) do { __builtin_amdgcn_s_setprio(1); \
;     _Pragma("unroll") for (int m = 0; m < 4; ++m) _Pragma("unroll") for (int n = 0; n < 2; ++n) _Pragma("unroll") for (int k = 0; k < 2; ++k) \
;       acc[ai][bj][m][n] = __builtin_amdgcn_mfma_f32_16x16x32_bf16(At[m][k], Bq[n][k], acc[ai][bj][m][n], 0, 0, 0); \
;     __builtin_amdgcn_s_setprio(0); } while (0)
; #define WAIT_V(n) asm volatile("s_waitcnt vmcnt(" #n ")" ::: "memory")
; #define WAIT_L(n) asm volatile("s_waitcnt lgkmcnt(" #n ")" ::: "memory")
; #define BAR __builtin_amdgcn_s_barrier()
; template <int MODE>
; DI void gemm_tile(const Params& p, const bf16_t* __restrict__ A, const bf16_t* __restrict__ Bt, int K, int brow, int bcol, int mp, int nt, bool vt, char* smem) {
;     ...
;     LDA(At, 0, 1); WAIT_V(4); BAR; WAIT_L(0); MMA(1, 0, At, B0); MMA(1, 1, At, B1); BAR; }
;   { LDB(B0, 1, 0); LDA(At, 1, 0); WAIT_V(2); BAR; WAIT_L(0); MMA(0, 0, At, B0); BAR;
	s_waitcnt lgkmcnt(0)
	s_nop 0
	s_waitcnt lgkmcnt(7)
	v_mfma_f32_16x16x32_bf16 v[62:65], v[66:69], v[136:139], v[62:65]
	v_mfma_f32_16x16x32_bf16 v[58:61], v[66:69], v[156:159], v[58:61]
	s_waitcnt lgkmcnt(5)
	v_mfma_f32_16x16x32_bf16 v[54:57], v[74:77], v[136:139], v[54:57]
	v_mfma_f32_16x16x32_bf16 v[50:53], v[74:77], v[156:159], v[50:53]
	v_mfma_f32_16x16x32_bf16 v[62:65], v[70:73], v[148:151], v[62:65]
	v_mfma_f32_16x16x32_bf16 v[58:61], v[70:73], v[164:167], v[58:61]
	s_waitcnt lgkmcnt(4)
	v_mfma_f32_16x16x32_bf16 v[54:57], v[78:81], v[148:151], v[54:57]
	v_mfma_f32_16x16x32_bf16 v[50:53], v[78:81], v[164:167], v[50:53]
	s_waitcnt lgkmcnt(3)
	v_mfma_f32_16x16x32_bf16 v[46:49], v[184:187], v[136:139], v[46:49]
	v_mfma_f32_16x16x32_bf16 v[42:45], v[184:187], v[156:159], v[42:45]
	s_waitcnt lgkmcnt(1)
	v_mfma_f32_16x16x32_bf16 v[38:41], v[192:195], v[136:139], v[38:41]
	v_mfma_f32_16x16x32_bf16 v[34:37], v[192:195], v[156:159], v[34:37]
	v_mfma_f32_16x16x32_bf16 v[222:225], v[188:191], v[148:151], v[46:49]
	v_mfma_f32_16x16x32_bf16 v[226:229], v[188:191], v[164:167], v[42:45]
	s_waitcnt lgkmcnt(0)
	v_mfma_f32_16x16x32_bf16 v[136:139], v[196:199], v[148:151], v[38:41]
	v_mfma_f32_16x16x32_bf16 v[148:151], v[196:199], v[164:167], v[34:37]
	s_nop 0
	s_nop 0
	v_mfma_f32_16x16x32_bf16 v[30:33], v[66:69], v[98:101], v[30:33]
	v_mfma_f32_16x16x32_bf16 v[26:29], v[66:69], v[106:109], v[26:29]
	v_mfma_f32_16x16x32_bf16 v[22:25], v[74:77], v[98:101], v[22:25]
	v_mfma_f32_16x16x32_bf16 v[18:21], v[74:77], v[106:109], v[18:21]
	v_mfma_f32_16x16x32_bf16 v[30:33], v[70:73], v[102:105], v[30:33]
	v_mfma_f32_16x16x32_bf16 v[26:29], v[70:73], v[110:113], v[26:29]
	v_mfma_f32_16x16x32_bf16 v[22:25], v[78:81], v[102:105], v[22:25]
	v_mfma_f32_16x16x32_bf16 v[18:21], v[78:81], v[110:113], v[18:21]
	v_mfma_f32_16x16x32_bf16 v[14:17], v[184:187], v[98:101], v[14:17]
	v_mfma_f32_16x16x32_bf16 v[10:13], v[184:187], v[106:109], v[10:13]
	v_mfma_f32_16x16x32_bf16 v[6:9], v[192:195], v[98:101], v[6:9]
	v_mfma_f32_16x16x32_bf16 v[2:5], v[192:195], v[106:109], v[2:5]
	v_mfma_f32_16x16x32_bf16 v[156:159], v[188:191], v[102:105], v[14:17]
	v_mfma_f32_16x16x32_bf16 v[164:167], v[188:191], v[110:113], v[10:13]
	v_mfma_f32_16x16x32_bf16 v[184:187], v[196:199], v[102:105], v[6:9]
	v_mfma_f32_16x16x32_bf16 v[188:191], v[196:199], v[110:113], v[2:5]
	s_nop 0
	s_barrier
	s_nop 1
	ds_read_b128 v[2:5], v147 offset:32768
	ds_read_b128 v[6:9], v147 offset:33792
	ds_read_b128 v[10:13], v147 offset:34816
	ds_read_b128 v[14:17], v147 offset:35840
	ds_read_b128 v[34:37], v145 offset:32768
	ds_read_b128 v[38:41], v145 offset:33792
	ds_read_b128 v[42:45], v145 offset:34816
	ds_read_b128 v[46:49], v145 offset:35840
	ds_read_b128 v[192:195], v145 offset:36864
	ds_read_b128 v[196:199], v145 offset:37888
	ds_read_b128 v[230:233], v145 offset:38912
	ds_read_b128 v[234:237], v145 offset:39936
	s_waitcnt vmcnt(2)
	s_barrier
	s_waitcnt lgkmcnt(0)
	s_nop 0
	s_waitcnt lgkmcnt(7)
	v_mfma_f32_16x16x32_bf16 v[66:69], v[34:37], v[2:5], v[126:129]
	s_waitcnt lgkmcnt(6)
	v_mfma_f32_16x16x32_bf16 v[98:101], v[38:41], v[6:9], v[66:69]
	v_mfma_f32_16x16x32_bf16 v[66:69], v[34:37], v[10:13], v[122:125]
	v_mfma_f32_16x16x32_bf16 v[102:105], v[38:41], v[14:17], v[66:69]
	s_waitcnt lgkmcnt(5)
	v_mfma_f32_16x16x32_bf16 v[66:69], v[42:45], v[2:5], v[118:121]
	s_waitcnt lgkmcnt(4)
	v_mfma_f32_16x16x32_bf16 v[106:109], v[46:49], v[6:9], v[66:69]
	v_mfma_f32_16x16x32_bf16 v[66:69], v[42:45], v[10:13], v[114:117]
	v_mfma_f32_16x16x32_bf16 v[110:113], v[46:49], v[14:17], v[66:69]
	s_waitcnt lgkmcnt(3)
	v_mfma_f32_16x16x32_bf16 v[66:69], v[192:195], v[2:5], v[132:135]
	s_waitcnt lgkmcnt(2)
	v_mfma_f32_16x16x32_bf16 v[114:117], v[196:199], v[6:9], v[66:69]
	v_mfma_f32_16x16x32_bf16 v[66:69], v[192:195], v[10:13], v[160:163]
	v_mfma_f32_16x16x32_bf16 v[118:121], v[196:199], v[14:17], v[66:69]
	s_waitcnt lgkmcnt(1)
	v_mfma_f32_16x16x32_bf16 v[66:69], v[230:233], v[2:5], v[214:217]
	s_waitcnt lgkmcnt(0)
	v_mfma_f32_16x16x32_bf16 v[122:125], v[234:237], v[6:9], v[66:69]
	v_mfma_f32_16x16x32_bf16 v[66:69], v[230:233], v[10:13], v[218:221]
	v_mfma_f32_16x16x32_bf16 v[126:129], v[234:237], v[14:17], v[66:69]
	s_nop 0
	s_barrier
; #define LDA(dst, b, h) _Pragma("unroll") for (int m = 0; m < 4; ++m) _Pragma("unroll") for (int k = 0; k < 2; ++k) \
;     dst[m][k] = *(const __attribute__((address_space(3))) bf16x8*)(aB + (((b) * 2 + (h)) * 16384 + m * 2048 + k * 1024))
; #define LDB(dst, b, h) _Pragma("unroll") for (int n = 0; n < 2; ++n) _Pragma("unroll") for (int k = 0; k < 2; ++k) \
;     dst[n][k] = *(const __attribute__((address_space(3))) bf16x8*)(bB + (((b) * 2 + (h)) * 16384 + n * 2048 + k * 1024))
; #define MMA(ai, bj, At, Bq) do { __builtin_amdgcn_s_setprio(1); \
;     _Pragma("unroll") for (int m = 0; m < 4; ++m) _Pragma("unroll") for (int n = 0; n < 2; ++n) _Pragma("unroll") for (int k = 0; k < 2; ++k) \
;       acc[ai][bj][m][n] = __builtin_amdgcn_mfma_f32_16x16x32_bf16(At[m][k], Bq[n][k], acc[ai][bj][m][n], 0, 0, 0); \
;     __builtin_amdgcn_s_setprio(0); } while (0)
; #define WAIT_V(n) asm volatile("s_waitcnt vmcnt(" #n ")" ::: "memory")
; #define WAIT_L(n) asm volatile("s_waitcnt lgkmcnt(" #n ")" ::: "memory")
; #define BAR __builtin_amdgcn_s_barrier()
; template <int MODE>
; DI void gemm_tile(const Params& p, const bf16_t* __restrict__ A, const bf16_t* __restrict__ Bt, int K, int brow, int bcol, int mp, int nt, bool vt, char* smem) {
;     ...
;   { LDB(B0, 1, 0); LDA(At, 1, 0); WAIT_V(2); BAR; WAIT_L(0); MMA(0, 0, At, B0); BAR;
;     LDB(B1, 1, 1); WAIT_V(0); BAR; WAIT_L(0); MMA(0, 1, At, B1); BAR;
;     LDA(At, 1, 1); BAR; WAIT_L(0); MMA(1, 0, At, B0); MMA(1, 1, At, B1); BAR; }
;   if (wr == 0) BAR;
	ds_read_b128 v[132:135], v147 offset:49152
	ds_read_b128 v[160:163], v147 offset:50176
	ds_read_b128 v[214:217], v147 offset:51200
	ds_read_b128 v[218:221], v147 offset:52224
	s_waitcnt vmcnt(0)
	s_barrier
	s_waitcnt lgkmcnt(0)
	s_nop 0
	s_waitcnt lgkmcnt(3)
	v_mfma_f32_16x16x32_bf16 v[66:69], v[34:37], v[132:135], v[94:97]
	s_waitcnt lgkmcnt(1)
	v_mfma_f32_16x16x32_bf16 v[34:37], v[34:37], v[214:217], v[90:93]
	s_waitcnt lgkmcnt(0)
	v_mfma_f32_16x16x32_bf16 v[70:73], v[38:41], v[218:221], v[34:37]
	v_mfma_f32_16x16x32_bf16 v[34:37], v[42:45], v[132:135], v[86:89]
	v_mfma_f32_16x16x32_bf16 v[74:77], v[46:49], v[160:163], v[34:37]
	v_mfma_f32_16x16x32_bf16 v[34:37], v[42:45], v[214:217], v[82:85]
	v_mfma_f32_16x16x32_bf16 v[78:81], v[46:49], v[218:221], v[34:37]
	v_mfma_f32_16x16x32_bf16 v[34:37], v[192:195], v[132:135], v[168:171]
	v_mfma_f32_16x16x32_bf16 v[82:85], v[196:199], v[160:163], v[34:37]
	v_mfma_f32_16x16x32_bf16 v[34:37], v[192:195], v[214:217], v[172:175]
	v_mfma_f32_16x16x32_bf16 v[86:89], v[196:199], v[218:221], v[34:37]
	v_mfma_f32_16x16x32_bf16 v[34:37], v[230:233], v[132:135], v[176:179]
	v_mfma_f32_16x16x32_bf16 v[90:93], v[234:237], v[160:163], v[34:37]
	v_mfma_f32_16x16x32_bf16 v[34:37], v[230:233], v[214:217], v[180:183]
	v_mfma_f32_16x16x32_bf16 v[66:69], v[38:41], v[160:163], v[66:69]
	v_mfma_f32_16x16x32_bf16 v[94:97], v[234:237], v[218:221], v[34:37]
	s_nop 0
	s_barrier
	ds_read_b128 v[168:171], v145 offset:49152
	ds_read_b128 v[172:175], v145 offset:50176
	ds_read_b128 v[176:179], v145 offset:51200
	ds_read_b128 v[180:183], v145 offset:52224
	ds_read_b128 v[192:195], v145 offset:53248
	ds_read_b128 v[196:199], v145 offset:54272
	ds_read_b128 v[230:233], v145 offset:55296
	ds_read_b128 v[144:147], v145 offset:56320
	s_barrier
	s_waitcnt lgkmcnt(0)
	s_nop 0
	s_waitcnt lgkmcnt(7)
	v_mfma_f32_16x16x32_bf16 v[34:37], v[168:171], v[2:5], v[62:65]
	s_waitcnt lgkmcnt(5)
	v_mfma_f32_16x16x32_bf16 v[42:45], v[176:179], v[2:5], v[54:57]
	v_mfma_f32_16x16x32_bf16 v[46:49], v[176:179], v[10:13], v[50:53]
	s_waitcnt lgkmcnt(3)
	v_mfma_f32_16x16x32_bf16 v[50:53], v[192:195], v[2:5], v[222:225]
	s_waitcnt lgkmcnt(1)
	v_mfma_f32_16x16x32_bf16 v[2:5], v[230:233], v[2:5], v[136:139]
	v_mfma_f32_16x16x32_bf16 v[38:41], v[168:171], v[10:13], v[58:61]
	v_mfma_f32_16x16x32_bf16 v[54:57], v[192:195], v[10:13], v[226:229]
	s_waitcnt lgkmcnt(0)
	v_mfma_f32_16x16x32_bf16 v[58:61], v[144:147], v[6:9], v[2:5]
	v_mfma_f32_16x16x32_bf16 v[2:5], v[230:233], v[10:13], v[148:151]
	v_mfma_f32_16x16x32_bf16 v[34:37], v[172:175], v[6:9], v[34:37]
	v_mfma_f32_16x16x32_bf16 v[38:41], v[172:175], v[14:17], v[38:41]
	v_mfma_f32_16x16x32_bf16 v[42:45], v[180:183], v[6:9], v[42:45]
	v_mfma_f32_16x16x32_bf16 v[46:49], v[180:183], v[14:17], v[46:49]
	v_mfma_f32_16x16x32_bf16 v[50:53], v[196:199], v[6:9], v[50:53]
	v_mfma_f32_16x16x32_bf16 v[54:57], v[196:199], v[14:17], v[54:57]
	v_mfma_f32_16x16x32_bf16 v[62:65], v[144:147], v[14:17], v[2:5]
	s_nop 0
	s_nop 0
	v_mfma_f32_16x16x32_bf16 v[2:5], v[168:171], v[132:135], v[30:33]
	v_mfma_f32_16x16x32_bf16 v[6:9], v[168:171], v[214:217], v[26:29]
	v_mfma_f32_16x16x32_bf16 v[10:13], v[176:179], v[132:135], v[22:25]
	v_mfma_f32_16x16x32_bf16 v[14:17], v[176:179], v[214:217], v[18:21]
	v_mfma_f32_16x16x32_bf16 v[18:21], v[192:195], v[132:135], v[156:159]
	v_mfma_f32_16x16x32_bf16 v[22:25], v[192:195], v[214:217], v[164:167]
	v_mfma_f32_16x16x32_bf16 v[26:29], v[230:233], v[132:135], v[184:187]
	v_mfma_f32_16x16x32_bf16 v[30:33], v[230:233], v[214:217], v[188:191]
	v_mfma_f32_16x16x32_bf16 v[2:5], v[172:175], v[160:163], v[2:5]
	v_mfma_f32_16x16x32_bf16 v[6:9], v[172:175], v[218:221], v[6:9]
	v_mfma_f32_16x16x32_bf16 v[10:13], v[180:183], v[160:163], v[10:13]
	v_mfma_f32_16x16x32_bf16 v[14:17], v[180:183], v[218:221], v[14:17]
	v_mfma_f32_16x16x32_bf16 v[18:21], v[196:199], v[160:163], v[18:21]
	v_mfma_f32_16x16x32_bf16 v[22:25], v[196:199], v[218:221], v[22:25]
	v_mfma_f32_16x16x32_bf16 v[26:29], v[144:147], v[160:163], v[26:29]
	v_mfma_f32_16x16x32_bf16 v[30:33], v[144:147], v[218:221], v[30:33]
	s_nop 0
	s_movk_i32 s1, 0x100
	v_cmp_gt_u32_e32 vcc, s1, v0
	s_barrier
	s_and_saveexec_b64 s[2:3], vcc
	s_cbranch_execz .LBB0_590
	s_barrier
